# GEMM main loops: removed the duplicated s_waitcnt lgkmcnt(0) after each inline-asm wait (36 sites)
# speedup vs baseline: 1.0167x; 1.0167x over previous
.LBB0_139:
	v_or_b32_e32 v140, 0x10000, v146
	v_add_u32_e32 v150, 0x10400, v146
	v_add_u32_e32 v154, 0x10800, v146
	v_add_u32_e32 v158, 0x10c00, v146
	ds_read_b128 v[140:143], v140
	ds_read_b128 v[150:153], v150
	ds_read_b128 v[154:157], v154
	ds_read_b128 v[158:161], v158
	s_add_u32 s10, s6, 0xfff80080
	s_addc_u32 s11, s7, -1
	s_cmp_eq_u32 s41, 28
	s_cselect_b32 s11, s63, s11
	s_cselect_b32 s10, s62, s10
	s_cselect_b32 s53, s61, s29
	s_cselect_b32 s52, s60, s28
	s_mov_b32 m0, s12
	v_lshl_add_u64 v[206:207], s[6:7], 0, v[136:137]
	ds_read_b128 v[162:165], v145
	ds_read_b128 v[166:169], v145 offset:1024
	ds_read_b128 v[170:173], v145 offset:2048
	ds_read_b128 v[174:177], v145 offset:3072
	ds_read_b128 v[178:181], v145 offset:4096
	ds_read_b128 v[182:185], v145 offset:5120
	ds_read_b128 v[186:189], v145 offset:6144
	ds_read_b128 v[190:193], v145 offset:7168
	global_load_lds_dwordx4 v[206:207], off
	v_lshl_add_u64 v[206:207], s[6:7], 0, v[138:139]
	s_mov_b32 m0, s78
	s_nop 0
	global_load_lds_dwordx4 v[206:207], off
	s_waitcnt lgkmcnt(8)
	s_barrier
	s_waitcnt lgkmcnt(0)
	s_setprio 1
	v_mfma_f32_16x16x32_bf16 v[126:129], v[140:143], v[162:165], v[126:129]
	v_mfma_f32_16x16x32_bf16 v[122:125], v[154:157], v[162:165], v[122:125]
	v_mfma_f32_16x16x32_bf16 v[118:121], v[140:143], v[170:173], v[118:121]
	v_mfma_f32_16x16x32_bf16 v[110:113], v[154:157], v[170:173], v[110:113]
	v_mfma_f32_16x16x32_bf16 v[102:105], v[140:143], v[178:181], v[102:105]
	v_mfma_f32_16x16x32_bf16 v[94:97], v[154:157], v[178:181], v[94:97]
	v_mfma_f32_16x16x32_bf16 v[86:89], v[140:143], v[186:189], v[86:89]
	v_mfma_f32_16x16x32_bf16 v[78:81], v[154:157], v[186:189], v[78:81]
	v_mfma_f32_16x16x32_bf16 v[126:129], v[150:153], v[166:169], v[126:129]
	v_mfma_f32_16x16x32_bf16 v[122:125], v[158:161], v[166:169], v[122:125]
	v_mfma_f32_16x16x32_bf16 v[118:121], v[150:153], v[174:177], v[118:121]
	v_mfma_f32_16x16x32_bf16 v[110:113], v[158:161], v[174:177], v[110:113]
	v_mfma_f32_16x16x32_bf16 v[102:105], v[150:153], v[182:185], v[102:105]
	v_mfma_f32_16x16x32_bf16 v[94:97], v[158:161], v[182:185], v[94:97]
	v_mfma_f32_16x16x32_bf16 v[86:89], v[150:153], v[190:193], v[86:89]
	v_mfma_f32_16x16x32_bf16 v[78:81], v[158:161], v[190:193], v[78:81]
	s_setprio 0
	s_barrier
	v_or_b32_e32 v197, 0x14000, v146
	s_mov_b32 m0, s83
	v_add_u32_e32 v199, 0x14400, v146
	ds_read_b128 v[206:209], v197
	ds_read_b128 v[210:213], v199
	v_add_u32_e32 v197, 0x14800, v146
	v_lshl_add_u64 v[222:223], s[52:53], 0, v[194:195]
	v_add_u32_e32 v199, 0x14c00, v146
	ds_read_b128 v[214:217], v197
	ds_read_b128 v[218:221], v199
	global_load_lds_dwordx4 v[222:223], off
	v_lshl_add_u64 v[224:225], s[52:53], 0, v[134:135]
	s_mov_b32 m0, s54
	s_nop 0
	global_load_lds_dwordx4 v[224:225], off
	s_barrier
	s_waitcnt lgkmcnt(0)
	s_setprio 1
	v_mfma_f32_16x16x32_bf16 v[114:117], v[206:209], v[162:165], v[114:117]
	v_mfma_f32_16x16x32_bf16 v[106:109], v[214:217], v[162:165], v[106:109]
	v_mfma_f32_16x16x32_bf16 v[98:101], v[206:209], v[170:173], v[98:101]
	v_mfma_f32_16x16x32_bf16 v[90:93], v[214:217], v[170:173], v[90:93]
	v_mfma_f32_16x16x32_bf16 v[82:85], v[206:209], v[178:181], v[82:85]
	v_mfma_f32_16x16x32_bf16 v[74:77], v[214:217], v[178:181], v[74:77]
	v_mfma_f32_16x16x32_bf16 v[70:73], v[206:209], v[186:189], v[70:73]
	v_mfma_f32_16x16x32_bf16 v[66:69], v[214:217], v[186:189], v[66:69]
	v_mfma_f32_16x16x32_bf16 v[114:117], v[210:213], v[166:169], v[114:117]
	v_mfma_f32_16x16x32_bf16 v[106:109], v[218:221], v[166:169], v[106:109]
	v_mfma_f32_16x16x32_bf16 v[98:101], v[210:213], v[174:177], v[98:101]
	v_mfma_f32_16x16x32_bf16 v[90:93], v[218:221], v[174:177], v[90:93]
	v_mfma_f32_16x16x32_bf16 v[82:85], v[210:213], v[182:185], v[82:85]
	v_mfma_f32_16x16x32_bf16 v[74:77], v[218:221], v[182:185], v[74:77]
	v_mfma_f32_16x16x32_bf16 v[70:73], v[210:213], v[190:193], v[70:73]
	v_mfma_f32_16x16x32_bf16 v[66:69], v[218:221], v[190:193], v[66:69]
	s_setprio 0
	s_mov_b32 m0, s55
	v_lshl_add_u64 v[226:227], s[10:11], 0, v[130:131]
	s_barrier
	ds_read_b128 v[162:165], v145 offset:16384
	ds_read_b128 v[166:169], v145 offset:17408
	ds_read_b128 v[170:173], v145 offset:18432
	ds_read_b128 v[174:177], v145 offset:19456
	ds_read_b128 v[178:181], v145 offset:20480
	ds_read_b128 v[182:185], v145 offset:21504
	ds_read_b128 v[186:189], v145 offset:22528
	ds_read_b128 v[190:193], v145 offset:23552
	global_load_lds_dwordx4 v[226:227], off
	v_lshl_add_u64 v[228:229], s[10:11], 0, v[132:133]
	s_mov_b32 m0, s34
	s_nop 0
	global_load_lds_dwordx4 v[228:229], off
	s_barrier
	s_waitcnt lgkmcnt(0)
	s_setprio 1
	v_mfma_f32_16x16x32_bf16 v[62:65], v[140:143], v[162:165], v[62:65]
	v_mfma_f32_16x16x32_bf16 v[58:61], v[154:157], v[162:165], v[58:61]
	v_mfma_f32_16x16x32_bf16 v[54:57], v[140:143], v[170:173], v[54:57]
	v_mfma_f32_16x16x32_bf16 v[46:49], v[154:157], v[170:173], v[46:49]
	v_mfma_f32_16x16x32_bf16 v[38:41], v[140:143], v[178:181], v[38:41]
	v_mfma_f32_16x16x32_bf16 v[30:33], v[154:157], v[178:181], v[30:33]
	v_mfma_f32_16x16x32_bf16 v[22:25], v[140:143], v[186:189], v[22:25]
	v_mfma_f32_16x16x32_bf16 v[14:17], v[154:157], v[186:189], v[14:17]
	v_mfma_f32_16x16x32_bf16 v[62:65], v[150:153], v[166:169], v[62:65]
	v_mfma_f32_16x16x32_bf16 v[58:61], v[158:161], v[166:169], v[58:61]
	v_mfma_f32_16x16x32_bf16 v[54:57], v[150:153], v[174:177], v[54:57]
	v_mfma_f32_16x16x32_bf16 v[46:49], v[158:161], v[174:177], v[46:49]
	v_mfma_f32_16x16x32_bf16 v[38:41], v[150:153], v[182:185], v[38:41]
	v_mfma_f32_16x16x32_bf16 v[30:33], v[158:161], v[182:185], v[30:33]
	v_mfma_f32_16x16x32_bf16 v[22:25], v[150:153], v[190:193], v[22:25]
	v_mfma_f32_16x16x32_bf16 v[14:17], v[158:161], v[190:193], v[14:17]
	s_setprio 0
	s_barrier
	s_add_u32 s58, s52, 0x80000
	s_addc_u32 s59, s53, 0
	s_mov_b32 m0, s4
	v_lshl_add_u64 v[140:141], s[58:59], 0, v[194:195]
	global_load_lds_dwordx4 v[140:141], off
	v_lshl_add_u64 v[140:141], s[58:59], 0, v[134:135]
	s_mov_b32 m0, s5
	s_nop 0
	global_load_lds_dwordx4 v[140:141], off
	s_waitcnt vmcnt(6)
	s_barrier
	s_setprio 1
	v_mfma_f32_16x16x32_bf16 v[50:53], v[206:209], v[162:165], v[50:53]
	v_mfma_f32_16x16x32_bf16 v[42:45], v[214:217], v[162:165], v[42:45]
	v_mfma_f32_16x16x32_bf16 v[34:37], v[206:209], v[170:173], v[34:37]
	v_mfma_f32_16x16x32_bf16 v[26:29], v[214:217], v[170:173], v[26:29]
	v_mfma_f32_16x16x32_bf16 v[18:21], v[206:209], v[178:181], v[18:21]
	v_mfma_f32_16x16x32_bf16 v[10:13], v[214:217], v[178:181], v[10:13]
	v_mfma_f32_16x16x32_bf16 v[6:9], v[206:209], v[186:189], v[6:9]
	v_mfma_f32_16x16x32_bf16 v[2:5], v[214:217], v[186:189], v[2:5]
	v_mfma_f32_16x16x32_bf16 v[50:53], v[210:213], v[166:169], v[50:53]
	v_mfma_f32_16x16x32_bf16 v[42:45], v[218:221], v[166:169], v[42:45]
	v_mfma_f32_16x16x32_bf16 v[34:37], v[210:213], v[174:177], v[34:37]
	v_mfma_f32_16x16x32_bf16 v[26:29], v[218:221], v[174:177], v[26:29]
	v_mfma_f32_16x16x32_bf16 v[18:21], v[210:213], v[182:185], v[18:21]
	v_mfma_f32_16x16x32_bf16 v[10:13], v[218:221], v[182:185], v[10:13]
	v_mfma_f32_16x16x32_bf16 v[6:9], v[210:213], v[190:193], v[6:9]
	v_mfma_f32_16x16x32_bf16 v[2:5], v[218:221], v[190:193], v[2:5]
	s_setprio 0
	v_or_b32_e32 v140, 0x18000, v146
	v_add_u32_e32 v150, 0x18400, v146
	v_add_u32_e32 v154, 0x18800, v146
	v_add_u32_e32 v158, 0x18c00, v146
	s_barrier
	ds_read_b128 v[140:143], v140
	ds_read_b128 v[150:153], v150
	ds_read_b128 v[154:157], v154
	ds_read_b128 v[158:161], v158
	s_add_u32 s10, s10, 0x80000
	s_addc_u32 s11, s11, 0
	s_mov_b32 m0, s56
	v_lshl_add_u64 v[206:207], s[10:11], 0, v[130:131]
	ds_read_b128 v[162:165], v145 offset:32768
	ds_read_b128 v[166:169], v145 offset:33792
	ds_read_b128 v[170:173], v145 offset:34816
	ds_read_b128 v[174:177], v145 offset:35840
	ds_read_b128 v[178:181], v145 offset:36864
	ds_read_b128 v[182:185], v145 offset:37888
	ds_read_b128 v[186:189], v145 offset:38912
	ds_read_b128 v[190:193], v145 offset:39936
	global_load_lds_dwordx4 v[206:207], off
	v_lshl_add_u64 v[206:207], s[10:11], 0, v[132:133]
	s_mov_b32 m0, s57
	s_nop 0
	global_load_lds_dwordx4 v[206:207], off
	s_waitcnt lgkmcnt(8)
	s_barrier
	s_waitcnt lgkmcnt(0)
	s_setprio 1
	v_mfma_f32_16x16x32_bf16 v[126:129], v[140:143], v[162:165], v[126:129]
	v_mfma_f32_16x16x32_bf16 v[122:125], v[154:157], v[162:165], v[122:125]
	v_mfma_f32_16x16x32_bf16 v[118:121], v[140:143], v[170:173], v[118:121]
	v_mfma_f32_16x16x32_bf16 v[110:113], v[154:157], v[170:173], v[110:113]
	v_mfma_f32_16x16x32_bf16 v[102:105], v[140:143], v[178:181], v[102:105]
	v_mfma_f32_16x16x32_bf16 v[94:97], v[154:157], v[178:181], v[94:97]
	v_mfma_f32_16x16x32_bf16 v[86:89], v[140:143], v[186:189], v[86:89]
	v_mfma_f32_16x16x32_bf16 v[78:81], v[154:157], v[186:189], v[78:81]
	v_mfma_f32_16x16x32_bf16 v[126:129], v[150:153], v[166:169], v[126:129]
	v_mfma_f32_16x16x32_bf16 v[122:125], v[158:161], v[166:169], v[122:125]
	v_mfma_f32_16x16x32_bf16 v[118:121], v[150:153], v[174:177], v[118:121]
	v_mfma_f32_16x16x32_bf16 v[110:113], v[158:161], v[174:177], v[110:113]
	v_mfma_f32_16x16x32_bf16 v[102:105], v[150:153], v[182:185], v[102:105]
	v_mfma_f32_16x16x32_bf16 v[94:97], v[158:161], v[182:185], v[94:97]
	v_mfma_f32_16x16x32_bf16 v[86:89], v[150:153], v[190:193], v[86:89]
	v_mfma_f32_16x16x32_bf16 v[78:81], v[158:161], v[190:193], v[78:81]
	s_setprio 0
	s_barrier
	v_or_b32_e32 v197, 0x1c000, v146
	s_mov_b32 m0, s70
	v_add_u32_e32 v199, 0x1c400, v146
	ds_read_b128 v[206:209], v197
	ds_read_b128 v[210:213], v199
	v_add_u32_e32 v197, 0x1c800, v146
	v_lshl_add_u64 v[222:223], v[222:223], 0, s[76:77]
	v_add_u32_e32 v199, 0x1cc00, v146
	ds_read_b128 v[214:217], v197
	ds_read_b128 v[218:221], v199
	global_load_lds_dwordx4 v[222:223], off
	v_lshl_add_u64 v[222:223], v[224:225], 0, s[76:77]
	s_mov_b32 m0, s71
	s_nop 0
	global_load_lds_dwordx4 v[222:223], off
	s_barrier
	s_waitcnt lgkmcnt(0)
	s_setprio 1
	v_mfma_f32_16x16x32_bf16 v[114:117], v[206:209], v[162:165], v[114:117]
	v_mfma_f32_16x16x32_bf16 v[106:109], v[214:217], v[162:165], v[106:109]
	v_mfma_f32_16x16x32_bf16 v[98:101], v[206:209], v[170:173], v[98:101]
	v_mfma_f32_16x16x32_bf16 v[90:93], v[214:217], v[170:173], v[90:93]
	v_mfma_f32_16x16x32_bf16 v[82:85], v[206:209], v[178:181], v[82:85]
	v_mfma_f32_16x16x32_bf16 v[74:77], v[214:217], v[178:181], v[74:77]
	v_mfma_f32_16x16x32_bf16 v[70:73], v[206:209], v[186:189], v[70:73]
	v_mfma_f32_16x16x32_bf16 v[66:69], v[214:217], v[186:189], v[66:69]
	v_mfma_f32_16x16x32_bf16 v[114:117], v[210:213], v[166:169], v[114:117]
	v_mfma_f32_16x16x32_bf16 v[106:109], v[218:221], v[166:169], v[106:109]
	v_mfma_f32_16x16x32_bf16 v[98:101], v[210:213], v[174:177], v[98:101]
	v_mfma_f32_16x16x32_bf16 v[90:93], v[218:221], v[174:177], v[90:93]
	v_mfma_f32_16x16x32_bf16 v[82:85], v[210:213], v[182:185], v[82:85]
	v_mfma_f32_16x16x32_bf16 v[74:77], v[218:221], v[182:185], v[74:77]
	v_mfma_f32_16x16x32_bf16 v[70:73], v[210:213], v[190:193], v[70:73]
	v_mfma_f32_16x16x32_bf16 v[66:69], v[218:221], v[190:193], v[66:69]
	s_setprio 0
	s_mov_b32 m0, s33
	v_lshl_add_u64 v[222:223], v[226:227], 0, s[76:77]
	s_barrier
	ds_read_b128 v[162:165], v145 offset:49152
	ds_read_b128 v[166:169], v145 offset:50176
	ds_read_b128 v[170:173], v145 offset:51200
	ds_read_b128 v[174:177], v145 offset:52224
	ds_read_b128 v[178:181], v145 offset:53248
	ds_read_b128 v[182:185], v145 offset:54272
	ds_read_b128 v[186:189], v145 offset:55296
	ds_read_b128 v[190:193], v145 offset:56320
	global_load_lds_dwordx4 v[222:223], off
	v_lshl_add_u64 v[222:223], v[228:229], 0, s[76:77]
	s_mov_b32 m0, s35
	s_nop 0
	global_load_lds_dwordx4 v[222:223], off
	s_barrier
	s_waitcnt lgkmcnt(0)
	s_setprio 1
	v_mfma_f32_16x16x32_bf16 v[62:65], v[140:143], v[162:165], v[62:65]
	v_mfma_f32_16x16x32_bf16 v[58:61], v[154:157], v[162:165], v[58:61]
	v_mfma_f32_16x16x32_bf16 v[54:57], v[140:143], v[170:173], v[54:57]
	v_mfma_f32_16x16x32_bf16 v[46:49], v[154:157], v[170:173], v[46:49]
	v_mfma_f32_16x16x32_bf16 v[38:41], v[140:143], v[178:181], v[38:41]
	v_mfma_f32_16x16x32_bf16 v[30:33], v[154:157], v[178:181], v[30:33]
	v_mfma_f32_16x16x32_bf16 v[22:25], v[140:143], v[186:189], v[22:25]
	v_mfma_f32_16x16x32_bf16 v[14:17], v[154:157], v[186:189], v[14:17]
	v_mfma_f32_16x16x32_bf16 v[62:65], v[150:153], v[166:169], v[62:65]
	v_mfma_f32_16x16x32_bf16 v[58:61], v[158:161], v[166:169], v[58:61]
	v_mfma_f32_16x16x32_bf16 v[54:57], v[150:153], v[174:177], v[54:57]
	v_mfma_f32_16x16x32_bf16 v[46:49], v[158:161], v[174:177], v[46:49]
	v_mfma_f32_16x16x32_bf16 v[38:41], v[150:153], v[182:185], v[38:41]
	v_mfma_f32_16x16x32_bf16 v[30:33], v[158:161], v[182:185], v[30:33]
	v_mfma_f32_16x16x32_bf16 v[22:25], v[150:153], v[190:193], v[22:25]
	v_mfma_f32_16x16x32_bf16 v[14:17], v[158:161], v[190:193], v[14:17]
	s_setprio 0
	s_barrier
	s_add_u32 s10, s52, 0x80080
	s_addc_u32 s11, s53, 0
	s_mov_b32 m0, s67
	v_lshl_add_u64 v[140:141], s[10:11], 0, v[194:195]
	global_load_lds_dwordx4 v[140:141], off
	v_lshl_add_u64 v[140:141], s[10:11], 0, v[134:135]
	s_mov_b32 m0, s17
	s_nop 0
	global_load_lds_dwordx4 v[140:141], off
	s_waitcnt vmcnt(6)
	s_barrier
	s_setprio 1
	v_mfma_f32_16x16x32_bf16 v[50:53], v[206:209], v[162:165], v[50:53]
	v_mfma_f32_16x16x32_bf16 v[42:45], v[214:217], v[162:165], v[42:45]
	v_mfma_f32_16x16x32_bf16 v[34:37], v[206:209], v[170:173], v[34:37]
	v_mfma_f32_16x16x32_bf16 v[26:29], v[214:217], v[170:173], v[26:29]
	v_mfma_f32_16x16x32_bf16 v[18:21], v[206:209], v[178:181], v[18:21]
	v_mfma_f32_16x16x32_bf16 v[10:13], v[214:217], v[178:181], v[10:13]
	v_mfma_f32_16x16x32_bf16 v[6:9], v[206:209], v[186:189], v[6:9]
	v_mfma_f32_16x16x32_bf16 v[2:5], v[214:217], v[186:189], v[2:5]
	v_mfma_f32_16x16x32_bf16 v[50:53], v[210:213], v[166:169], v[50:53]
	v_mfma_f32_16x16x32_bf16 v[42:45], v[218:221], v[166:169], v[42:45]
	v_mfma_f32_16x16x32_bf16 v[34:37], v[210:213], v[174:177], v[34:37]
	v_mfma_f32_16x16x32_bf16 v[26:29], v[218:221], v[174:177], v[26:29]
	v_mfma_f32_16x16x32_bf16 v[18:21], v[210:213], v[182:185], v[18:21]
	v_mfma_f32_16x16x32_bf16 v[10:13], v[218:221], v[182:185], v[10:13]
	v_mfma_f32_16x16x32_bf16 v[6:9], v[210:213], v[190:193], v[6:9]
	v_mfma_f32_16x16x32_bf16 v[2:5], v[218:221], v[190:193], v[2:5]
	s_setprio 0
	s_add_i32 s41, s41, 2
	s_add_u32 s6, s6, 0x100
	s_addc_u32 s7, s7, 0
	s_add_u32 s28, s28, 0x100
	s_addc_u32 s29, s29, 0
	s_cmp_gt_u32 s41, 29
	s_barrier
	s_cbranch_scc0 .LBB0_139
	s_cmp_gt_i32 s79, 3
	s_mov_b64 s[6:7], -1
	s_cbranch_scc0 .LBB0_146
	s_lshl_b32 s10, s82, 8
	v_lshl_or_b32 v140, s80, 8, v149
	s_cmp_lg_u32 s79, 4
	v_ashrrev_i32_e32 v141, 31, v140
	s_cbranch_scc0 .LBB0_143
	v_readlane_b32 s6, v252, 55
	v_readlane_b32 s7, v252, 56
	v_add_u32_e32 v150, s10, v147
	s_nop 0
	v_mov_b64_e32 v[142:143], s[6:7]
	s_mov_b32 s6, 0x9000
	v_mad_i64_i32 v[142:143], s[6:7], v150, s6, v[142:143]
	v_lshl_add_u64 v[142:143], v[140:141], 1, v[142:143]
	v_cvt_pk_bf16_f32 v150, v126, v127
	v_cvt_pk_bf16_f32 v151, v128, v129
	v_cvt_pk_bf16_f32 v152, v122, v123
	v_cvt_pk_bf16_f32 v153, v124, v125
	global_store_dwordx4 v[142:143], v[150:153], off
	v_add_co_u32_e32 v154, vcc, s44, v142
	s_nop 0
	v_cvt_pk_bf16_f32 v150, v114, v115
	v_cvt_pk_bf16_f32 v151, v116, v117
	v_cvt_pk_bf16_f32 v152, v106, v107
	v_cvt_pk_bf16_f32 v153, v108, v109
	global_store_dwordx4 v[142:143], v[150:153], off offset:256
	v_addc_co_u32_e32 v155, vcc, 0, v143, vcc
	s_nop 0
	v_cvt_pk_bf16_f32 v150, v118, v119
	v_cvt_pk_bf16_f32 v151, v120, v121
	v_cvt_pk_bf16_f32 v152, v110, v111
	v_cvt_pk_bf16_f32 v153, v112, v113
	global_store_dwordx4 v[154:155], v[150:153], off
	s_mov_b64 s[6:7], 0
	s_nop 0
	v_cvt_pk_bf16_f32 v150, v98, v99
	v_cvt_pk_bf16_f32 v151, v100, v101
	v_cvt_pk_bf16_f32 v152, v90, v91
	v_cvt_pk_bf16_f32 v153, v92, v93
	global_store_dwordx4 v[154:155], v[150:153], off offset:256
	v_add_co_u32_e32 v154, vcc, s45, v142
	s_nop 0
	v_cvt_pk_bf16_f32 v150, v102, v103
	v_cvt_pk_bf16_f32 v151, v104, v105
	v_cvt_pk_bf16_f32 v152, v94, v95
	v_cvt_pk_bf16_f32 v153, v96, v97
	s_nop 0
	v_addc_co_u32_e32 v155, vcc, 0, v143, vcc
	global_store_dwordx4 v[154:155], v[150:153], off
	s_nop 1
	v_cvt_pk_bf16_f32 v150, v82, v83
	v_cvt_pk_bf16_f32 v151, v84, v85
	v_cvt_pk_bf16_f32 v152, v74, v75
	v_cvt_pk_bf16_f32 v153, v76, v77
	global_store_dwordx4 v[154:155], v[150:153], off offset:256
	v_add_co_u32_e32 v154, vcc, s90, v142
	s_nop 0
	v_cvt_pk_bf16_f32 v150, v86, v87
	v_cvt_pk_bf16_f32 v151, v88, v89
	v_cvt_pk_bf16_f32 v152, v78, v79
	v_cvt_pk_bf16_f32 v153, v80, v81
	s_nop 0
	v_addc_co_u32_e32 v155, vcc, 0, v143, vcc
	global_store_dwordx4 v[154:155], v[150:153], off
	s_nop 1
	v_cvt_pk_bf16_f32 v150, v70, v71
	v_cvt_pk_bf16_f32 v151, v72, v73
	v_cvt_pk_bf16_f32 v152, v66, v67
	v_cvt_pk_bf16_f32 v153, v68, v69
	global_store_dwordx4 v[154:155], v[150:153], off offset:256
	v_add_co_u32_e32 v154, vcc, s20, v142
	s_nop 0
	v_cvt_pk_bf16_f32 v150, v62, v63
	v_cvt_pk_bf16_f32 v151, v64, v65
	v_cvt_pk_bf16_f32 v152, v58, v59
	v_cvt_pk_bf16_f32 v153, v60, v61
	s_nop 0
	v_addc_co_u32_e32 v155, vcc, 0, v143, vcc
	global_store_dwordx4 v[154:155], v[150:153], off
	s_nop 1
	v_cvt_pk_bf16_f32 v150, v50, v51
	v_cvt_pk_bf16_f32 v151, v52, v53
	v_cvt_pk_bf16_f32 v152, v42, v43
	v_cvt_pk_bf16_f32 v153, v44, v45
	global_store_dwordx4 v[154:155], v[150:153], off offset:256
	v_add_co_u32_e32 v154, vcc, s21, v142
	s_nop 0
	v_cvt_pk_bf16_f32 v150, v54, v55
	v_cvt_pk_bf16_f32 v151, v56, v57
	v_cvt_pk_bf16_f32 v152, v46, v47
	v_cvt_pk_bf16_f32 v153, v48, v49
	s_nop 0
	v_addc_co_u32_e32 v155, vcc, 0, v143, vcc
	global_store_dwordx4 v[154:155], v[150:153], off
	s_nop 1
	v_cvt_pk_bf16_f32 v150, v34, v35
	v_cvt_pk_bf16_f32 v151, v36, v37
	v_cvt_pk_bf16_f32 v152, v26, v27
	v_cvt_pk_bf16_f32 v153, v28, v29
	global_store_dwordx4 v[154:155], v[150:153], off offset:256
	v_add_co_u32_e32 v154, vcc, s22, v142
	s_nop 0
	v_cvt_pk_bf16_f32 v150, v38, v39
	v_cvt_pk_bf16_f32 v151, v40, v41
	v_cvt_pk_bf16_f32 v152, v30, v31
	v_cvt_pk_bf16_f32 v153, v32, v33
	s_nop 0
	v_addc_co_u32_e32 v155, vcc, 0, v143, vcc
	global_store_dwordx4 v[154:155], v[150:153], off
	v_add_co_u32_e32 v142, vcc, s23, v142
	s_nop 0
	v_cvt_pk_bf16_f32 v150, v18, v19
	v_cvt_pk_bf16_f32 v151, v20, v21
	v_cvt_pk_bf16_f32 v152, v10, v11
	v_cvt_pk_bf16_f32 v153, v12, v13
	global_store_dwordx4 v[154:155], v[150:153], off offset:256
	v_addc_co_u32_e32 v143, vcc, 0, v143, vcc
	s_nop 0
	v_cvt_pk_bf16_f32 v150, v22, v23
	v_cvt_pk_bf16_f32 v151, v24, v25
	v_cvt_pk_bf16_f32 v152, v14, v15
	v_cvt_pk_bf16_f32 v153, v16, v17
	global_store_dwordx4 v[142:143], v[150:153], off
	s_nop 1
	v_cvt_pk_bf16_f32 v150, v6, v7
	v_cvt_pk_bf16_f32 v151, v8, v9
	v_cvt_pk_bf16_f32 v152, v2, v3
	v_cvt_pk_bf16_f32 v153, v4, v5
	global_store_dwordx4 v[142:143], v[150:153], off offset:256

.LBB0_204:
	s_add_u32 s80, s54, s62
	s_addc_u32 s81, s55, s63
	s_add_u32 s82, s80, 0x100
	s_addc_u32 s83, s81, 0
	s_and_b64 s[10:11], s[8:9], exec
	s_cselect_b32 s83, s1, s83
	s_cselect_b32 s82, s0, s82
	s_add_u32 s10, s52, s62
	s_addc_u32 s11, s53, s63
	s_add_u32 s10, s10, 0x100
	s_addc_u32 s11, s11, 0
	s_and_b64 s[8:9], s[8:9], exec
	s_cselect_b32 vcc_hi, s7, s11
	s_cselect_b32 vcc_lo, s6, s10
	s_add_u32 s10, s80, 0x10080
	v_or_b32_e32 v138, 0x10000, v142
	s_addc_u32 s11, s81, 0
	s_add_i32 m0, s5, 0xc000
	s_add_i32 s87, s5, 0xe000
	ds_read_b128 v[144:147], v138
	v_add_u32_e32 v138, 0x10400, v142
	s_add_u32 s80, vcc_lo, 0x340000
	ds_read_b128 v[148:151], v138
	v_add_u32_e32 v138, 0x10800, v142
	s_addc_u32 s81, vcc_hi, 0
	ds_read_b128 v[152:155], v138
	v_add_u32_e32 v138, 0x10c00, v142
	s_add_u32 s62, s82, 0x10000
	ds_read_b128 v[156:159], v138
	s_addc_u32 s63, s83, 0
	s_add_u32 s8, vcc_lo, 0x340080
	s_addc_u32 s9, vcc_hi, 0
	v_lshl_add_u64 v[138:139], s[10:11], 0, v[136:137]
	ds_read_b128 v[160:163], v141
	ds_read_b128 v[164:167], v141 offset:1024
	ds_read_b128 v[168:171], v141 offset:2048
	ds_read_b128 v[172:175], v141 offset:3072
	ds_read_b128 v[176:179], v141 offset:4096
	ds_read_b128 v[180:183], v141 offset:5120
	ds_read_b128 v[184:187], v141 offset:6144
	ds_read_b128 v[188:191], v141 offset:7168
	global_load_lds_dwordx4 v[138:139], off
	v_lshl_add_u64 v[138:139], s[10:11], 0, v[132:133]
	s_mov_b32 m0, s87
	s_nop 0
	global_load_lds_dwordx4 v[138:139], off
	s_waitcnt lgkmcnt(8)
	s_barrier
	s_waitcnt lgkmcnt(0)
	s_setprio 1
	v_mfma_f32_16x16x32_bf16 v[126:129], v[144:147], v[160:163], v[126:129]
	v_mfma_f32_16x16x32_bf16 v[122:125], v[152:155], v[160:163], v[122:125]
	v_mfma_f32_16x16x32_bf16 v[118:121], v[144:147], v[168:171], v[118:121]
	v_mfma_f32_16x16x32_bf16 v[110:113], v[152:155], v[168:171], v[110:113]
	v_mfma_f32_16x16x32_bf16 v[102:105], v[144:147], v[176:179], v[102:105]
	v_mfma_f32_16x16x32_bf16 v[94:97], v[152:155], v[176:179], v[94:97]
	v_mfma_f32_16x16x32_bf16 v[86:89], v[144:147], v[184:187], v[86:89]
	v_mfma_f32_16x16x32_bf16 v[78:81], v[152:155], v[184:187], v[78:81]
	v_mfma_f32_16x16x32_bf16 v[126:129], v[148:151], v[164:167], v[126:129]
	v_mfma_f32_16x16x32_bf16 v[122:125], v[156:159], v[164:167], v[122:125]
	v_mfma_f32_16x16x32_bf16 v[118:121], v[148:151], v[172:175], v[118:121]
	v_mfma_f32_16x16x32_bf16 v[110:113], v[156:159], v[172:175], v[110:113]
	v_mfma_f32_16x16x32_bf16 v[102:105], v[148:151], v[180:183], v[102:105]
	v_mfma_f32_16x16x32_bf16 v[94:97], v[156:159], v[180:183], v[94:97]
	v_mfma_f32_16x16x32_bf16 v[86:89], v[148:151], v[188:191], v[86:89]
	v_mfma_f32_16x16x32_bf16 v[78:81], v[156:159], v[188:191], v[78:81]
	s_setprio 0
	s_barrier
	v_or_b32_e32 v138, 0x14000, v142
	v_add_u32_e32 v139, 0x14400, v142
	ds_read_b128 v[206:209], v138
	ds_read_b128 v[210:213], v139
	v_add_u32_e32 v138, 0x14800, v142
	v_add_u32_e32 v139, 0x14c00, v142
	s_mov_b32 m0, s12
	ds_read_b128 v[214:217], v138
	ds_read_b128 v[218:221], v139
	v_lshl_add_u64 v[138:139], vcc, 0, v[134:135]
	global_load_lds_dwordx4 v[138:139], off
	v_lshl_add_u64 v[192:193], vcc, 0, v[130:131]
	s_mov_b32 m0, s17
	s_nop 0
	global_load_lds_dwordx4 v[192:193], off
	s_barrier
	s_waitcnt lgkmcnt(0)
	s_setprio 1
	v_mfma_f32_16x16x32_bf16 v[114:117], v[206:209], v[160:163], v[114:117]
	v_mfma_f32_16x16x32_bf16 v[106:109], v[214:217], v[160:163], v[106:109]
	v_mfma_f32_16x16x32_bf16 v[98:101], v[206:209], v[168:171], v[98:101]
	v_mfma_f32_16x16x32_bf16 v[90:93], v[214:217], v[168:171], v[90:93]
	v_mfma_f32_16x16x32_bf16 v[82:85], v[206:209], v[176:179], v[82:85]
	v_mfma_f32_16x16x32_bf16 v[74:77], v[214:217], v[176:179], v[74:77]
	v_mfma_f32_16x16x32_bf16 v[70:73], v[206:209], v[184:187], v[70:73]
	v_mfma_f32_16x16x32_bf16 v[66:69], v[214:217], v[184:187], v[66:69]
	v_mfma_f32_16x16x32_bf16 v[114:117], v[210:213], v[164:167], v[114:117]
	v_mfma_f32_16x16x32_bf16 v[106:109], v[218:221], v[164:167], v[106:109]
	v_mfma_f32_16x16x32_bf16 v[98:101], v[210:213], v[172:175], v[98:101]
	v_mfma_f32_16x16x32_bf16 v[90:93], v[218:221], v[172:175], v[90:93]
	v_mfma_f32_16x16x32_bf16 v[82:85], v[210:213], v[180:183], v[82:85]
	v_mfma_f32_16x16x32_bf16 v[74:77], v[218:221], v[180:183], v[74:77]
	v_mfma_f32_16x16x32_bf16 v[70:73], v[210:213], v[188:191], v[70:73]
	v_mfma_f32_16x16x32_bf16 v[66:69], v[218:221], v[188:191], v[66:69]
	s_setprio 0
	s_mov_b32 m0, s5
	v_lshl_add_u64 v[222:223], s[82:83], 0, v[136:137]
	s_barrier
	ds_read_b128 v[160:163], v141 offset:16384
	ds_read_b128 v[164:167], v141 offset:17408
	ds_read_b128 v[168:171], v141 offset:18432
	ds_read_b128 v[172:175], v141 offset:19456
	ds_read_b128 v[176:179], v141 offset:20480
	ds_read_b128 v[180:183], v141 offset:21504
	ds_read_b128 v[184:187], v141 offset:22528
	ds_read_b128 v[188:191], v141 offset:23552
	global_load_lds_dwordx4 v[222:223], off
	v_lshl_add_u64 v[224:225], s[82:83], 0, v[132:133]
	s_mov_b32 m0, s26
	s_nop 0
	global_load_lds_dwordx4 v[224:225], off
	s_barrier
	s_waitcnt lgkmcnt(0)
	s_setprio 1
	v_mfma_f32_16x16x32_bf16 v[62:65], v[144:147], v[160:163], v[62:65]
	v_mfma_f32_16x16x32_bf16 v[58:61], v[152:155], v[160:163], v[58:61]
	v_mfma_f32_16x16x32_bf16 v[54:57], v[144:147], v[168:171], v[54:57]
	v_mfma_f32_16x16x32_bf16 v[46:49], v[152:155], v[168:171], v[46:49]
	v_mfma_f32_16x16x32_bf16 v[38:41], v[144:147], v[176:179], v[38:41]
	v_mfma_f32_16x16x32_bf16 v[30:33], v[152:155], v[176:179], v[30:33]
	v_mfma_f32_16x16x32_bf16 v[22:25], v[144:147], v[184:187], v[22:25]
	v_mfma_f32_16x16x32_bf16 v[14:17], v[152:155], v[184:187], v[14:17]
	v_mfma_f32_16x16x32_bf16 v[62:65], v[148:151], v[164:167], v[62:65]
	v_mfma_f32_16x16x32_bf16 v[58:61], v[156:159], v[164:167], v[58:61]
	v_mfma_f32_16x16x32_bf16 v[54:57], v[148:151], v[172:175], v[54:57]
	v_mfma_f32_16x16x32_bf16 v[46:49], v[156:159], v[172:175], v[46:49]
	v_mfma_f32_16x16x32_bf16 v[38:41], v[148:151], v[180:183], v[38:41]
	v_mfma_f32_16x16x32_bf16 v[30:33], v[156:159], v[180:183], v[30:33]
	v_mfma_f32_16x16x32_bf16 v[22:25], v[148:151], v[188:191], v[22:25]
	v_mfma_f32_16x16x32_bf16 v[14:17], v[156:159], v[188:191], v[14:17]
	s_setprio 0
	s_barrier
	s_mov_b32 m0, s34
	v_lshl_add_u64 v[144:145], s[80:81], 0, v[134:135]
	global_load_lds_dwordx4 v[144:145], off
	v_lshl_add_u64 v[144:145], s[80:81], 0, v[130:131]
	s_mov_b32 m0, s35
	s_nop 0
	global_load_lds_dwordx4 v[144:145], off
	s_waitcnt vmcnt(6)
	s_barrier
	s_setprio 1
	v_mfma_f32_16x16x32_bf16 v[50:53], v[206:209], v[160:163], v[50:53]
	v_mfma_f32_16x16x32_bf16 v[42:45], v[214:217], v[160:163], v[42:45]
	v_mfma_f32_16x16x32_bf16 v[34:37], v[206:209], v[168:171], v[34:37]
	v_mfma_f32_16x16x32_bf16 v[26:29], v[214:217], v[168:171], v[26:29]
	v_mfma_f32_16x16x32_bf16 v[18:21], v[206:209], v[176:179], v[18:21]
	v_mfma_f32_16x16x32_bf16 v[10:13], v[214:217], v[176:179], v[10:13]
	v_mfma_f32_16x16x32_bf16 v[6:9], v[206:209], v[184:187], v[6:9]
	v_mfma_f32_16x16x32_bf16 v[2:5], v[214:217], v[184:187], v[2:5]
	v_mfma_f32_16x16x32_bf16 v[50:53], v[210:213], v[164:167], v[50:53]
	v_mfma_f32_16x16x32_bf16 v[42:45], v[218:221], v[164:167], v[42:45]
	v_mfma_f32_16x16x32_bf16 v[34:37], v[210:213], v[172:175], v[34:37]
	v_mfma_f32_16x16x32_bf16 v[26:29], v[218:221], v[172:175], v[26:29]
	v_mfma_f32_16x16x32_bf16 v[18:21], v[210:213], v[180:183], v[18:21]
	v_mfma_f32_16x16x32_bf16 v[10:13], v[218:221], v[180:183], v[10:13]
	v_mfma_f32_16x16x32_bf16 v[6:9], v[210:213], v[188:191], v[6:9]
	v_mfma_f32_16x16x32_bf16 v[2:5], v[218:221], v[188:191], v[2:5]
	s_setprio 0
	v_or_b32_e32 v144, 0x18000, v142
	v_add_u32_e32 v148, 0x18400, v142
	v_add_u32_e32 v152, 0x18800, v142
	v_add_u32_e32 v156, 0x18c00, v142
	s_barrier
	ds_read_b128 v[144:147], v144
	ds_read_b128 v[148:151], v148
	ds_read_b128 v[152:155], v152
	ds_read_b128 v[156:159], v156
	s_mov_b32 m0, s56
	v_lshl_add_u64 v[206:207], s[62:63], 0, v[136:137]
	ds_read_b128 v[160:163], v141 offset:32768
	ds_read_b128 v[164:167], v141 offset:33792
	ds_read_b128 v[168:171], v141 offset:34816
	ds_read_b128 v[172:175], v141 offset:35840
	ds_read_b128 v[176:179], v141 offset:36864
	ds_read_b128 v[180:183], v141 offset:37888
	ds_read_b128 v[184:187], v141 offset:38912
	ds_read_b128 v[188:191], v141 offset:39936
	global_load_lds_dwordx4 v[206:207], off
	v_lshl_add_u64 v[206:207], s[62:63], 0, v[132:133]
	s_mov_b32 m0, s57
	s_nop 0
	global_load_lds_dwordx4 v[206:207], off
	s_waitcnt lgkmcnt(8)
	s_barrier
	s_waitcnt lgkmcnt(0)
	s_setprio 1
	v_mfma_f32_16x16x32_bf16 v[126:129], v[144:147], v[160:163], v[126:129]
	v_mfma_f32_16x16x32_bf16 v[122:125], v[152:155], v[160:163], v[122:125]
	v_mfma_f32_16x16x32_bf16 v[118:121], v[144:147], v[168:171], v[118:121]
	v_mfma_f32_16x16x32_bf16 v[110:113], v[152:155], v[168:171], v[110:113]
	v_mfma_f32_16x16x32_bf16 v[102:105], v[144:147], v[176:179], v[102:105]
	v_mfma_f32_16x16x32_bf16 v[94:97], v[152:155], v[176:179], v[94:97]
	v_mfma_f32_16x16x32_bf16 v[86:89], v[144:147], v[184:187], v[86:89]
	v_mfma_f32_16x16x32_bf16 v[78:81], v[152:155], v[184:187], v[78:81]
	v_mfma_f32_16x16x32_bf16 v[126:129], v[148:151], v[164:167], v[126:129]
	v_mfma_f32_16x16x32_bf16 v[122:125], v[156:159], v[164:167], v[122:125]
	v_mfma_f32_16x16x32_bf16 v[118:121], v[148:151], v[172:175], v[118:121]
	v_mfma_f32_16x16x32_bf16 v[110:113], v[156:159], v[172:175], v[110:113]
	v_mfma_f32_16x16x32_bf16 v[102:105], v[148:151], v[180:183], v[102:105]
	v_mfma_f32_16x16x32_bf16 v[94:97], v[156:159], v[180:183], v[94:97]
	v_mfma_f32_16x16x32_bf16 v[86:89], v[148:151], v[188:191], v[86:89]
	v_mfma_f32_16x16x32_bf16 v[78:81], v[156:159], v[188:191], v[78:81]
	s_setprio 0
	s_barrier
	v_or_b32_e32 v197, 0x1c000, v142
	s_mov_b32 m0, s58
	v_add_u32_e32 v199, 0x1c400, v142
	ds_read_b128 v[206:209], v197
	ds_read_b128 v[210:213], v199
	v_add_u32_e32 v197, 0x1c800, v142
	v_lshl_add_u64 v[138:139], v[138:139], 0, s[76:77]
	v_add_u32_e32 v199, 0x1cc00, v142
	ds_read_b128 v[214:217], v197
	ds_read_b128 v[218:221], v199
	global_load_lds_dwordx4 v[138:139], off
	v_lshl_add_u64 v[138:139], v[192:193], 0, s[76:77]
	s_mov_b32 m0, s59
	s_nop 0
	global_load_lds_dwordx4 v[138:139], off
	s_barrier
	s_waitcnt lgkmcnt(0)
	s_setprio 1
	v_mfma_f32_16x16x32_bf16 v[114:117], v[206:209], v[160:163], v[114:117]
	v_mfma_f32_16x16x32_bf16 v[106:109], v[214:217], v[160:163], v[106:109]
	v_mfma_f32_16x16x32_bf16 v[98:101], v[206:209], v[168:171], v[98:101]
	v_mfma_f32_16x16x32_bf16 v[90:93], v[214:217], v[168:171], v[90:93]
	v_mfma_f32_16x16x32_bf16 v[82:85], v[206:209], v[176:179], v[82:85]
	v_mfma_f32_16x16x32_bf16 v[74:77], v[214:217], v[176:179], v[74:77]
	v_mfma_f32_16x16x32_bf16 v[70:73], v[206:209], v[184:187], v[70:73]
	v_mfma_f32_16x16x32_bf16 v[66:69], v[214:217], v[184:187], v[66:69]
	v_mfma_f32_16x16x32_bf16 v[114:117], v[210:213], v[164:167], v[114:117]
	v_mfma_f32_16x16x32_bf16 v[106:109], v[218:221], v[164:167], v[106:109]
	v_mfma_f32_16x16x32_bf16 v[98:101], v[210:213], v[172:175], v[98:101]
	v_mfma_f32_16x16x32_bf16 v[90:93], v[218:221], v[172:175], v[90:93]
	v_mfma_f32_16x16x32_bf16 v[82:85], v[210:213], v[180:183], v[82:85]
	v_mfma_f32_16x16x32_bf16 v[74:77], v[218:221], v[180:183], v[74:77]
	v_mfma_f32_16x16x32_bf16 v[70:73], v[210:213], v[188:191], v[70:73]
	v_mfma_f32_16x16x32_bf16 v[66:69], v[218:221], v[188:191], v[66:69]
	s_setprio 0
	s_mov_b32 m0, s67
	v_lshl_add_u64 v[138:139], v[222:223], 0, s[76:77]
	s_barrier
	ds_read_b128 v[160:163], v141 offset:49152
	ds_read_b128 v[164:167], v141 offset:50176
	ds_read_b128 v[168:171], v141 offset:51200
	ds_read_b128 v[172:175], v141 offset:52224
	ds_read_b128 v[176:179], v141 offset:53248
	ds_read_b128 v[180:183], v141 offset:54272
	ds_read_b128 v[184:187], v141 offset:55296
	ds_read_b128 v[188:191], v141 offset:56320
	global_load_lds_dwordx4 v[138:139], off
	v_lshl_add_u64 v[138:139], v[224:225], 0, s[76:77]
	s_mov_b32 m0, s70
	s_nop 0
	global_load_lds_dwordx4 v[138:139], off
	s_barrier
	s_waitcnt lgkmcnt(0)
	s_setprio 1
	v_mfma_f32_16x16x32_bf16 v[62:65], v[144:147], v[160:163], v[62:65]
	v_mfma_f32_16x16x32_bf16 v[58:61], v[152:155], v[160:163], v[58:61]
	v_mfma_f32_16x16x32_bf16 v[54:57], v[144:147], v[168:171], v[54:57]
	v_mfma_f32_16x16x32_bf16 v[46:49], v[152:155], v[168:171], v[46:49]
	v_mfma_f32_16x16x32_bf16 v[38:41], v[144:147], v[176:179], v[38:41]
	v_mfma_f32_16x16x32_bf16 v[30:33], v[152:155], v[176:179], v[30:33]
	v_mfma_f32_16x16x32_bf16 v[22:25], v[144:147], v[184:187], v[22:25]
	v_mfma_f32_16x16x32_bf16 v[14:17], v[152:155], v[184:187], v[14:17]
	v_mfma_f32_16x16x32_bf16 v[62:65], v[148:151], v[164:167], v[62:65]
	v_mfma_f32_16x16x32_bf16 v[58:61], v[156:159], v[164:167], v[58:61]
	v_mfma_f32_16x16x32_bf16 v[54:57], v[148:151], v[172:175], v[54:57]
	v_mfma_f32_16x16x32_bf16 v[46:49], v[156:159], v[172:175], v[46:49]
	v_mfma_f32_16x16x32_bf16 v[38:41], v[148:151], v[180:183], v[38:41]
	v_mfma_f32_16x16x32_bf16 v[30:33], v[156:159], v[180:183], v[30:33]
	v_mfma_f32_16x16x32_bf16 v[22:25], v[148:151], v[188:191], v[22:25]
	v_mfma_f32_16x16x32_bf16 v[14:17], v[156:159], v[188:191], v[14:17]
	s_setprio 0
	s_barrier
	s_mov_b32 m0, s71
	v_lshl_add_u64 v[138:139], s[8:9], 0, v[134:135]
	global_load_lds_dwordx4 v[138:139], off
	v_lshl_add_u64 v[138:139], s[8:9], 0, v[130:131]
	s_mov_b32 m0, s78
	s_nop 0
	global_load_lds_dwordx4 v[138:139], off
	s_waitcnt vmcnt(6)
	s_barrier
	s_setprio 1
	v_mfma_f32_16x16x32_bf16 v[50:53], v[206:209], v[160:163], v[50:53]
	v_mfma_f32_16x16x32_bf16 v[42:45], v[214:217], v[160:163], v[42:45]
	v_mfma_f32_16x16x32_bf16 v[34:37], v[206:209], v[168:171], v[34:37]
	v_mfma_f32_16x16x32_bf16 v[26:29], v[214:217], v[168:171], v[26:29]
	v_mfma_f32_16x16x32_bf16 v[18:21], v[206:209], v[176:179], v[18:21]
	v_mfma_f32_16x16x32_bf16 v[10:13], v[214:217], v[176:179], v[10:13]
	v_mfma_f32_16x16x32_bf16 v[6:9], v[206:209], v[184:187], v[6:9]
	v_mfma_f32_16x16x32_bf16 v[2:5], v[214:217], v[184:187], v[2:5]
	v_mfma_f32_16x16x32_bf16 v[50:53], v[210:213], v[164:167], v[50:53]
	v_mfma_f32_16x16x32_bf16 v[42:45], v[218:221], v[164:167], v[42:45]
	v_mfma_f32_16x16x32_bf16 v[34:37], v[210:213], v[172:175], v[34:37]
	v_mfma_f32_16x16x32_bf16 v[26:29], v[218:221], v[172:175], v[26:29]
	v_mfma_f32_16x16x32_bf16 v[18:21], v[210:213], v[180:183], v[18:21]
	v_mfma_f32_16x16x32_bf16 v[10:13], v[218:221], v[180:183], v[10:13]
	v_mfma_f32_16x16x32_bf16 v[6:9], v[210:213], v[188:191], v[6:9]
	v_mfma_f32_16x16x32_bf16 v[2:5], v[218:221], v[188:191], v[2:5]
	s_setprio 0
	s_andn2_b64 vcc, exec, s[60:61]
	s_mov_b64 s[8:9], -1
	s_mov_b64 s[60:61], 0
	s_mov_b64 s[62:63], 0x100
	s_barrier
	s_cbranch_vccz .LBB0_204
	s_cmp_gt_i32 s29, 63
	s_cbranch_scc0 .LBB0_207
	s_lshl_b32 s8, s29, 10
	s_lshl_b32 s9, s94, 8
	s_add_i32 s9, s9, s8
	v_add_u32_e32 v138, s9, v143
	v_ashrrev_i32_e32 v139, 31, v138
	v_lshlrev_b64 v[138:139], 10, v[138:139]
	s_lshl_b32 s8, s42, 8
	v_lshl_add_u64 v[138:139], s[64:65], 0, v[138:139]
	s_ashr_i32 s9, s8, 31
	v_lshl_add_u64 v[138:139], s[8:9], 1, v[138:139]
	s_mov_b64 s[8:9], 0

.LBB0_255:
	v_or_b32_e32 v130, 0x10000, v182
	v_add_u32_e32 v134, 0x10400, v182
	v_add_u32_e32 v138, 0x10800, v182
	v_add_u32_e32 v142, 0x10c00, v182
	ds_read_b128 v[130:133], v130
	ds_read_b128 v[134:137], v134
	ds_read_b128 v[138:141], v138
	ds_read_b128 v[142:145], v142
	s_add_u32 s8, s6, 0xfff00080
	s_addc_u32 s9, s7, -1
	s_cmp_eq_u32 s79, 60
	s_cselect_b32 s11, s53, s9
	s_cselect_b32 s10, s52, s8
	s_cselect_b32 s9, s61, s78
	s_cselect_b32 s8, s60, s1
	v_lshl_add_u64 v[178:179], s[6:7], 0, v[166:167]
	s_add_i32 m0, s5, 0xc000
	ds_read_b128 v[146:149], v181
	ds_read_b128 v[150:153], v181 offset:1024
	ds_read_b128 v[154:157], v181 offset:2048
	ds_read_b128 v[170:173], v181 offset:3072
	ds_read_b128 v[174:177], v181 offset:4096
	ds_read_b128 v[184:187], v181 offset:5120
	ds_read_b128 v[188:191], v181 offset:6144
	ds_read_b128 v[206:209], v181 offset:7168
	global_load_lds_dwordx4 v[178:179], off
	v_lshl_add_u64 v[178:179], s[6:7], 0, v[168:169]
	s_add_i32 m0, s5, 0xe000
	s_nop 0
	global_load_lds_dwordx4 v[178:179], off
	s_waitcnt lgkmcnt(8)
	s_barrier
	s_waitcnt lgkmcnt(0)
	s_setprio 1
	v_mfma_f32_16x16x32_bf16 v[126:129], v[130:133], v[146:149], v[126:129]
	v_mfma_f32_16x16x32_bf16 v[122:125], v[138:141], v[146:149], v[122:125]
	v_mfma_f32_16x16x32_bf16 v[110:113], v[130:133], v[154:157], v[110:113]
	v_mfma_f32_16x16x32_bf16 v[106:109], v[138:141], v[154:157], v[106:109]
	v_mfma_f32_16x16x32_bf16 v[94:97], v[130:133], v[174:177], v[94:97]
	v_mfma_f32_16x16x32_bf16 v[90:93], v[138:141], v[174:177], v[90:93]
	v_mfma_f32_16x16x32_bf16 v[78:81], v[130:133], v[188:191], v[78:81]
	v_mfma_f32_16x16x32_bf16 v[74:77], v[138:141], v[188:191], v[74:77]
	v_mfma_f32_16x16x32_bf16 v[126:129], v[134:137], v[150:153], v[126:129]
	v_mfma_f32_16x16x32_bf16 v[122:125], v[142:145], v[150:153], v[122:125]
	v_mfma_f32_16x16x32_bf16 v[110:113], v[134:137], v[170:173], v[110:113]
	v_mfma_f32_16x16x32_bf16 v[106:109], v[142:145], v[170:173], v[106:109]
	v_mfma_f32_16x16x32_bf16 v[94:97], v[134:137], v[184:187], v[94:97]
	v_mfma_f32_16x16x32_bf16 v[90:93], v[142:145], v[184:187], v[90:93]
	v_mfma_f32_16x16x32_bf16 v[78:81], v[134:137], v[206:209], v[78:81]
	v_mfma_f32_16x16x32_bf16 v[74:77], v[142:145], v[206:209], v[74:77]
	s_setprio 0
	s_barrier
	v_or_b32_e32 v178, 0x14000, v182
	v_add_u32_e32 v179, 0x14400, v182
	ds_read_b128 v[210:213], v178
	ds_read_b128 v[214:217], v179
	v_add_u32_e32 v178, 0x14800, v182
	v_add_u32_e32 v179, 0x14c00, v182
	s_mov_b32 m0, s12
	ds_read_b128 v[218:221], v178
	ds_read_b128 v[222:225], v179
	v_lshl_add_u64 v[178:179], s[8:9], 0, v[162:163]
	global_load_lds_dwordx4 v[178:179], off
	v_lshl_add_u64 v[192:193], s[8:9], 0, v[158:159]
	s_mov_b32 m0, s17
	s_nop 0
	global_load_lds_dwordx4 v[192:193], off
	s_barrier
	s_waitcnt lgkmcnt(0)
	s_setprio 1
	v_mfma_f32_16x16x32_bf16 v[118:121], v[210:213], v[146:149], v[118:121]
	v_mfma_f32_16x16x32_bf16 v[114:117], v[218:221], v[146:149], v[114:117]
	v_mfma_f32_16x16x32_bf16 v[102:105], v[210:213], v[154:157], v[102:105]
	v_mfma_f32_16x16x32_bf16 v[98:101], v[218:221], v[154:157], v[98:101]
	v_mfma_f32_16x16x32_bf16 v[86:89], v[210:213], v[174:177], v[86:89]
	v_mfma_f32_16x16x32_bf16 v[82:85], v[218:221], v[174:177], v[82:85]
	v_mfma_f32_16x16x32_bf16 v[70:73], v[210:213], v[188:191], v[70:73]
	v_mfma_f32_16x16x32_bf16 v[66:69], v[218:221], v[188:191], v[66:69]
	v_mfma_f32_16x16x32_bf16 v[118:121], v[214:217], v[150:153], v[118:121]
	v_mfma_f32_16x16x32_bf16 v[114:117], v[222:225], v[150:153], v[114:117]
	v_mfma_f32_16x16x32_bf16 v[102:105], v[214:217], v[170:173], v[102:105]
	v_mfma_f32_16x16x32_bf16 v[98:101], v[222:225], v[170:173], v[98:101]
	v_mfma_f32_16x16x32_bf16 v[86:89], v[214:217], v[184:187], v[86:89]
	v_mfma_f32_16x16x32_bf16 v[82:85], v[222:225], v[184:187], v[82:85]
	v_mfma_f32_16x16x32_bf16 v[70:73], v[214:217], v[206:209], v[70:73]
	v_mfma_f32_16x16x32_bf16 v[66:69], v[222:225], v[206:209], v[66:69]
	s_setprio 0
	s_mov_b32 m0, s5
	v_lshl_add_u64 v[226:227], s[10:11], 0, v[164:165]
	s_barrier
	ds_read_b128 v[146:149], v181 offset:16384
	ds_read_b128 v[150:153], v181 offset:17408
	ds_read_b128 v[154:157], v181 offset:18432
	ds_read_b128 v[170:173], v181 offset:19456
	ds_read_b128 v[174:177], v181 offset:20480
	ds_read_b128 v[184:187], v181 offset:21504
	ds_read_b128 v[188:191], v181 offset:22528
	ds_read_b128 v[206:209], v181 offset:23552
	global_load_lds_dwordx4 v[226:227], off
	v_lshl_add_u64 v[228:229], s[10:11], 0, v[160:161]
	s_mov_b32 m0, s26
	s_nop 0
	global_load_lds_dwordx4 v[228:229], off
	s_barrier
	s_waitcnt lgkmcnt(0)
	s_setprio 1
	v_mfma_f32_16x16x32_bf16 v[62:65], v[130:133], v[146:149], v[62:65]
	v_mfma_f32_16x16x32_bf16 v[58:61], v[138:141], v[146:149], v[58:61]
	v_mfma_f32_16x16x32_bf16 v[46:49], v[130:133], v[154:157], v[46:49]
	v_mfma_f32_16x16x32_bf16 v[42:45], v[138:141], v[154:157], v[42:45]
	v_mfma_f32_16x16x32_bf16 v[30:33], v[130:133], v[174:177], v[30:33]
	v_mfma_f32_16x16x32_bf16 v[26:29], v[138:141], v[174:177], v[26:29]
	v_mfma_f32_16x16x32_bf16 v[14:17], v[130:133], v[188:191], v[14:17]
	v_mfma_f32_16x16x32_bf16 v[10:13], v[138:141], v[188:191], v[10:13]
	v_mfma_f32_16x16x32_bf16 v[62:65], v[134:137], v[150:153], v[62:65]
	v_mfma_f32_16x16x32_bf16 v[58:61], v[142:145], v[150:153], v[58:61]
	v_mfma_f32_16x16x32_bf16 v[46:49], v[134:137], v[170:173], v[46:49]
	v_mfma_f32_16x16x32_bf16 v[42:45], v[142:145], v[170:173], v[42:45]
	v_mfma_f32_16x16x32_bf16 v[30:33], v[134:137], v[184:187], v[30:33]
	v_mfma_f32_16x16x32_bf16 v[26:29], v[142:145], v[184:187], v[26:29]
	v_mfma_f32_16x16x32_bf16 v[14:17], v[134:137], v[206:209], v[14:17]
	v_mfma_f32_16x16x32_bf16 v[10:13], v[142:145], v[206:209], v[10:13]
	s_setprio 0
	s_barrier
	s_add_u32 s80, s8, 0x100000
	s_addc_u32 s81, s9, 0
	s_mov_b32 m0, s34
	v_lshl_add_u64 v[130:131], s[80:81], 0, v[162:163]
	global_load_lds_dwordx4 v[130:131], off
	v_lshl_add_u64 v[130:131], s[80:81], 0, v[158:159]
	s_mov_b32 m0, s35
	s_nop 0
	global_load_lds_dwordx4 v[130:131], off
	s_waitcnt vmcnt(6)
	s_barrier
	s_setprio 1
	v_mfma_f32_16x16x32_bf16 v[54:57], v[210:213], v[146:149], v[54:57]
	v_mfma_f32_16x16x32_bf16 v[50:53], v[218:221], v[146:149], v[50:53]
	v_mfma_f32_16x16x32_bf16 v[38:41], v[210:213], v[154:157], v[38:41]
	v_mfma_f32_16x16x32_bf16 v[34:37], v[218:221], v[154:157], v[34:37]
	v_mfma_f32_16x16x32_bf16 v[22:25], v[210:213], v[174:177], v[22:25]
	v_mfma_f32_16x16x32_bf16 v[18:21], v[218:221], v[174:177], v[18:21]
	v_mfma_f32_16x16x32_bf16 v[6:9], v[210:213], v[188:191], v[6:9]
	v_mfma_f32_16x16x32_bf16 v[2:5], v[218:221], v[188:191], v[2:5]
	v_mfma_f32_16x16x32_bf16 v[54:57], v[214:217], v[150:153], v[54:57]
	v_mfma_f32_16x16x32_bf16 v[50:53], v[222:225], v[150:153], v[50:53]
	v_mfma_f32_16x16x32_bf16 v[38:41], v[214:217], v[170:173], v[38:41]
	v_mfma_f32_16x16x32_bf16 v[34:37], v[222:225], v[170:173], v[34:37]
	v_mfma_f32_16x16x32_bf16 v[22:25], v[214:217], v[184:187], v[22:25]
	v_mfma_f32_16x16x32_bf16 v[18:21], v[222:225], v[184:187], v[18:21]
	v_mfma_f32_16x16x32_bf16 v[6:9], v[214:217], v[206:209], v[6:9]
	v_mfma_f32_16x16x32_bf16 v[2:5], v[222:225], v[206:209], v[2:5]
	s_setprio 0
	v_or_b32_e32 v130, 0x18000, v182
	v_add_u32_e32 v134, 0x18400, v182
	v_add_u32_e32 v138, 0x18800, v182
	v_add_u32_e32 v142, 0x18c00, v182
	s_barrier
	ds_read_b128 v[130:133], v130
	ds_read_b128 v[134:137], v134
	ds_read_b128 v[138:141], v138
	ds_read_b128 v[142:145], v142
	s_add_u32 s10, s10, 0x100000
	s_addc_u32 s11, s11, 0
	s_mov_b32 m0, s42
	v_lshl_add_u64 v[210:211], s[10:11], 0, v[164:165]
	ds_read_b128 v[146:149], v181 offset:32768
	ds_read_b128 v[150:153], v181 offset:33792
	ds_read_b128 v[154:157], v181 offset:34816
	ds_read_b128 v[170:173], v181 offset:35840
	ds_read_b128 v[174:177], v181 offset:36864
	ds_read_b128 v[184:187], v181 offset:37888
	ds_read_b128 v[188:191], v181 offset:38912
	ds_read_b128 v[206:209], v181 offset:39936
	global_load_lds_dwordx4 v[210:211], off
	v_lshl_add_u64 v[210:211], s[10:11], 0, v[160:161]
	s_mov_b32 m0, s54
	s_nop 0
	global_load_lds_dwordx4 v[210:211], off
	s_waitcnt lgkmcnt(8)
	s_barrier
	s_waitcnt lgkmcnt(0)
	s_setprio 1
	v_mfma_f32_16x16x32_bf16 v[126:129], v[130:133], v[146:149], v[126:129]
	v_mfma_f32_16x16x32_bf16 v[122:125], v[138:141], v[146:149], v[122:125]
	v_mfma_f32_16x16x32_bf16 v[110:113], v[130:133], v[154:157], v[110:113]
	v_mfma_f32_16x16x32_bf16 v[106:109], v[138:141], v[154:157], v[106:109]
	v_mfma_f32_16x16x32_bf16 v[94:97], v[130:133], v[174:177], v[94:97]
	v_mfma_f32_16x16x32_bf16 v[90:93], v[138:141], v[174:177], v[90:93]
	v_mfma_f32_16x16x32_bf16 v[78:81], v[130:133], v[188:191], v[78:81]
	v_mfma_f32_16x16x32_bf16 v[74:77], v[138:141], v[188:191], v[74:77]
	v_mfma_f32_16x16x32_bf16 v[126:129], v[134:137], v[150:153], v[126:129]
	v_mfma_f32_16x16x32_bf16 v[122:125], v[142:145], v[150:153], v[122:125]
	v_mfma_f32_16x16x32_bf16 v[110:113], v[134:137], v[170:173], v[110:113]
	v_mfma_f32_16x16x32_bf16 v[106:109], v[142:145], v[170:173], v[106:109]
	v_mfma_f32_16x16x32_bf16 v[94:97], v[134:137], v[184:187], v[94:97]
	v_mfma_f32_16x16x32_bf16 v[90:93], v[142:145], v[184:187], v[90:93]
	v_mfma_f32_16x16x32_bf16 v[78:81], v[134:137], v[206:209], v[78:81]
	v_mfma_f32_16x16x32_bf16 v[74:77], v[142:145], v[206:209], v[74:77]
	s_setprio 0
	s_barrier
	v_or_b32_e32 v194, 0x1c000, v182
	s_mov_b32 m0, s55
	v_add_u32_e32 v197, 0x1c400, v182
	ds_read_b128 v[210:213], v194
	ds_read_b128 v[214:217], v197
	v_add_u32_e32 v194, 0x1c800, v182
	v_lshl_add_u64 v[178:179], v[178:179], 0, s[76:77]
	v_add_u32_e32 v197, 0x1cc00, v182
	ds_read_b128 v[218:221], v194
	ds_read_b128 v[222:225], v197
	global_load_lds_dwordx4 v[178:179], off
	v_lshl_add_u64 v[178:179], v[192:193], 0, s[76:77]
	s_mov_b32 m0, s56
	s_nop 0
	global_load_lds_dwordx4 v[178:179], off
	s_barrier
	s_waitcnt lgkmcnt(0)
	s_setprio 1
	v_mfma_f32_16x16x32_bf16 v[118:121], v[210:213], v[146:149], v[118:121]
	v_mfma_f32_16x16x32_bf16 v[114:117], v[218:221], v[146:149], v[114:117]
	v_mfma_f32_16x16x32_bf16 v[102:105], v[210:213], v[154:157], v[102:105]
	v_mfma_f32_16x16x32_bf16 v[98:101], v[218:221], v[154:157], v[98:101]
	v_mfma_f32_16x16x32_bf16 v[86:89], v[210:213], v[174:177], v[86:89]
	v_mfma_f32_16x16x32_bf16 v[82:85], v[218:221], v[174:177], v[82:85]
	v_mfma_f32_16x16x32_bf16 v[70:73], v[210:213], v[188:191], v[70:73]
	v_mfma_f32_16x16x32_bf16 v[66:69], v[218:221], v[188:191], v[66:69]
	v_mfma_f32_16x16x32_bf16 v[118:121], v[214:217], v[150:153], v[118:121]
	v_mfma_f32_16x16x32_bf16 v[114:117], v[222:225], v[150:153], v[114:117]
	v_mfma_f32_16x16x32_bf16 v[102:105], v[214:217], v[170:173], v[102:105]
	v_mfma_f32_16x16x32_bf16 v[98:101], v[222:225], v[170:173], v[98:101]
	v_mfma_f32_16x16x32_bf16 v[86:89], v[214:217], v[184:187], v[86:89]
	v_mfma_f32_16x16x32_bf16 v[82:85], v[222:225], v[184:187], v[82:85]
	v_mfma_f32_16x16x32_bf16 v[70:73], v[214:217], v[206:209], v[70:73]
	v_mfma_f32_16x16x32_bf16 v[66:69], v[222:225], v[206:209], v[66:69]
	s_setprio 0
	s_mov_b32 m0, s57
	v_lshl_add_u64 v[178:179], v[226:227], 0, s[76:77]
	s_barrier
	ds_read_b128 v[146:149], v181 offset:49152
	ds_read_b128 v[150:153], v181 offset:50176
	ds_read_b128 v[154:157], v181 offset:51200
	ds_read_b128 v[170:173], v181 offset:52224
	ds_read_b128 v[174:177], v181 offset:53248
	ds_read_b128 v[184:187], v181 offset:54272
	ds_read_b128 v[188:191], v181 offset:55296
	ds_read_b128 v[206:209], v181 offset:56320
	global_load_lds_dwordx4 v[178:179], off
	v_lshl_add_u64 v[178:179], v[228:229], 0, s[76:77]
	s_mov_b32 m0, s58
	s_nop 0
	global_load_lds_dwordx4 v[178:179], off
	s_barrier
	s_waitcnt lgkmcnt(0)
	s_setprio 1
	v_mfma_f32_16x16x32_bf16 v[62:65], v[130:133], v[146:149], v[62:65]
	v_mfma_f32_16x16x32_bf16 v[58:61], v[138:141], v[146:149], v[58:61]
	v_mfma_f32_16x16x32_bf16 v[46:49], v[130:133], v[154:157], v[46:49]
	v_mfma_f32_16x16x32_bf16 v[42:45], v[138:141], v[154:157], v[42:45]
	v_mfma_f32_16x16x32_bf16 v[30:33], v[130:133], v[174:177], v[30:33]
	v_mfma_f32_16x16x32_bf16 v[26:29], v[138:141], v[174:177], v[26:29]
	v_mfma_f32_16x16x32_bf16 v[14:17], v[130:133], v[188:191], v[14:17]
	v_mfma_f32_16x16x32_bf16 v[10:13], v[138:141], v[188:191], v[10:13]
	v_mfma_f32_16x16x32_bf16 v[62:65], v[134:137], v[150:153], v[62:65]
	v_mfma_f32_16x16x32_bf16 v[58:61], v[142:145], v[150:153], v[58:61]
	v_mfma_f32_16x16x32_bf16 v[46:49], v[134:137], v[170:173], v[46:49]
	v_mfma_f32_16x16x32_bf16 v[42:45], v[142:145], v[170:173], v[42:45]
	v_mfma_f32_16x16x32_bf16 v[30:33], v[134:137], v[184:187], v[30:33]
	v_mfma_f32_16x16x32_bf16 v[26:29], v[142:145], v[184:187], v[26:29]
	v_mfma_f32_16x16x32_bf16 v[14:17], v[134:137], v[206:209], v[14:17]
	v_mfma_f32_16x16x32_bf16 v[10:13], v[142:145], v[206:209], v[10:13]
	s_setprio 0
	s_barrier
	s_add_u32 s8, s8, 0x100080
	s_addc_u32 s9, s9, 0
	s_mov_b32 m0, s59
	v_lshl_add_u64 v[130:131], s[8:9], 0, v[162:163]
	global_load_lds_dwordx4 v[130:131], off
	v_lshl_add_u64 v[130:131], s[8:9], 0, v[158:159]
	s_mov_b32 m0, s67
	s_nop 0
	global_load_lds_dwordx4 v[130:131], off
	s_waitcnt vmcnt(6)
	s_barrier
	s_setprio 1
	v_mfma_f32_16x16x32_bf16 v[54:57], v[210:213], v[146:149], v[54:57]
	v_mfma_f32_16x16x32_bf16 v[50:53], v[218:221], v[146:149], v[50:53]
	v_mfma_f32_16x16x32_bf16 v[38:41], v[210:213], v[154:157], v[38:41]
	v_mfma_f32_16x16x32_bf16 v[34:37], v[218:221], v[154:157], v[34:37]
	v_mfma_f32_16x16x32_bf16 v[22:25], v[210:213], v[174:177], v[22:25]
	v_mfma_f32_16x16x32_bf16 v[18:21], v[218:221], v[174:177], v[18:21]
	v_mfma_f32_16x16x32_bf16 v[6:9], v[210:213], v[188:191], v[6:9]
	v_mfma_f32_16x16x32_bf16 v[2:5], v[218:221], v[188:191], v[2:5]
	v_mfma_f32_16x16x32_bf16 v[54:57], v[214:217], v[150:153], v[54:57]
	v_mfma_f32_16x16x32_bf16 v[50:53], v[222:225], v[150:153], v[50:53]
	v_mfma_f32_16x16x32_bf16 v[38:41], v[214:217], v[170:173], v[38:41]
	v_mfma_f32_16x16x32_bf16 v[34:37], v[222:225], v[170:173], v[34:37]
	v_mfma_f32_16x16x32_bf16 v[22:25], v[214:217], v[184:187], v[22:25]
	v_mfma_f32_16x16x32_bf16 v[18:21], v[222:225], v[184:187], v[18:21]
	v_mfma_f32_16x16x32_bf16 v[6:9], v[214:217], v[206:209], v[6:9]
	v_mfma_f32_16x16x32_bf16 v[2:5], v[222:225], v[206:209], v[2:5]
	s_setprio 0
	s_add_i32 s79, s79, 2
	s_add_u32 s6, s6, 0x100
	s_addc_u32 s7, s7, 0
	s_add_u32 s1, s1, 0x100
	s_addc_u32 s78, s78, 0
	s_cmp_gt_u32 s79, 61
	s_barrier
	s_cbranch_scc0 .LBB0_255
	s_lshl_b32 s1, s28, 9
	s_and_b32 s1, s1, 0xfffff800
	s_lshl_b32 s6, s29, 8
	s_add_i32 s1, s1, s6
	v_add_u32_e32 v172, s1, v180
	s_lshl_b32 s1, s28, 8
	s_and_b32 s1, s1, 0x300
	v_or_b32_e32 v132, s1, v183
	v_mov_b64_e32 v[170:171], s[50:51]
	v_mad_i64_i32 v[130:131], s[6:7], v172, s37, v[170:171]
	v_lshlrev_b32_e32 v194, 1, v132
	v_lshl_add_u64 v[130:131], v[130:131], 0, v[194:195]
	v_lshl_add_u64 v[132:133], v[130:131], 0, s[84:85]
	v_add_co_u32_e32 v130, vcc, s16, v130
	v_or_b32_e32 v178, 16, v172
	s_nop 0
	v_addc_co_u32_e32 v131, vcc, 0, v131, vcc
	global_load_dwordx4 v[184:187], v[130:131], off offset:2048
	global_load_dwordx4 v[154:157], v[132:133], off offset:256
	v_mad_i64_i32 v[130:131], s[6:7], v178, s37, v[170:171]
	v_lshl_add_u64 v[130:131], v[130:131], 0, v[194:195]
	v_lshl_add_u64 v[132:133], v[130:131], 0, s[84:85]
	v_add_co_u32_e32 v130, vcc, s16, v130
	v_or_b32_e32 v176, 32, v172
	s_nop 0
	v_addc_co_u32_e32 v131, vcc, 0, v131, vcc
	global_load_dwordx4 v[150:153], v[130:131], off offset:2048
	global_load_dwordx4 v[146:149], v[132:133], off offset:256
	v_mad_i64_i32 v[130:131], s[6:7], v176, s37, v[170:171]
	v_lshl_add_u64 v[130:131], v[130:131], 0, v[194:195]
	v_lshl_add_u64 v[132:133], v[130:131], 0, s[84:85]
	v_add_co_u32_e32 v130, vcc, s16, v130
	v_or_b32_e32 v174, 48, v172
	s_nop 0
	v_addc_co_u32_e32 v131, vcc, 0, v131, vcc
	global_load_dwordx4 v[142:145], v[130:131], off offset:2048
	global_load_dwordx4 v[138:141], v[132:133], off offset:256
	v_mad_i64_i32 v[130:131], s[6:7], v174, s37, v[170:171]
	v_lshl_add_u64 v[130:131], v[130:131], 0, v[194:195]
	v_lshl_add_u64 v[132:133], v[130:131], 0, s[84:85]
	v_add_co_u32_e32 v130, vcc, s16, v130
	v_pk_mul_f32 v[126:127], v[126:127], s[72:73] op_sel_hi:[1,0]
	s_nop 0
	v_addc_co_u32_e32 v131, vcc, 0, v131, vcc
	global_load_dwordx4 v[134:137], v[130:131], off offset:2048
	s_nop 0
	global_load_dwordx4 v[130:133], v[132:133], off offset:256
	v_pk_mul_f32 v[190:191], v[124:125], s[72:73] op_sel_hi:[1,0]
	v_pk_mul_f32 v[128:129], v[128:129], s[72:73] op_sel_hi:[1,0]
	v_pk_mul_f32 v[122:123], v[122:123], s[72:73] op_sel_hi:[1,0]
	v_ashrrev_i32_e32 v173, 31, v172
	v_lshlrev_b64 v[188:189], 11, v[172:173]
	v_pk_mul_f32 v[118:119], v[118:119], s[72:73] op_sel_hi:[1,0]
	v_pk_mul_f32 v[120:121], v[120:121], s[72:73] op_sel_hi:[1,0]
	v_pk_mul_f32 v[110:111], v[110:111], s[72:73] op_sel_hi:[1,0]
	v_pk_mul_f32 v[112:113], v[112:113], s[72:73] op_sel_hi:[1,0]
	v_ashrrev_i32_e32 v179, 31, v178
	v_pk_mul_f32 v[102:103], v[102:103], s[72:73] op_sel_hi:[1,0]
	v_pk_mul_f32 v[104:105], v[104:105], s[72:73] op_sel_hi:[1,0]
	v_pk_mul_f32 v[94:95], v[94:95], s[72:73] op_sel_hi:[1,0]
	v_pk_mul_f32 v[96:97], v[96:97], s[72:73] op_sel_hi:[1,0]
	v_ashrrev_i32_e32 v177, 31, v176
	v_pk_mul_f32 v[86:87], v[86:87], s[72:73] op_sel_hi:[1,0]
	v_pk_mul_f32 v[88:89], v[88:89], s[72:73] op_sel_hi:[1,0]
	v_pk_mul_f32 v[78:79], v[78:79], s[72:73] op_sel_hi:[1,0]
	v_pk_mul_f32 v[80:81], v[80:81], s[72:73] op_sel_hi:[1,0]
	v_ashrrev_i32_e32 v175, 31, v174
	v_pk_mul_f32 v[70:71], v[70:71], s[72:73] op_sel_hi:[1,0]
	v_pk_mul_f32 v[72:73], v[72:73], s[72:73] op_sel_hi:[1,0]
	s_waitcnt vmcnt(0)
	v_lshlrev_b32_e32 v124, 16, v184
	v_and_b32_e32 v125, 0xffff0000, v184
	v_mul_f32_e32 v124, v126, v124
	v_mul_f32_e32 v125, v127, v125
	v_cvt_pk_bf16_f32 v124, v124, v125
	v_lshlrev_b32_e32 v125, 16, v185
	v_and_b32_e32 v126, 0xffff0000, v185
	v_mul_f32_e32 v125, v128, v125
	v_mul_f32_e32 v126, v129, v126
	v_cvt_pk_bf16_f32 v125, v125, v126
	v_lshlrev_b32_e32 v126, 16, v186
	v_mul_f32_e32 v122, v122, v126
	v_and_b32_e32 v126, 0xffff0000, v186
	v_mul_f32_e32 v123, v123, v126
	v_cvt_pk_bf16_f32 v126, v122, v123
	v_lshlrev_b32_e32 v122, 16, v187
	v_and_b32_e32 v123, 0xffff0000, v187
	v_mul_f32_e32 v122, v190, v122
	v_mul_f32_e32 v123, v191, v123
	v_cvt_pk_bf16_f32 v127, v122, v123
	v_lshl_add_u64 v[122:123], s[74:75], 0, v[188:189]
	v_lshl_add_u64 v[122:123], v[122:123], 0, v[194:195]
	global_store_dwordx4 v[122:123], v[124:127], off
	s_nop 1
	v_pk_mul_f32 v[124:125], v[116:117], s[72:73] op_sel_hi:[1,0]
	v_pk_mul_f32 v[116:117], v[114:115], s[72:73] op_sel_hi:[1,0]
	v_lshlrev_b32_e32 v114, 16, v154
	v_and_b32_e32 v115, 0xffff0000, v154
	v_mul_f32_e32 v114, v118, v114
	v_mul_f32_e32 v115, v119, v115
	v_cvt_pk_bf16_f32 v114, v114, v115
	v_lshlrev_b32_e32 v115, 16, v155
	v_and_b32_e32 v118, 0xffff0000, v155
	v_mul_f32_e32 v115, v120, v115
	v_mul_f32_e32 v118, v121, v118
	v_cvt_pk_bf16_f32 v115, v115, v118
	v_lshlrev_b32_e32 v118, 16, v156
	v_mul_f32_e32 v116, v116, v118
	v_and_b32_e32 v118, 0xffff0000, v156
	v_mul_f32_e32 v117, v117, v118
	v_cvt_pk_bf16_f32 v116, v116, v117
	v_lshlrev_b32_e32 v117, 16, v157
	v_mul_f32_e32 v117, v124, v117
	v_and_b32_e32 v118, 0xffff0000, v157
	v_mul_f32_e32 v118, v125, v118
	v_cvt_pk_bf16_f32 v117, v117, v118
	global_store_dwordx4 v[122:123], v[114:117], off offset:256
	s_nop 1
	v_pk_mul_f32 v[116:117], v[108:109], s[72:73] op_sel_hi:[1,0]
	v_pk_mul_f32 v[108:109], v[106:107], s[72:73] op_sel_hi:[1,0]
	v_lshlrev_b32_e32 v106, 16, v150
	v_and_b32_e32 v107, 0xffff0000, v150
	v_mul_f32_e32 v106, v110, v106
	v_mul_f32_e32 v107, v111, v107
	v_cvt_pk_bf16_f32 v106, v106, v107
	v_lshlrev_b32_e32 v107, 16, v151
	v_and_b32_e32 v110, 0xffff0000, v151
	v_mul_f32_e32 v107, v112, v107
	v_mul_f32_e32 v110, v113, v110
	v_cvt_pk_bf16_f32 v107, v107, v110
	v_lshlrev_b32_e32 v110, 16, v152
	v_mul_f32_e32 v108, v108, v110
	v_and_b32_e32 v110, 0xffff0000, v152
	v_mul_f32_e32 v109, v109, v110
	v_cvt_pk_bf16_f32 v108, v108, v109
	v_lshlrev_b32_e32 v109, 16, v153
	v_and_b32_e32 v110, 0xffff0000, v153
	v_lshlrev_b64 v[114:115], 11, v[178:179]
	v_mul_f32_e32 v109, v116, v109
	v_mul_f32_e32 v110, v117, v110
	v_cvt_pk_bf16_f32 v109, v109, v110
	v_lshl_add_u64 v[110:111], s[74:75], 0, v[114:115]
	v_lshl_add_u64 v[110:111], v[110:111], 0, v[194:195]
	global_store_dwordx4 v[110:111], v[106:109], off
	s_nop 1
	v_pk_mul_f32 v[106:107], v[100:101], s[72:73] op_sel_hi:[1,0]
	v_pk_mul_f32 v[100:101], v[98:99], s[72:73] op_sel_hi:[1,0]
	v_lshlrev_b32_e32 v98, 16, v146
	v_and_b32_e32 v99, 0xffff0000, v146
	v_mul_f32_e32 v98, v102, v98
	v_mul_f32_e32 v99, v103, v99
	v_cvt_pk_bf16_f32 v98, v98, v99
	v_lshlrev_b32_e32 v99, 16, v147
	v_and_b32_e32 v102, 0xffff0000, v147
	v_mul_f32_e32 v99, v104, v99
	v_mul_f32_e32 v102, v105, v102
	v_cvt_pk_bf16_f32 v99, v99, v102
	v_lshlrev_b32_e32 v102, 16, v148
	v_mul_f32_e32 v100, v100, v102
	v_and_b32_e32 v102, 0xffff0000, v148
	v_mul_f32_e32 v101, v101, v102
	v_cvt_pk_bf16_f32 v100, v100, v101
	v_lshlrev_b32_e32 v101, 16, v149
	v_mul_f32_e32 v101, v106, v101
	v_and_b32_e32 v102, 0xffff0000, v149
	v_mul_f32_e32 v102, v107, v102
	v_cvt_pk_bf16_f32 v101, v101, v102
	global_store_dwordx4 v[110:111], v[98:101], off offset:256
	s_nop 1
	v_pk_mul_f32 v[100:101], v[92:93], s[72:73] op_sel_hi:[1,0]
	v_pk_mul_f32 v[92:93], v[90:91], s[72:73] op_sel_hi:[1,0]
	v_lshlrev_b32_e32 v90, 16, v142
	v_and_b32_e32 v91, 0xffff0000, v142
	v_mul_f32_e32 v90, v94, v90
	v_mul_f32_e32 v91, v95, v91
	v_cvt_pk_bf16_f32 v90, v90, v91
	v_lshlrev_b32_e32 v91, 16, v143
	v_and_b32_e32 v94, 0xffff0000, v143
	v_mul_f32_e32 v91, v96, v91
	v_mul_f32_e32 v94, v97, v94
	v_cvt_pk_bf16_f32 v91, v91, v94
	v_lshlrev_b32_e32 v94, 16, v144
	v_mul_f32_e32 v92, v92, v94
	v_and_b32_e32 v94, 0xffff0000, v144
	v_mul_f32_e32 v93, v93, v94
	v_cvt_pk_bf16_f32 v92, v92, v93
	v_lshlrev_b32_e32 v93, 16, v145
	v_and_b32_e32 v94, 0xffff0000, v145
	v_lshlrev_b64 v[98:99], 11, v[176:177]
	v_mul_f32_e32 v93, v100, v93
	v_mul_f32_e32 v94, v101, v94
	v_cvt_pk_bf16_f32 v93, v93, v94
	v_lshl_add_u64 v[94:95], s[74:75], 0, v[98:99]
	v_lshl_add_u64 v[94:95], v[94:95], 0, v[194:195]
	global_store_dwordx4 v[94:95], v[90:93], off
	s_nop 1
	v_pk_mul_f32 v[90:91], v[84:85], s[72:73] op_sel_hi:[1,0]
	v_pk_mul_f32 v[84:85], v[82:83], s[72:73] op_sel_hi:[1,0]
	v_lshlrev_b32_e32 v82, 16, v138
	v_and_b32_e32 v83, 0xffff0000, v138
	v_mul_f32_e32 v82, v86, v82
	v_mul_f32_e32 v83, v87, v83
	v_cvt_pk_bf16_f32 v82, v82, v83
	v_lshlrev_b32_e32 v83, 16, v139
	v_and_b32_e32 v86, 0xffff0000, v139
	v_mul_f32_e32 v83, v88, v83
	v_mul_f32_e32 v86, v89, v86
	v_cvt_pk_bf16_f32 v83, v83, v86
	v_lshlrev_b32_e32 v86, 16, v140
	v_mul_f32_e32 v84, v84, v86
	v_and_b32_e32 v86, 0xffff0000, v140
	v_mul_f32_e32 v85, v85, v86
	v_cvt_pk_bf16_f32 v84, v84, v85
	v_lshlrev_b32_e32 v85, 16, v141
	v_mul_f32_e32 v85, v90, v85
	v_and_b32_e32 v86, 0xffff0000, v141
	v_mul_f32_e32 v86, v91, v86
	v_cvt_pk_bf16_f32 v85, v85, v86
	global_store_dwordx4 v[94:95], v[82:85], off offset:256
	s_nop 1
	v_pk_mul_f32 v[84:85], v[76:77], s[72:73] op_sel_hi:[1,0]
	v_pk_mul_f32 v[76:77], v[74:75], s[72:73] op_sel_hi:[1,0]
	v_lshlrev_b32_e32 v74, 16, v134
	v_and_b32_e32 v75, 0xffff0000, v134
	v_mul_f32_e32 v74, v78, v74
	v_mul_f32_e32 v75, v79, v75
	v_cvt_pk_bf16_f32 v74, v74, v75
	v_lshlrev_b32_e32 v75, 16, v135
	v_and_b32_e32 v78, 0xffff0000, v135
	v_mul_f32_e32 v75, v80, v75
	v_mul_f32_e32 v78, v81, v78
	v_cvt_pk_bf16_f32 v75, v75, v78
	v_lshlrev_b32_e32 v78, 16, v136
	v_mul_f32_e32 v76, v76, v78
	v_and_b32_e32 v78, 0xffff0000, v136
	v_mul_f32_e32 v77, v77, v78
	v_cvt_pk_bf16_f32 v76, v76, v77
	v_lshlrev_b32_e32 v77, 16, v137
	v_and_b32_e32 v78, 0xffff0000, v137
	v_lshlrev_b64 v[82:83], 11, v[174:175]
	v_mul_f32_e32 v77, v84, v77
	v_mul_f32_e32 v78, v85, v78
	v_cvt_pk_bf16_f32 v77, v77, v78
	v_lshl_add_u64 v[78:79], s[74:75], 0, v[82:83]
	v_lshl_add_u64 v[78:79], v[78:79], 0, v[194:195]
	global_store_dwordx4 v[78:79], v[74:77], off
	s_nop 1
	v_pk_mul_f32 v[74:75], v[68:69], s[72:73] op_sel_hi:[1,0]
	v_pk_mul_f32 v[68:69], v[66:67], s[72:73] op_sel_hi:[1,0]
	v_lshlrev_b32_e32 v66, 16, v130
	v_and_b32_e32 v67, 0xffff0000, v130
	v_mul_f32_e32 v66, v70, v66
	v_mul_f32_e32 v67, v71, v67
	v_cvt_pk_bf16_f32 v66, v66, v67
	v_lshlrev_b32_e32 v67, 16, v131
	v_and_b32_e32 v70, 0xffff0000, v131
	v_mul_f32_e32 v67, v72, v67
	v_mul_f32_e32 v70, v73, v70
	v_cvt_pk_bf16_f32 v67, v67, v70
	v_lshlrev_b32_e32 v70, 16, v132
	v_mul_f32_e32 v68, v68, v70
	v_and_b32_e32 v70, 0xffff0000, v132
	v_mul_f32_e32 v69, v69, v70
	v_cvt_pk_bf16_f32 v68, v68, v69
	v_lshlrev_b32_e32 v69, 16, v133
	v_mul_f32_e32 v69, v74, v69
	v_and_b32_e32 v70, 0xffff0000, v133
	v_mul_f32_e32 v70, v75, v70
	v_cvt_pk_bf16_f32 v69, v69, v70
	global_store_dwordx4 v[78:79], v[66:69], off offset:256
	v_add_u32_e32 v78, 0x80, v172
	s_nop 0
	v_mad_i64_i32 v[66:67], s[6:7], v78, s37, v[170:171]
	v_lshl_add_u64 v[66:67], v[66:67], 0, v[194:195]
	v_add_co_u32_e32 v68, vcc, s16, v66
	v_add_u32_e32 v86, 0x90, v172
	s_nop 0
	v_addc_co_u32_e32 v69, vcc, 0, v67, vcc
	global_load_dwordx4 v[70:73], v[68:69], off offset:2048
	v_lshl_add_u64 v[66:67], v[66:67], 0, s[84:85]
	global_load_dwordx4 v[74:77], v[66:67], off offset:256
	v_pk_mul_f32 v[96:97], v[56:57], s[72:73] op_sel_hi:[1,0]
	v_mad_i64_i32 v[56:57], s[6:7], v86, s37, v[170:171]
	v_lshl_add_u64 v[56:57], v[56:57], 0, v[194:195]
	v_pk_mul_f32 v[94:95], v[58:59], s[72:73] op_sel_hi:[1,0]
	v_add_co_u32_e32 v58, vcc, s16, v56
	v_pk_mul_f32 v[92:93], v[60:61], s[72:73] op_sel_hi:[1,0]
	s_nop 0
	v_addc_co_u32_e32 v59, vcc, 0, v57, vcc
	global_load_dwordx4 v[58:61], v[58:59], off offset:2048
	v_add_u32_e32 v68, 0xa0, v172
	v_pk_mul_f32 v[102:103], v[50:51], s[72:73] op_sel_hi:[1,0]
	v_mad_i64_i32 v[50:51], s[6:7], v68, s37, v[170:171]
	v_add_u32_e32 v66, 0xb0, v172
	v_lshl_add_u64 v[50:51], v[50:51], 0, v[194:195]
	v_pk_mul_f32 v[100:101], v[52:53], s[72:73] op_sel_hi:[1,0]
	v_mad_i64_i32 v[52:53], s[6:7], v66, s37, v[170:171]
	v_lshl_add_u64 v[82:83], v[50:51], 0, s[84:85]
	v_add_co_u32_e32 v50, vcc, s16, v50
	v_lshl_add_u64 v[52:53], v[52:53], 0, v[194:195]
	s_nop 0
	v_addc_co_u32_e32 v51, vcc, 0, v51, vcc
	v_ashrrev_i32_e32 v79, 31, v78
	v_lshl_add_u64 v[104:105], v[52:53], 0, s[84:85]
	v_add_co_u32_e32 v52, vcc, s16, v52
	v_pk_mul_f32 v[98:99], v[54:55], s[72:73] op_sel_hi:[1,0]
	v_lshlrev_b64 v[54:55], 11, v[78:79]
	v_lshl_add_u64 v[56:57], v[56:57], 0, s[84:85]
	v_addc_co_u32_e32 v53, vcc, 0, v53, vcc
	v_pk_mul_f32 v[88:89], v[64:65], s[72:73] op_sel_hi:[1,0]
	v_pk_mul_f32 v[90:91], v[62:63], s[72:73] op_sel_hi:[1,0]
	v_lshl_add_u64 v[106:107], s[74:75], 0, v[54:55]
	global_load_dwordx4 v[62:65], v[56:57], off offset:256
	global_load_dwordx4 v[78:81], v[50:51], off offset:2048
	s_nop 0
	global_load_dwordx4 v[82:85], v[82:83], off offset:256
	s_nop 0
	global_load_dwordx4 v[54:57], v[52:53], off offset:2048
	s_nop 0
	global_load_dwordx4 v[50:53], v[104:105], off offset:256
	v_lshl_add_u64 v[104:105], v[106:107], 0, v[194:195]
	v_pk_mul_f32 v[46:47], v[46:47], s[72:73] op_sel_hi:[1,0]
	v_pk_mul_f32 v[48:49], v[48:49], s[72:73] op_sel_hi:[1,0]
	v_ashrrev_i32_e32 v87, 31, v86
	v_pk_mul_f32 v[38:39], v[38:39], s[72:73] op_sel_hi:[1,0]
	v_pk_mul_f32 v[40:41], v[40:41], s[72:73] op_sel_hi:[1,0]
	v_pk_mul_f32 v[30:31], v[30:31], s[72:73] op_sel_hi:[1,0]
	v_pk_mul_f32 v[32:33], v[32:33], s[72:73] op_sel_hi:[1,0]
	v_ashrrev_i32_e32 v69, 31, v68
	v_pk_mul_f32 v[22:23], v[22:23], s[72:73] op_sel_hi:[1,0]
	v_pk_mul_f32 v[24:25], v[24:25], s[72:73] op_sel_hi:[1,0]
	v_pk_mul_f32 v[14:15], v[14:15], s[72:73] op_sel_hi:[1,0]
	v_pk_mul_f32 v[16:17], v[16:17], s[72:73] op_sel_hi:[1,0]
	v_ashrrev_i32_e32 v67, 31, v66
	v_pk_mul_f32 v[6:7], v[6:7], s[72:73] op_sel_hi:[1,0]
	v_pk_mul_f32 v[8:9], v[8:9], s[72:73] op_sel_hi:[1,0]
	s_waitcnt vmcnt(0)
	v_lshlrev_b32_e32 v106, 16, v70
	v_and_b32_e32 v70, 0xffff0000, v70
	v_lshlrev_b32_e32 v107, 16, v71
	v_and_b32_e32 v71, 0xffff0000, v71
	v_lshlrev_b32_e32 v108, 16, v72
	v_and_b32_e32 v72, 0xffff0000, v72
	v_lshlrev_b32_e32 v109, 16, v73
	v_and_b32_e32 v73, 0xffff0000, v73
	v_mul_f32_e32 v70, v91, v70
	v_mul_f32_e32 v71, v89, v71
	v_mul_f32_e32 v72, v95, v72
	v_mul_f32_e32 v73, v93, v73
	v_mul_f32_e32 v90, v90, v106
	v_mul_f32_e32 v88, v88, v107
	v_mul_f32_e32 v89, v94, v108
	v_mul_f32_e32 v91, v92, v109
	v_cvt_pk_bf16_f32 v70, v90, v70
	v_cvt_pk_bf16_f32 v71, v88, v71
	v_cvt_pk_bf16_f32 v72, v89, v72
	v_cvt_pk_bf16_f32 v73, v91, v73
	v_lshlrev_b32_e32 v111, 16, v75
	v_and_b32_e32 v75, 0xffff0000, v75
	global_store_dwordx4 v[104:105], v[70:73], off
	v_lshlrev_b32_e32 v110, 16, v74
	v_and_b32_e32 v74, 0xffff0000, v74
	v_lshlrev_b32_e32 v72, 16, v76
	v_and_b32_e32 v73, 0xffff0000, v76
	v_mul_f32_e32 v71, v97, v75
	v_mul_f32_e32 v72, v102, v72
	v_mul_f32_e32 v73, v103, v73
	v_mul_f32_e32 v92, v98, v110
	v_mul_f32_e32 v74, v99, v74
	v_mul_f32_e32 v93, v96, v111
	v_cvt_pk_bf16_f32 v70, v92, v74
	v_cvt_pk_bf16_f32 v71, v93, v71
	v_cvt_pk_bf16_f32 v72, v72, v73
	v_lshlrev_b32_e32 v73, 16, v77
	v_mul_f32_e32 v73, v100, v73
	v_and_b32_e32 v74, 0xffff0000, v77
	v_mul_f32_e32 v74, v101, v74
	v_cvt_pk_bf16_f32 v73, v73, v74
	global_store_dwordx4 v[104:105], v[70:73], off offset:256
	s_nop 1
	v_pk_mul_f32 v[72:73], v[44:45], s[72:73] op_sel_hi:[1,0]
	v_pk_mul_f32 v[44:45], v[42:43], s[72:73] op_sel_hi:[1,0]
	v_lshlrev_b32_e32 v42, 16, v58
	v_and_b32_e32 v43, 0xffff0000, v58
	v_mul_f32_e32 v42, v46, v42
	v_mul_f32_e32 v43, v47, v43
	v_cvt_pk_bf16_f32 v42, v42, v43
	v_lshlrev_b32_e32 v43, 16, v59
	v_and_b32_e32 v46, 0xffff0000, v59
	v_mul_f32_e32 v43, v48, v43
	v_mul_f32_e32 v46, v49, v46
	v_cvt_pk_bf16_f32 v43, v43, v46
	v_lshlrev_b32_e32 v46, 16, v60
	v_mul_f32_e32 v44, v44, v46
	v_and_b32_e32 v46, 0xffff0000, v60
	v_mul_f32_e32 v45, v45, v46
	v_cvt_pk_bf16_f32 v44, v44, v45
	v_lshlrev_b32_e32 v45, 16, v61
	v_and_b32_e32 v46, 0xffff0000, v61
	v_lshlrev_b64 v[70:71], 11, v[86:87]
	v_mul_f32_e32 v45, v72, v45
	v_mul_f32_e32 v46, v73, v46
	v_cvt_pk_bf16_f32 v45, v45, v46
	v_lshl_add_u64 v[46:47], s[74:75], 0, v[70:71]
	v_lshl_add_u64 v[46:47], v[46:47], 0, v[194:195]
	global_store_dwordx4 v[46:47], v[42:45], off
	s_nop 1
	v_pk_mul_f32 v[42:43], v[36:37], s[72:73] op_sel_hi:[1,0]
	v_pk_mul_f32 v[36:37], v[34:35], s[72:73] op_sel_hi:[1,0]
	v_lshlrev_b32_e32 v34, 16, v62
	v_and_b32_e32 v35, 0xffff0000, v62
	v_mul_f32_e32 v34, v38, v34
	v_mul_f32_e32 v35, v39, v35
	v_cvt_pk_bf16_f32 v34, v34, v35
	v_lshlrev_b32_e32 v35, 16, v63
	v_and_b32_e32 v38, 0xffff0000, v63
	v_mul_f32_e32 v35, v40, v35
	v_mul_f32_e32 v38, v41, v38
	v_cvt_pk_bf16_f32 v35, v35, v38
	v_lshlrev_b32_e32 v38, 16, v64
	v_mul_f32_e32 v36, v36, v38
	v_and_b32_e32 v38, 0xffff0000, v64
	v_mul_f32_e32 v37, v37, v38
	v_cvt_pk_bf16_f32 v36, v36, v37
	v_lshlrev_b32_e32 v37, 16, v65
	v_mul_f32_e32 v37, v42, v37
	v_and_b32_e32 v38, 0xffff0000, v65
	v_mul_f32_e32 v38, v43, v38
	v_cvt_pk_bf16_f32 v37, v37, v38
	global_store_dwordx4 v[46:47], v[34:37], off offset:256
	s_nop 1
	v_pk_mul_f32 v[36:37], v[28:29], s[72:73] op_sel_hi:[1,0]
	v_pk_mul_f32 v[28:29], v[26:27], s[72:73] op_sel_hi:[1,0]
	v_lshlrev_b32_e32 v26, 16, v78
	v_and_b32_e32 v27, 0xffff0000, v78
	v_mul_f32_e32 v26, v30, v26
	v_mul_f32_e32 v27, v31, v27
	v_cvt_pk_bf16_f32 v26, v26, v27
	v_lshlrev_b32_e32 v27, 16, v79
	v_and_b32_e32 v30, 0xffff0000, v79
	v_mul_f32_e32 v27, v32, v27
	v_mul_f32_e32 v30, v33, v30
	v_cvt_pk_bf16_f32 v27, v27, v30
	v_lshlrev_b32_e32 v30, 16, v80
	v_mul_f32_e32 v28, v28, v30
	v_and_b32_e32 v30, 0xffff0000, v80
	v_mul_f32_e32 v29, v29, v30
	v_cvt_pk_bf16_f32 v28, v28, v29
	v_lshlrev_b32_e32 v29, 16, v81
	v_and_b32_e32 v30, 0xffff0000, v81
	v_lshlrev_b64 v[34:35], 11, v[68:69]
	v_mul_f32_e32 v29, v36, v29
	v_mul_f32_e32 v30, v37, v30
	v_cvt_pk_bf16_f32 v29, v29, v30
	v_lshl_add_u64 v[30:31], s[74:75], 0, v[34:35]
	v_lshl_add_u64 v[30:31], v[30:31], 0, v[194:195]
	global_store_dwordx4 v[30:31], v[26:29], off
	s_nop 1
	v_pk_mul_f32 v[26:27], v[20:21], s[72:73] op_sel_hi:[1,0]
	v_pk_mul_f32 v[20:21], v[18:19], s[72:73] op_sel_hi:[1,0]
	v_lshlrev_b32_e32 v18, 16, v82
	v_and_b32_e32 v19, 0xffff0000, v82
	v_mul_f32_e32 v18, v22, v18
	v_mul_f32_e32 v19, v23, v19
	v_cvt_pk_bf16_f32 v18, v18, v19
	v_lshlrev_b32_e32 v19, 16, v83
	v_and_b32_e32 v22, 0xffff0000, v83
	v_mul_f32_e32 v19, v24, v19
	v_mul_f32_e32 v22, v25, v22
	v_cvt_pk_bf16_f32 v19, v19, v22
	v_lshlrev_b32_e32 v22, 16, v84
	v_mul_f32_e32 v20, v20, v22
	v_and_b32_e32 v22, 0xffff0000, v84
	v_mul_f32_e32 v21, v21, v22
	v_cvt_pk_bf16_f32 v20, v20, v21
	v_lshlrev_b32_e32 v21, 16, v85
	v_mul_f32_e32 v21, v26, v21
	v_and_b32_e32 v22, 0xffff0000, v85
	v_mul_f32_e32 v22, v27, v22
	v_cvt_pk_bf16_f32 v21, v21, v22
	global_store_dwordx4 v[30:31], v[18:21], off offset:256
	s_nop 1
	v_pk_mul_f32 v[20:21], v[12:13], s[72:73] op_sel_hi:[1,0]
	v_pk_mul_f32 v[12:13], v[10:11], s[72:73] op_sel_hi:[1,0]
	v_lshlrev_b32_e32 v10, 16, v54
	v_and_b32_e32 v11, 0xffff0000, v54
	v_mul_f32_e32 v10, v14, v10
	v_mul_f32_e32 v11, v15, v11
	v_cvt_pk_bf16_f32 v10, v10, v11
	v_lshlrev_b32_e32 v11, 16, v55
	v_and_b32_e32 v14, 0xffff0000, v55
	v_mul_f32_e32 v11, v16, v11
	v_mul_f32_e32 v14, v17, v14
	v_cvt_pk_bf16_f32 v11, v11, v14
	v_lshlrev_b32_e32 v14, 16, v56
	v_mul_f32_e32 v12, v12, v14
	v_and_b32_e32 v14, 0xffff0000, v56
	v_mul_f32_e32 v13, v13, v14
	v_cvt_pk_bf16_f32 v12, v12, v13
	v_lshlrev_b32_e32 v13, 16, v57
	v_and_b32_e32 v14, 0xffff0000, v57
	v_lshlrev_b64 v[18:19], 11, v[66:67]
	v_mul_f32_e32 v13, v20, v13
	v_mul_f32_e32 v14, v21, v14
	v_cvt_pk_bf16_f32 v13, v13, v14
	v_lshl_add_u64 v[14:15], s[74:75], 0, v[18:19]
	v_lshl_add_u64 v[14:15], v[14:15], 0, v[194:195]
	global_store_dwordx4 v[14:15], v[10:13], off
	s_nop 1
	v_pk_mul_f32 v[10:11], v[4:5], s[72:73] op_sel_hi:[1,0]
	v_pk_mul_f32 v[4:5], v[2:3], s[72:73] op_sel_hi:[1,0]
	v_lshlrev_b32_e32 v2, 16, v50
	v_and_b32_e32 v3, 0xffff0000, v50
	v_mul_f32_e32 v2, v6, v2
	v_mul_f32_e32 v3, v7, v3
	v_cvt_pk_bf16_f32 v2, v2, v3
	v_lshlrev_b32_e32 v3, 16, v51
	v_and_b32_e32 v6, 0xffff0000, v51
	v_mul_f32_e32 v3, v8, v3
	v_mul_f32_e32 v6, v9, v6
	v_cvt_pk_bf16_f32 v3, v3, v6
	v_lshlrev_b32_e32 v6, 16, v52
	v_mul_f32_e32 v4, v4, v6
	v_and_b32_e32 v6, 0xffff0000, v52
	v_mul_f32_e32 v5, v5, v6
	v_cvt_pk_bf16_f32 v4, v4, v5
	v_lshlrev_b32_e32 v5, 16, v53
	v_mul_f32_e32 v5, v10, v5
	v_and_b32_e32 v6, 0xffff0000, v53
	v_mul_f32_e32 v6, v11, v6
	v_cvt_pk_bf16_f32 v5, v5, v6
	global_store_dwordx4 v[14:15], v[2:5], off offset:256
	s_and_b64 vcc, exec, s[62:63]
	s_mov_b32 s29, s71
	s_mov_b32 s28, s0
	s_mov_b64 s[8:9], s[60:61]
	s_mov_b64 s[6:7], s[52:53]
	s_cbranch_vccz .LBB0_252
	s_waitcnt vmcnt(0)
	v_readlane_b32 s28, v250, 12
	s_cmpk_gt_u32 s4, 0xff
	v_readlane_b32 s29, v250, 13
	s_mov_b32 s70, 0x800000
	s_cbranch_scc1 .LBB0_259
	s_barrier

.LBB0_266:
	s_add_u32 s8, s6, 0x100
	s_addc_u32 s9, s7, 0
	v_or_b32_e32 v142, 0x10000, v147
	v_add_u32_e32 v150, 0x10400, v147
	v_add_u32_e32 v154, 0x10800, v147
	v_add_u32_e32 v158, 0x10c00, v147
	s_add_u32 s10, s71, s6
	ds_read_b128 v[142:145], v142
	ds_read_b128 v[150:153], v150
	ds_read_b128 v[154:157], v154
	ds_read_b128 v[158:161], v158
	s_addc_u32 s11, s78, s7
	s_cmp_eq_u32 s79, 4
	s_cselect_b32 s81, 0, s8
	s_cselect_b32 s80, 0, s9
	s_cselect_b32 s54, s29, s10
	s_cselect_b32 s55, s5, s11
	s_add_u32 s10, s18, s81
	s_addc_u32 s11, s19, s80
	v_lshl_add_u64 v[206:207], v[138:139], 0, s[6:7]
	s_add_i32 m0, s17, 0xc000
	ds_read_b128 v[162:165], v146
	ds_read_b128 v[166:169], v146 offset:1024
	ds_read_b128 v[170:173], v146 offset:2048
	ds_read_b128 v[174:177], v146 offset:3072
	ds_read_b128 v[178:181], v146 offset:4096
	ds_read_b128 v[182:185], v146 offset:5120
	ds_read_b128 v[186:189], v146 offset:6144
	ds_read_b128 v[190:193], v146 offset:7168
	global_load_lds_dwordx4 v[206:207], off
	v_lshl_add_u64 v[206:207], v[140:141], 0, s[6:7]
	s_add_i32 m0, s17, 0xe000
	s_nop 0
	global_load_lds_dwordx4 v[206:207], off
	s_waitcnt lgkmcnt(8)
	s_barrier
	s_waitcnt lgkmcnt(0)
	s_setprio 1
	v_mfma_f32_16x16x32_bf16 v[126:129], v[142:145], v[162:165], v[126:129]
	v_mfma_f32_16x16x32_bf16 v[122:125], v[154:157], v[162:165], v[122:125]
	v_mfma_f32_16x16x32_bf16 v[110:113], v[142:145], v[170:173], v[110:113]
	v_mfma_f32_16x16x32_bf16 v[106:109], v[154:157], v[170:173], v[106:109]
	v_mfma_f32_16x16x32_bf16 v[94:97], v[142:145], v[178:181], v[94:97]
	v_mfma_f32_16x16x32_bf16 v[90:93], v[154:157], v[178:181], v[90:93]
	v_mfma_f32_16x16x32_bf16 v[78:81], v[142:145], v[186:189], v[78:81]
	v_mfma_f32_16x16x32_bf16 v[74:77], v[154:157], v[186:189], v[74:77]
	v_mfma_f32_16x16x32_bf16 v[126:129], v[150:153], v[166:169], v[126:129]
	v_mfma_f32_16x16x32_bf16 v[122:125], v[158:161], v[166:169], v[122:125]
	v_mfma_f32_16x16x32_bf16 v[110:113], v[150:153], v[174:177], v[110:113]
	v_mfma_f32_16x16x32_bf16 v[106:109], v[158:161], v[174:177], v[106:109]
	v_mfma_f32_16x16x32_bf16 v[94:97], v[150:153], v[182:185], v[94:97]
	v_mfma_f32_16x16x32_bf16 v[90:93], v[158:161], v[182:185], v[90:93]
	v_mfma_f32_16x16x32_bf16 v[78:81], v[150:153], v[190:193], v[78:81]
	v_mfma_f32_16x16x32_bf16 v[74:77], v[158:161], v[190:193], v[74:77]
	s_setprio 0
	s_barrier
	v_or_b32_e32 v194, 0x14000, v147
	s_mov_b32 m0, s26
	v_add_u32_e32 v197, 0x14400, v147
	ds_read_b128 v[206:209], v194
	ds_read_b128 v[210:213], v197
	v_add_u32_e32 v194, 0x14800, v147
	v_lshl_add_u64 v[222:223], s[54:55], 0, v[134:135]
	v_add_u32_e32 v197, 0x14c00, v147
	ds_read_b128 v[214:217], v194
	ds_read_b128 v[218:221], v197
	global_load_lds_dwordx4 v[222:223], off
	v_lshl_add_u64 v[224:225], s[54:55], 0, v[130:131]
	s_mov_b32 m0, s34
	s_nop 0
	global_load_lds_dwordx4 v[224:225], off
	s_barrier
	s_waitcnt lgkmcnt(0)
	s_setprio 1
	v_mfma_f32_16x16x32_bf16 v[118:121], v[206:209], v[162:165], v[118:121]
	v_mfma_f32_16x16x32_bf16 v[114:117], v[214:217], v[162:165], v[114:117]
	v_mfma_f32_16x16x32_bf16 v[102:105], v[206:209], v[170:173], v[102:105]
	v_mfma_f32_16x16x32_bf16 v[98:101], v[214:217], v[170:173], v[98:101]
	v_mfma_f32_16x16x32_bf16 v[86:89], v[206:209], v[178:181], v[86:89]
	v_mfma_f32_16x16x32_bf16 v[82:85], v[214:217], v[178:181], v[82:85]
	v_mfma_f32_16x16x32_bf16 v[70:73], v[206:209], v[186:189], v[70:73]
	v_mfma_f32_16x16x32_bf16 v[66:69], v[214:217], v[186:189], v[66:69]
	v_mfma_f32_16x16x32_bf16 v[118:121], v[210:213], v[166:169], v[118:121]
	v_mfma_f32_16x16x32_bf16 v[114:117], v[218:221], v[166:169], v[114:117]
	v_mfma_f32_16x16x32_bf16 v[102:105], v[210:213], v[174:177], v[102:105]
	v_mfma_f32_16x16x32_bf16 v[98:101], v[218:221], v[174:177], v[98:101]
	v_mfma_f32_16x16x32_bf16 v[86:89], v[210:213], v[182:185], v[86:89]
	v_mfma_f32_16x16x32_bf16 v[82:85], v[218:221], v[182:185], v[82:85]
	v_mfma_f32_16x16x32_bf16 v[70:73], v[210:213], v[190:193], v[70:73]
	v_mfma_f32_16x16x32_bf16 v[66:69], v[218:221], v[190:193], v[66:69]
	s_setprio 0
	s_mov_b32 m0, s17
	v_lshl_add_u64 v[226:227], s[10:11], 0, v[136:137]
	s_barrier
	ds_read_b128 v[162:165], v146 offset:16384
	ds_read_b128 v[166:169], v146 offset:17408
	ds_read_b128 v[170:173], v146 offset:18432
	ds_read_b128 v[174:177], v146 offset:19456
	ds_read_b128 v[178:181], v146 offset:20480
	ds_read_b128 v[182:185], v146 offset:21504
	ds_read_b128 v[186:189], v146 offset:22528
	ds_read_b128 v[190:193], v146 offset:23552
	global_load_lds_dwordx4 v[226:227], off
	v_lshl_add_u64 v[228:229], s[10:11], 0, v[132:133]
	s_mov_b32 m0, s35
	s_nop 0
	global_load_lds_dwordx4 v[228:229], off
	s_barrier
	s_waitcnt lgkmcnt(0)
	s_setprio 1
	v_mfma_f32_16x16x32_bf16 v[62:65], v[142:145], v[162:165], v[62:65]
	v_mfma_f32_16x16x32_bf16 v[58:61], v[154:157], v[162:165], v[58:61]
	v_mfma_f32_16x16x32_bf16 v[46:49], v[142:145], v[170:173], v[46:49]
	v_mfma_f32_16x16x32_bf16 v[42:45], v[154:157], v[170:173], v[42:45]
	v_mfma_f32_16x16x32_bf16 v[30:33], v[142:145], v[178:181], v[30:33]
	v_mfma_f32_16x16x32_bf16 v[26:29], v[154:157], v[178:181], v[26:29]
	v_mfma_f32_16x16x32_bf16 v[14:17], v[142:145], v[186:189], v[14:17]
	v_mfma_f32_16x16x32_bf16 v[10:13], v[154:157], v[186:189], v[10:13]
	v_mfma_f32_16x16x32_bf16 v[62:65], v[150:153], v[166:169], v[62:65]
	v_mfma_f32_16x16x32_bf16 v[58:61], v[158:161], v[166:169], v[58:61]
	v_mfma_f32_16x16x32_bf16 v[46:49], v[150:153], v[174:177], v[46:49]
	v_mfma_f32_16x16x32_bf16 v[42:45], v[158:161], v[174:177], v[42:45]
	v_mfma_f32_16x16x32_bf16 v[30:33], v[150:153], v[182:185], v[30:33]
	v_mfma_f32_16x16x32_bf16 v[26:29], v[158:161], v[182:185], v[26:29]
	v_mfma_f32_16x16x32_bf16 v[14:17], v[150:153], v[190:193], v[14:17]
	v_mfma_f32_16x16x32_bf16 v[10:13], v[158:161], v[190:193], v[10:13]
	s_setprio 0
	s_barrier
	s_add_u32 s6, s54, 0x20000
	s_addc_u32 s7, s55, 0
	s_mov_b32 m0, s42
	v_lshl_add_u64 v[142:143], s[6:7], 0, v[134:135]
	global_load_lds_dwordx4 v[142:143], off
	v_lshl_add_u64 v[142:143], s[6:7], 0, v[130:131]
	s_mov_b32 m0, s56
	s_nop 0
	global_load_lds_dwordx4 v[142:143], off
	s_waitcnt vmcnt(6)
	s_barrier
	s_setprio 1
	v_mfma_f32_16x16x32_bf16 v[54:57], v[206:209], v[162:165], v[54:57]
	v_mfma_f32_16x16x32_bf16 v[50:53], v[214:217], v[162:165], v[50:53]
	v_mfma_f32_16x16x32_bf16 v[38:41], v[206:209], v[170:173], v[38:41]
	v_mfma_f32_16x16x32_bf16 v[34:37], v[214:217], v[170:173], v[34:37]
	v_mfma_f32_16x16x32_bf16 v[22:25], v[206:209], v[178:181], v[22:25]
	v_mfma_f32_16x16x32_bf16 v[18:21], v[214:217], v[178:181], v[18:21]
	v_mfma_f32_16x16x32_bf16 v[6:9], v[206:209], v[186:189], v[6:9]
	v_mfma_f32_16x16x32_bf16 v[2:5], v[214:217], v[186:189], v[2:5]
	v_mfma_f32_16x16x32_bf16 v[54:57], v[210:213], v[166:169], v[54:57]
	v_mfma_f32_16x16x32_bf16 v[50:53], v[218:221], v[166:169], v[50:53]
	v_mfma_f32_16x16x32_bf16 v[38:41], v[210:213], v[174:177], v[38:41]
	v_mfma_f32_16x16x32_bf16 v[34:37], v[218:221], v[174:177], v[34:37]
	v_mfma_f32_16x16x32_bf16 v[22:25], v[210:213], v[182:185], v[22:25]
	v_mfma_f32_16x16x32_bf16 v[18:21], v[218:221], v[182:185], v[18:21]
	v_mfma_f32_16x16x32_bf16 v[6:9], v[210:213], v[190:193], v[6:9]
	v_mfma_f32_16x16x32_bf16 v[2:5], v[218:221], v[190:193], v[2:5]
	s_setprio 0
	v_or_b32_e32 v142, 0x18000, v147
	v_add_u32_e32 v150, 0x18400, v147
	v_add_u32_e32 v154, 0x18800, v147
	v_add_u32_e32 v158, 0x18c00, v147
	s_barrier
	ds_read_b128 v[142:145], v142
	ds_read_b128 v[150:153], v150
	ds_read_b128 v[154:157], v154
	ds_read_b128 v[158:161], v158
	s_add_u32 s6, s10, 0x20000
	s_addc_u32 s7, s11, 0
	s_mov_b32 m0, s57
	v_lshl_add_u64 v[206:207], s[6:7], 0, v[136:137]
	ds_read_b128 v[162:165], v146 offset:32768
	ds_read_b128 v[166:169], v146 offset:33792
	ds_read_b128 v[170:173], v146 offset:34816
	ds_read_b128 v[174:177], v146 offset:35840
	ds_read_b128 v[178:181], v146 offset:36864
	ds_read_b128 v[182:185], v146 offset:37888
	ds_read_b128 v[186:189], v146 offset:38912
	ds_read_b128 v[190:193], v146 offset:39936
	global_load_lds_dwordx4 v[206:207], off
	v_lshl_add_u64 v[206:207], s[6:7], 0, v[132:133]
	s_mov_b32 m0, s58
	s_nop 0
	global_load_lds_dwordx4 v[206:207], off
	s_waitcnt lgkmcnt(8)
	s_barrier
	s_waitcnt lgkmcnt(0)
	s_setprio 1
	v_mfma_f32_16x16x32_bf16 v[126:129], v[142:145], v[162:165], v[126:129]
	v_mfma_f32_16x16x32_bf16 v[122:125], v[154:157], v[162:165], v[122:125]
	v_mfma_f32_16x16x32_bf16 v[110:113], v[142:145], v[170:173], v[110:113]
	v_mfma_f32_16x16x32_bf16 v[106:109], v[154:157], v[170:173], v[106:109]
	v_mfma_f32_16x16x32_bf16 v[94:97], v[142:145], v[178:181], v[94:97]
	v_mfma_f32_16x16x32_bf16 v[90:93], v[154:157], v[178:181], v[90:93]
	v_mfma_f32_16x16x32_bf16 v[78:81], v[142:145], v[186:189], v[78:81]
	v_mfma_f32_16x16x32_bf16 v[74:77], v[154:157], v[186:189], v[74:77]
	v_mfma_f32_16x16x32_bf16 v[126:129], v[150:153], v[166:169], v[126:129]
	v_mfma_f32_16x16x32_bf16 v[122:125], v[158:161], v[166:169], v[122:125]
	v_mfma_f32_16x16x32_bf16 v[110:113], v[150:153], v[174:177], v[110:113]
	v_mfma_f32_16x16x32_bf16 v[106:109], v[158:161], v[174:177], v[106:109]
	v_mfma_f32_16x16x32_bf16 v[94:97], v[150:153], v[182:185], v[94:97]
	v_mfma_f32_16x16x32_bf16 v[90:93], v[158:161], v[182:185], v[90:93]
	v_mfma_f32_16x16x32_bf16 v[78:81], v[150:153], v[190:193], v[78:81]
	v_mfma_f32_16x16x32_bf16 v[74:77], v[158:161], v[190:193], v[74:77]
	s_setprio 0
	s_barrier
	v_or_b32_e32 v194, 0x1c000, v147
	s_mov_b32 m0, s59
	v_add_u32_e32 v197, 0x1c400, v147
	ds_read_b128 v[206:209], v194
	ds_read_b128 v[210:213], v197
	v_add_u32_e32 v194, 0x1c800, v147
	v_lshl_add_u64 v[222:223], v[222:223], 0, s[76:77]
	v_add_u32_e32 v197, 0x1cc00, v147
	ds_read_b128 v[214:217], v194
	ds_read_b128 v[218:221], v197
	global_load_lds_dwordx4 v[222:223], off
	v_lshl_add_u64 v[222:223], v[224:225], 0, s[76:77]
	s_mov_b32 m0, s60
	s_nop 0
	global_load_lds_dwordx4 v[222:223], off
	s_barrier
	s_waitcnt lgkmcnt(0)
	s_setprio 1
	v_mfma_f32_16x16x32_bf16 v[118:121], v[206:209], v[162:165], v[118:121]
	v_mfma_f32_16x16x32_bf16 v[114:117], v[214:217], v[162:165], v[114:117]
	v_mfma_f32_16x16x32_bf16 v[102:105], v[206:209], v[170:173], v[102:105]
	v_mfma_f32_16x16x32_bf16 v[98:101], v[214:217], v[170:173], v[98:101]
	v_mfma_f32_16x16x32_bf16 v[86:89], v[206:209], v[178:181], v[86:89]
	v_mfma_f32_16x16x32_bf16 v[82:85], v[214:217], v[178:181], v[82:85]
	v_mfma_f32_16x16x32_bf16 v[70:73], v[206:209], v[186:189], v[70:73]
	v_mfma_f32_16x16x32_bf16 v[66:69], v[214:217], v[186:189], v[66:69]
	v_mfma_f32_16x16x32_bf16 v[118:121], v[210:213], v[166:169], v[118:121]
	v_mfma_f32_16x16x32_bf16 v[114:117], v[218:221], v[166:169], v[114:117]
	v_mfma_f32_16x16x32_bf16 v[102:105], v[210:213], v[174:177], v[102:105]
	v_mfma_f32_16x16x32_bf16 v[98:101], v[218:221], v[174:177], v[98:101]
	v_mfma_f32_16x16x32_bf16 v[86:89], v[210:213], v[182:185], v[86:89]
	v_mfma_f32_16x16x32_bf16 v[82:85], v[218:221], v[182:185], v[82:85]
	v_mfma_f32_16x16x32_bf16 v[70:73], v[210:213], v[190:193], v[70:73]
	v_mfma_f32_16x16x32_bf16 v[66:69], v[218:221], v[190:193], v[66:69]
	s_setprio 0
	s_mov_b32 m0, s61
	v_lshl_add_u64 v[222:223], v[226:227], 0, s[76:77]
	s_barrier
	ds_read_b128 v[162:165], v146 offset:49152
	ds_read_b128 v[166:169], v146 offset:50176
	ds_read_b128 v[170:173], v146 offset:51200
	ds_read_b128 v[174:177], v146 offset:52224
	ds_read_b128 v[178:181], v146 offset:53248
	ds_read_b128 v[182:185], v146 offset:54272
	ds_read_b128 v[186:189], v146 offset:55296
	ds_read_b128 v[190:193], v146 offset:56320
	global_load_lds_dwordx4 v[222:223], off
	v_lshl_add_u64 v[222:223], v[228:229], 0, s[76:77]
	s_mov_b32 m0, s62
	s_nop 0
	global_load_lds_dwordx4 v[222:223], off
	s_barrier
	s_waitcnt lgkmcnt(0)
	s_setprio 1
	v_mfma_f32_16x16x32_bf16 v[62:65], v[142:145], v[162:165], v[62:65]
	v_mfma_f32_16x16x32_bf16 v[58:61], v[154:157], v[162:165], v[58:61]
	v_mfma_f32_16x16x32_bf16 v[46:49], v[142:145], v[170:173], v[46:49]
	v_mfma_f32_16x16x32_bf16 v[42:45], v[154:157], v[170:173], v[42:45]
	v_mfma_f32_16x16x32_bf16 v[30:33], v[142:145], v[178:181], v[30:33]
	v_mfma_f32_16x16x32_bf16 v[26:29], v[154:157], v[178:181], v[26:29]
	v_mfma_f32_16x16x32_bf16 v[14:17], v[142:145], v[186:189], v[14:17]
	v_mfma_f32_16x16x32_bf16 v[10:13], v[154:157], v[186:189], v[10:13]
	v_mfma_f32_16x16x32_bf16 v[62:65], v[150:153], v[166:169], v[62:65]
	v_mfma_f32_16x16x32_bf16 v[58:61], v[158:161], v[166:169], v[58:61]
	v_mfma_f32_16x16x32_bf16 v[46:49], v[150:153], v[174:177], v[46:49]
	v_mfma_f32_16x16x32_bf16 v[42:45], v[158:161], v[174:177], v[42:45]
	v_mfma_f32_16x16x32_bf16 v[30:33], v[150:153], v[182:185], v[30:33]
	v_mfma_f32_16x16x32_bf16 v[26:29], v[158:161], v[182:185], v[26:29]
	v_mfma_f32_16x16x32_bf16 v[14:17], v[150:153], v[190:193], v[14:17]
	v_mfma_f32_16x16x32_bf16 v[10:13], v[158:161], v[190:193], v[10:13]
	s_setprio 0
	s_barrier
	s_add_u32 s6, s54, 0x20080
	s_addc_u32 s7, s55, 0
	s_mov_b32 m0, s63
	v_lshl_add_u64 v[142:143], s[6:7], 0, v[134:135]
	global_load_lds_dwordx4 v[142:143], off
	v_lshl_add_u64 v[142:143], s[6:7], 0, v[130:131]
	s_mov_b32 m0, s67
	s_nop 0
	global_load_lds_dwordx4 v[142:143], off
	s_waitcnt vmcnt(6)
	s_barrier
	s_setprio 1
	v_mfma_f32_16x16x32_bf16 v[54:57], v[206:209], v[162:165], v[54:57]
	v_mfma_f32_16x16x32_bf16 v[50:53], v[214:217], v[162:165], v[50:53]
	v_mfma_f32_16x16x32_bf16 v[38:41], v[206:209], v[170:173], v[38:41]
	v_mfma_f32_16x16x32_bf16 v[34:37], v[214:217], v[170:173], v[34:37]
	v_mfma_f32_16x16x32_bf16 v[22:25], v[206:209], v[178:181], v[22:25]
	v_mfma_f32_16x16x32_bf16 v[18:21], v[214:217], v[178:181], v[18:21]
	v_mfma_f32_16x16x32_bf16 v[6:9], v[206:209], v[186:189], v[6:9]
	v_mfma_f32_16x16x32_bf16 v[2:5], v[214:217], v[186:189], v[2:5]
	v_mfma_f32_16x16x32_bf16 v[54:57], v[210:213], v[166:169], v[54:57]
	v_mfma_f32_16x16x32_bf16 v[50:53], v[218:221], v[166:169], v[50:53]
	v_mfma_f32_16x16x32_bf16 v[38:41], v[210:213], v[174:177], v[38:41]
	v_mfma_f32_16x16x32_bf16 v[34:37], v[218:221], v[174:177], v[34:37]
	v_mfma_f32_16x16x32_bf16 v[22:25], v[210:213], v[182:185], v[22:25]
	v_mfma_f32_16x16x32_bf16 v[18:21], v[218:221], v[182:185], v[18:21]
	v_mfma_f32_16x16x32_bf16 v[6:9], v[210:213], v[190:193], v[6:9]
	v_mfma_f32_16x16x32_bf16 v[2:5], v[218:221], v[190:193], v[2:5]
	s_setprio 0
	s_add_i32 s79, s79, 2
	s_cmp_gt_u32 s79, 5
	s_mov_b64 s[6:7], s[8:9]
	s_barrier
	s_cbranch_scc0 .LBB0_266
	s_lshl_b32 s5, s28, 6
	s_and_b32 s5, s5, 0xffffff00
	v_add_u32_e32 v144, s5, v148
	s_lshl_b32 s5, s28, 8
	s_and_b32 s5, s5, 0x300
	v_or_b32_e32 v145, s5, v149
	v_mov_b64_e32 v[142:143], s[50:51]
	v_mad_i64_i32 v[150:151], s[6:7], v144, s37, v[142:143]
	v_lshlrev_b32_e32 v194, 1, v145
	v_lshl_add_u64 v[154:155], v[150:151], 0, v[194:195]
	v_add_co_u32_e32 v150, vcc, 0x1000, v154
	v_or_b32_e32 v184, 16, v144
	s_nop 0
	v_addc_co_u32_e32 v151, vcc, 0, v155, vcc
	global_load_dwordx4 v[150:153], v[150:151], off offset:2048
	v_lshl_add_u64 v[154:155], v[154:155], 0, s[84:85]
	global_load_dwordx4 v[154:157], v[154:155], off offset:256
	v_pk_mul_f32 v[182:183], v[114:115], s[36:37] op_sel_hi:[1,0]
	v_mad_i64_i32 v[114:115], s[6:7], v184, s37, v[142:143]
	v_lshl_add_u64 v[114:115], v[114:115], 0, v[194:195]
	v_pk_mul_f32 v[180:181], v[116:117], s[36:37] op_sel_hi:[1,0]
	v_add_co_u32_e32 v116, vcc, 0x1000, v114
	v_pk_mul_f32 v[170:171], v[126:127], s[36:37] op_sel_hi:[1,0]
	s_nop 0
	v_addc_co_u32_e32 v117, vcc, 0, v115, vcc
	v_pk_mul_f32 v[172:173], v[124:125], s[36:37] op_sel_hi:[1,0]
	global_load_dwordx4 v[124:127], v[116:117], off offset:2048
	v_lshl_add_u64 v[114:115], v[114:115], 0, s[84:85]
	global_load_dwordx4 v[158:161], v[114:115], off offset:256
	v_or_b32_e32 v186, 32, v144
	v_mad_i64_i32 v[116:117], s[6:7], v186, s37, v[142:143]
	v_lshl_add_u64 v[116:117], v[116:117], 0, v[194:195]
	v_lshl_add_u64 v[166:167], v[116:117], 0, s[84:85]
	v_add_co_u32_e32 v116, vcc, 0x1000, v116
	v_pk_mul_f32 v[174:175], v[122:123], s[36:37] op_sel_hi:[1,0]
	s_nop 0
	v_addc_co_u32_e32 v117, vcc, 0, v117, vcc
	global_load_dwordx4 v[162:165], v[116:117], off offset:2048
	s_nop 0
	global_load_dwordx4 v[166:169], v[166:167], off offset:256
	v_or_b32_e32 v122, 48, v144
	v_pk_mul_f32 v[178:179], v[118:119], s[36:37] op_sel_hi:[1,0]
	v_mad_i64_i32 v[118:119], s[6:7], v122, s37, v[142:143]
	v_ashrrev_i32_e32 v145, 31, v144
	v_lshl_add_u64 v[118:119], v[118:119], 0, v[194:195]
	v_pk_mul_f32 v[176:177], v[120:121], s[36:37] op_sel_hi:[1,0]
	v_lshlrev_b64 v[120:121], 11, v[144:145]
	v_add_co_u32_e32 v114, vcc, 0x1000, v118
	v_lshl_add_u64 v[120:121], s[74:75], 0, v[120:121]
	s_nop 0
	v_addc_co_u32_e32 v115, vcc, 0, v119, vcc
	v_lshl_add_u64 v[188:189], v[118:119], 0, s[84:85]
	v_lshl_add_u64 v[190:191], v[120:121], 0, v[194:195]
	global_load_dwordx4 v[118:121], v[114:115], off offset:2048
	s_nop 0
	global_load_dwordx4 v[114:117], v[188:189], off offset:256
	v_pk_mul_f32 v[128:129], v[128:129], s[36:37] op_sel_hi:[1,0]
	v_pk_mul_f32 v[110:111], v[110:111], s[36:37] op_sel_hi:[1,0]
	v_pk_mul_f32 v[112:113], v[112:113], s[36:37] op_sel_hi:[1,0]
	v_ashrrev_i32_e32 v185, 31, v184
	v_pk_mul_f32 v[102:103], v[102:103], s[36:37] op_sel_hi:[1,0]
	v_pk_mul_f32 v[104:105], v[104:105], s[36:37] op_sel_hi:[1,0]
	v_pk_mul_f32 v[94:95], v[94:95], s[36:37] op_sel_hi:[1,0]
	v_pk_mul_f32 v[96:97], v[96:97], s[36:37] op_sel_hi:[1,0]
	v_ashrrev_i32_e32 v187, 31, v186
	v_pk_mul_f32 v[86:87], v[86:87], s[36:37] op_sel_hi:[1,0]
	v_pk_mul_f32 v[88:89], v[88:89], s[36:37] op_sel_hi:[1,0]
	v_pk_mul_f32 v[78:79], v[78:79], s[36:37] op_sel_hi:[1,0]
	v_pk_mul_f32 v[80:81], v[80:81], s[36:37] op_sel_hi:[1,0]
	v_ashrrev_i32_e32 v123, 31, v122
	v_pk_mul_f32 v[70:71], v[70:71], s[36:37] op_sel_hi:[1,0]
	v_pk_mul_f32 v[72:73], v[72:73], s[36:37] op_sel_hi:[1,0]
	s_waitcnt vmcnt(0)
	v_lshlrev_b32_e32 v145, 16, v150
	v_and_b32_e32 v150, 0xffff0000, v150
	v_lshlrev_b32_e32 v188, 16, v151
	v_and_b32_e32 v151, 0xffff0000, v151
	v_mul_f32_e32 v150, v171, v150
	v_mul_f32_e32 v128, v128, v188
	v_mul_f32_e32 v129, v129, v151
	v_lshlrev_b32_e32 v189, 16, v152
	v_and_b32_e32 v152, 0xffff0000, v152
	v_lshlrev_b32_e32 v192, 16, v153
	v_and_b32_e32 v153, 0xffff0000, v153
	v_mul_f32_e32 v145, v170, v145
	v_cvt_pk_bf16_f32 v150, v145, v150
	v_cvt_pk_bf16_f32 v151, v128, v129
	v_lshlrev_b32_e32 v128, 16, v154
	v_and_b32_e32 v129, 0xffff0000, v154
	v_mul_f32_e32 v152, v175, v152
	v_mul_f32_e32 v153, v173, v153
	v_mul_f32_e32 v128, v178, v128
	v_mul_f32_e32 v129, v179, v129
	v_mul_f32_e32 v170, v174, v189
	v_mul_f32_e32 v171, v172, v192
	v_cvt_pk_bf16_f32 v152, v170, v152
	v_cvt_pk_bf16_f32 v153, v171, v153
	global_store_dwordx4 v[190:191], v[150:153], off
	s_nop 1
	v_cvt_pk_bf16_f32 v150, v128, v129
	v_lshlrev_b32_e32 v128, 16, v155
	v_and_b32_e32 v129, 0xffff0000, v155
	v_mul_f32_e32 v128, v176, v128
	v_mul_f32_e32 v129, v177, v129
	v_cvt_pk_bf16_f32 v151, v128, v129
	v_lshlrev_b32_e32 v128, 16, v156
	v_and_b32_e32 v129, 0xffff0000, v156
	v_mul_f32_e32 v128, v182, v128
	v_mul_f32_e32 v129, v183, v129
	v_cvt_pk_bf16_f32 v152, v128, v129
	v_lshlrev_b32_e32 v128, 16, v157
	v_and_b32_e32 v129, 0xffff0000, v157
	v_mul_f32_e32 v128, v180, v128
	v_mul_f32_e32 v129, v181, v129
	v_cvt_pk_bf16_f32 v153, v128, v129
	global_store_dwordx4 v[190:191], v[150:153], off offset:256
	v_lshlrev_b64 v[128:129], 11, v[184:185]
	s_nop 0
	v_pk_mul_f32 v[150:151], v[108:109], s[36:37] op_sel_hi:[1,0]
	v_pk_mul_f32 v[108:109], v[106:107], s[36:37] op_sel_hi:[1,0]
	v_lshlrev_b32_e32 v106, 16, v124
	v_and_b32_e32 v107, 0xffff0000, v124
	v_mul_f32_e32 v106, v110, v106
	v_mul_f32_e32 v107, v111, v107
	v_cvt_pk_bf16_f32 v106, v106, v107
	v_lshlrev_b32_e32 v107, 16, v125
	v_and_b32_e32 v110, 0xffff0000, v125
	v_mul_f32_e32 v107, v112, v107
	v_mul_f32_e32 v110, v113, v110
	v_cvt_pk_bf16_f32 v107, v107, v110
	v_lshlrev_b32_e32 v110, 16, v126
	v_mul_f32_e32 v108, v108, v110
	v_and_b32_e32 v110, 0xffff0000, v126
	v_mul_f32_e32 v109, v109, v110
	v_cvt_pk_bf16_f32 v108, v108, v109
	v_lshlrev_b32_e32 v109, 16, v127
	v_and_b32_e32 v110, 0xffff0000, v127
	v_mul_f32_e32 v109, v150, v109
	v_mul_f32_e32 v110, v151, v110
	v_cvt_pk_bf16_f32 v109, v109, v110
	v_lshl_add_u64 v[110:111], s[74:75], 0, v[128:129]
	v_lshl_add_u64 v[110:111], v[110:111], 0, v[194:195]
	global_store_dwordx4 v[110:111], v[106:109], off
	s_nop 1
	v_pk_mul_f32 v[106:107], v[100:101], s[36:37] op_sel_hi:[1,0]
	v_pk_mul_f32 v[100:101], v[98:99], s[36:37] op_sel_hi:[1,0]
	v_lshlrev_b32_e32 v98, 16, v158
	v_and_b32_e32 v99, 0xffff0000, v158
	v_mul_f32_e32 v98, v102, v98
	v_mul_f32_e32 v99, v103, v99
	v_cvt_pk_bf16_f32 v98, v98, v99
	v_lshlrev_b32_e32 v99, 16, v159
	v_and_b32_e32 v102, 0xffff0000, v159
	v_mul_f32_e32 v99, v104, v99
	v_mul_f32_e32 v102, v105, v102
	v_cvt_pk_bf16_f32 v99, v99, v102
	v_lshlrev_b32_e32 v102, 16, v160
	v_mul_f32_e32 v100, v100, v102
	v_and_b32_e32 v102, 0xffff0000, v160
	v_mul_f32_e32 v101, v101, v102
	v_cvt_pk_bf16_f32 v100, v100, v101
	v_lshlrev_b32_e32 v101, 16, v161
	v_mul_f32_e32 v101, v106, v101
	v_and_b32_e32 v102, 0xffff0000, v161
	v_mul_f32_e32 v102, v107, v102
	v_cvt_pk_bf16_f32 v101, v101, v102
	global_store_dwordx4 v[110:111], v[98:101], off offset:256
	s_nop 1
	v_pk_mul_f32 v[100:101], v[92:93], s[36:37] op_sel_hi:[1,0]
	v_pk_mul_f32 v[92:93], v[90:91], s[36:37] op_sel_hi:[1,0]
	v_lshlrev_b32_e32 v90, 16, v162
	v_and_b32_e32 v91, 0xffff0000, v162
	v_mul_f32_e32 v90, v94, v90
	v_mul_f32_e32 v91, v95, v91
	v_cvt_pk_bf16_f32 v90, v90, v91
	v_lshlrev_b32_e32 v91, 16, v163
	v_and_b32_e32 v94, 0xffff0000, v163
	v_mul_f32_e32 v91, v96, v91
	v_mul_f32_e32 v94, v97, v94
	v_cvt_pk_bf16_f32 v91, v91, v94
	v_lshlrev_b32_e32 v94, 16, v164
	v_mul_f32_e32 v92, v92, v94
	v_and_b32_e32 v94, 0xffff0000, v164
	v_mul_f32_e32 v93, v93, v94
	v_cvt_pk_bf16_f32 v92, v92, v93
	v_lshlrev_b32_e32 v93, 16, v165
	v_and_b32_e32 v94, 0xffff0000, v165
	v_lshlrev_b64 v[98:99], 11, v[186:187]
	v_mul_f32_e32 v93, v100, v93
	v_mul_f32_e32 v94, v101, v94
	v_cvt_pk_bf16_f32 v93, v93, v94
	v_lshl_add_u64 v[94:95], s[74:75], 0, v[98:99]
	v_lshl_add_u64 v[94:95], v[94:95], 0, v[194:195]
	global_store_dwordx4 v[94:95], v[90:93], off
	s_nop 1
	v_pk_mul_f32 v[90:91], v[84:85], s[36:37] op_sel_hi:[1,0]
	v_pk_mul_f32 v[84:85], v[82:83], s[36:37] op_sel_hi:[1,0]
	v_lshlrev_b32_e32 v82, 16, v166
	v_and_b32_e32 v83, 0xffff0000, v166
	v_mul_f32_e32 v82, v86, v82
	v_mul_f32_e32 v83, v87, v83
	v_cvt_pk_bf16_f32 v82, v82, v83
	v_lshlrev_b32_e32 v83, 16, v167
	v_and_b32_e32 v86, 0xffff0000, v167
	v_mul_f32_e32 v83, v88, v83
	v_mul_f32_e32 v86, v89, v86
	v_cvt_pk_bf16_f32 v83, v83, v86
	v_lshlrev_b32_e32 v86, 16, v168
	v_mul_f32_e32 v84, v84, v86
	v_and_b32_e32 v86, 0xffff0000, v168
	v_mul_f32_e32 v85, v85, v86
	v_cvt_pk_bf16_f32 v84, v84, v85
	v_lshlrev_b32_e32 v85, 16, v169
	v_mul_f32_e32 v85, v90, v85
	v_and_b32_e32 v86, 0xffff0000, v169
	v_mul_f32_e32 v86, v91, v86
	v_cvt_pk_bf16_f32 v85, v85, v86
	global_store_dwordx4 v[94:95], v[82:85], off offset:256
	s_nop 1
	v_pk_mul_f32 v[84:85], v[76:77], s[36:37] op_sel_hi:[1,0]
	v_pk_mul_f32 v[76:77], v[74:75], s[36:37] op_sel_hi:[1,0]
	v_lshlrev_b32_e32 v74, 16, v118
	v_and_b32_e32 v75, 0xffff0000, v118
	v_mul_f32_e32 v74, v78, v74
	v_mul_f32_e32 v75, v79, v75
	v_cvt_pk_bf16_f32 v74, v74, v75
	v_lshlrev_b32_e32 v75, 16, v119
	v_and_b32_e32 v78, 0xffff0000, v119
	v_mul_f32_e32 v75, v80, v75
	v_mul_f32_e32 v78, v81, v78
	v_cvt_pk_bf16_f32 v75, v75, v78
	v_lshlrev_b32_e32 v78, 16, v120
	v_mul_f32_e32 v76, v76, v78
	v_and_b32_e32 v78, 0xffff0000, v120
	v_mul_f32_e32 v77, v77, v78
	v_cvt_pk_bf16_f32 v76, v76, v77
	v_lshlrev_b32_e32 v77, 16, v121
	v_and_b32_e32 v78, 0xffff0000, v121
	v_lshlrev_b64 v[82:83], 11, v[122:123]
	v_mul_f32_e32 v77, v84, v77
	v_mul_f32_e32 v78, v85, v78
	v_cvt_pk_bf16_f32 v77, v77, v78
	v_lshl_add_u64 v[78:79], s[74:75], 0, v[82:83]
	v_lshl_add_u64 v[78:79], v[78:79], 0, v[194:195]
	global_store_dwordx4 v[78:79], v[74:77], off
	s_nop 1
	v_pk_mul_f32 v[74:75], v[68:69], s[36:37] op_sel_hi:[1,0]
	v_pk_mul_f32 v[68:69], v[66:67], s[36:37] op_sel_hi:[1,0]
	v_lshlrev_b32_e32 v66, 16, v114
	v_and_b32_e32 v67, 0xffff0000, v114
	v_mul_f32_e32 v66, v70, v66
	v_mul_f32_e32 v67, v71, v67
	v_cvt_pk_bf16_f32 v66, v66, v67
	v_lshlrev_b32_e32 v67, 16, v115
	v_and_b32_e32 v70, 0xffff0000, v115
	v_mul_f32_e32 v67, v72, v67
	v_mul_f32_e32 v70, v73, v70
	v_cvt_pk_bf16_f32 v67, v67, v70
	v_lshlrev_b32_e32 v70, 16, v116
	v_mul_f32_e32 v68, v68, v70
	v_and_b32_e32 v70, 0xffff0000, v116
	v_mul_f32_e32 v69, v69, v70
	v_cvt_pk_bf16_f32 v68, v68, v69
	v_lshlrev_b32_e32 v69, 16, v117
	v_mul_f32_e32 v69, v74, v69
	v_and_b32_e32 v70, 0xffff0000, v117
	v_mul_f32_e32 v70, v75, v70
	v_cvt_pk_bf16_f32 v69, v69, v70
	global_store_dwordx4 v[78:79], v[66:69], off offset:256
	v_add_u32_e32 v78, 0x80, v144
	s_nop 0
	v_mad_i64_i32 v[66:67], s[6:7], v78, s37, v[142:143]
	v_lshl_add_u64 v[66:67], v[66:67], 0, v[194:195]
	v_add_co_u32_e32 v68, vcc, s16, v66
	v_add_u32_e32 v86, 0x90, v144
	s_nop 0
	v_addc_co_u32_e32 v69, vcc, 0, v67, vcc
	global_load_dwordx4 v[70:73], v[68:69], off offset:2048
	v_lshl_add_u64 v[66:67], v[66:67], 0, s[84:85]
	global_load_dwordx4 v[74:77], v[66:67], off offset:256
	v_pk_mul_f32 v[96:97], v[56:57], s[36:37] op_sel_hi:[1,0]
	v_mad_i64_i32 v[56:57], s[6:7], v86, s37, v[142:143]
	v_lshl_add_u64 v[56:57], v[56:57], 0, v[194:195]
	v_pk_mul_f32 v[94:95], v[58:59], s[36:37] op_sel_hi:[1,0]
	v_add_co_u32_e32 v58, vcc, s16, v56
	v_pk_mul_f32 v[92:93], v[60:61], s[36:37] op_sel_hi:[1,0]
	s_nop 0
	v_addc_co_u32_e32 v59, vcc, 0, v57, vcc
	global_load_dwordx4 v[58:61], v[58:59], off offset:2048
	v_add_u32_e32 v68, 0xa0, v144
	v_pk_mul_f32 v[102:103], v[50:51], s[36:37] op_sel_hi:[1,0]
	v_mad_i64_i32 v[50:51], s[6:7], v68, s37, v[142:143]
	v_add_u32_e32 v66, 0xb0, v144
	v_lshl_add_u64 v[50:51], v[50:51], 0, v[194:195]
	v_pk_mul_f32 v[100:101], v[52:53], s[36:37] op_sel_hi:[1,0]
	v_mad_i64_i32 v[52:53], s[6:7], v66, s37, v[142:143]
	v_lshl_add_u64 v[82:83], v[50:51], 0, s[84:85]
	v_add_co_u32_e32 v50, vcc, s16, v50
	v_lshl_add_u64 v[52:53], v[52:53], 0, v[194:195]
	s_nop 0
	v_addc_co_u32_e32 v51, vcc, 0, v51, vcc
	v_ashrrev_i32_e32 v79, 31, v78
	v_lshl_add_u64 v[104:105], v[52:53], 0, s[84:85]
	v_add_co_u32_e32 v52, vcc, s16, v52
	v_pk_mul_f32 v[98:99], v[54:55], s[36:37] op_sel_hi:[1,0]
	v_lshlrev_b64 v[54:55], 11, v[78:79]
	v_lshl_add_u64 v[56:57], v[56:57], 0, s[84:85]
	v_addc_co_u32_e32 v53, vcc, 0, v53, vcc
	v_pk_mul_f32 v[88:89], v[64:65], s[36:37] op_sel_hi:[1,0]
	v_pk_mul_f32 v[90:91], v[62:63], s[36:37] op_sel_hi:[1,0]
	v_lshl_add_u64 v[106:107], s[74:75], 0, v[54:55]
	global_load_dwordx4 v[62:65], v[56:57], off offset:256
	global_load_dwordx4 v[78:81], v[50:51], off offset:2048
	s_nop 0
	global_load_dwordx4 v[82:85], v[82:83], off offset:256
	s_nop 0
	global_load_dwordx4 v[54:57], v[52:53], off offset:2048
	s_nop 0
	global_load_dwordx4 v[50:53], v[104:105], off offset:256
	v_lshl_add_u64 v[104:105], v[106:107], 0, v[194:195]
	v_pk_mul_f32 v[46:47], v[46:47], s[36:37] op_sel_hi:[1,0]
	v_pk_mul_f32 v[48:49], v[48:49], s[36:37] op_sel_hi:[1,0]
	v_ashrrev_i32_e32 v87, 31, v86
	v_pk_mul_f32 v[38:39], v[38:39], s[36:37] op_sel_hi:[1,0]
	v_pk_mul_f32 v[40:41], v[40:41], s[36:37] op_sel_hi:[1,0]
	v_pk_mul_f32 v[30:31], v[30:31], s[36:37] op_sel_hi:[1,0]
	v_pk_mul_f32 v[32:33], v[32:33], s[36:37] op_sel_hi:[1,0]
	v_ashrrev_i32_e32 v69, 31, v68
	v_pk_mul_f32 v[22:23], v[22:23], s[36:37] op_sel_hi:[1,0]
	v_pk_mul_f32 v[24:25], v[24:25], s[36:37] op_sel_hi:[1,0]
	v_pk_mul_f32 v[14:15], v[14:15], s[36:37] op_sel_hi:[1,0]
	v_pk_mul_f32 v[16:17], v[16:17], s[36:37] op_sel_hi:[1,0]
	v_ashrrev_i32_e32 v67, 31, v66
	v_pk_mul_f32 v[6:7], v[6:7], s[36:37] op_sel_hi:[1,0]
	v_pk_mul_f32 v[8:9], v[8:9], s[36:37] op_sel_hi:[1,0]
	s_waitcnt vmcnt(0)
	v_lshlrev_b32_e32 v106, 16, v70
	v_and_b32_e32 v70, 0xffff0000, v70
	v_lshlrev_b32_e32 v107, 16, v71
	v_and_b32_e32 v71, 0xffff0000, v71
	v_lshlrev_b32_e32 v108, 16, v72
	v_and_b32_e32 v72, 0xffff0000, v72
	v_lshlrev_b32_e32 v109, 16, v73
	v_and_b32_e32 v73, 0xffff0000, v73
	v_mul_f32_e32 v70, v91, v70
	v_mul_f32_e32 v71, v89, v71
	v_mul_f32_e32 v72, v95, v72
	v_mul_f32_e32 v73, v93, v73
	v_mul_f32_e32 v90, v90, v106
	v_mul_f32_e32 v88, v88, v107
	v_mul_f32_e32 v89, v94, v108
	v_mul_f32_e32 v91, v92, v109
	v_cvt_pk_bf16_f32 v70, v90, v70
	v_cvt_pk_bf16_f32 v71, v88, v71
	v_cvt_pk_bf16_f32 v72, v89, v72
	v_cvt_pk_bf16_f32 v73, v91, v73
	v_lshlrev_b32_e32 v111, 16, v75
	v_and_b32_e32 v75, 0xffff0000, v75
	global_store_dwordx4 v[104:105], v[70:73], off
	v_lshlrev_b32_e32 v110, 16, v74
	v_and_b32_e32 v74, 0xffff0000, v74
	v_lshlrev_b32_e32 v72, 16, v76
	v_and_b32_e32 v73, 0xffff0000, v76
	v_mul_f32_e32 v71, v97, v75
	v_mul_f32_e32 v72, v102, v72
	v_mul_f32_e32 v73, v103, v73
	v_mul_f32_e32 v92, v98, v110
	v_mul_f32_e32 v74, v99, v74
	v_mul_f32_e32 v93, v96, v111
	v_cvt_pk_bf16_f32 v70, v92, v74
	v_cvt_pk_bf16_f32 v71, v93, v71
	v_cvt_pk_bf16_f32 v72, v72, v73
	v_lshlrev_b32_e32 v73, 16, v77
	v_mul_f32_e32 v73, v100, v73
	v_and_b32_e32 v74, 0xffff0000, v77
	v_mul_f32_e32 v74, v101, v74
	v_cvt_pk_bf16_f32 v73, v73, v74
	global_store_dwordx4 v[104:105], v[70:73], off offset:256
	s_nop 1
	v_pk_mul_f32 v[72:73], v[44:45], s[36:37] op_sel_hi:[1,0]
	v_pk_mul_f32 v[44:45], v[42:43], s[36:37] op_sel_hi:[1,0]
	v_lshlrev_b32_e32 v42, 16, v58
	v_and_b32_e32 v43, 0xffff0000, v58
	v_mul_f32_e32 v42, v46, v42
	v_mul_f32_e32 v43, v47, v43
	v_cvt_pk_bf16_f32 v42, v42, v43
	v_lshlrev_b32_e32 v43, 16, v59
	v_and_b32_e32 v46, 0xffff0000, v59
	v_mul_f32_e32 v43, v48, v43
	v_mul_f32_e32 v46, v49, v46
	v_cvt_pk_bf16_f32 v43, v43, v46
	v_lshlrev_b32_e32 v46, 16, v60
	v_mul_f32_e32 v44, v44, v46
	v_and_b32_e32 v46, 0xffff0000, v60
	v_mul_f32_e32 v45, v45, v46
	v_cvt_pk_bf16_f32 v44, v44, v45
	v_lshlrev_b32_e32 v45, 16, v61
	v_and_b32_e32 v46, 0xffff0000, v61
	v_lshlrev_b64 v[70:71], 11, v[86:87]
	v_mul_f32_e32 v45, v72, v45
	v_mul_f32_e32 v46, v73, v46
	v_cvt_pk_bf16_f32 v45, v45, v46
	v_lshl_add_u64 v[46:47], s[74:75], 0, v[70:71]
	v_lshl_add_u64 v[46:47], v[46:47], 0, v[194:195]
	global_store_dwordx4 v[46:47], v[42:45], off
	s_nop 1
	v_pk_mul_f32 v[42:43], v[36:37], s[36:37] op_sel_hi:[1,0]
	v_pk_mul_f32 v[36:37], v[34:35], s[36:37] op_sel_hi:[1,0]
	v_lshlrev_b32_e32 v34, 16, v62
	v_and_b32_e32 v35, 0xffff0000, v62
	v_mul_f32_e32 v34, v38, v34
	v_mul_f32_e32 v35, v39, v35
	v_cvt_pk_bf16_f32 v34, v34, v35
	v_lshlrev_b32_e32 v35, 16, v63
	v_and_b32_e32 v38, 0xffff0000, v63
	v_mul_f32_e32 v35, v40, v35
	v_mul_f32_e32 v38, v41, v38
	v_cvt_pk_bf16_f32 v35, v35, v38
	v_lshlrev_b32_e32 v38, 16, v64
	v_mul_f32_e32 v36, v36, v38
	v_and_b32_e32 v38, 0xffff0000, v64
	v_mul_f32_e32 v37, v37, v38
	v_cvt_pk_bf16_f32 v36, v36, v37
	v_lshlrev_b32_e32 v37, 16, v65
	v_mul_f32_e32 v37, v42, v37
	v_and_b32_e32 v38, 0xffff0000, v65
	v_mul_f32_e32 v38, v43, v38
	v_cvt_pk_bf16_f32 v37, v37, v38
	global_store_dwordx4 v[46:47], v[34:37], off offset:256
	s_nop 1
	v_pk_mul_f32 v[36:37], v[28:29], s[36:37] op_sel_hi:[1,0]
	v_pk_mul_f32 v[28:29], v[26:27], s[36:37] op_sel_hi:[1,0]
	v_lshlrev_b32_e32 v26, 16, v78
	v_and_b32_e32 v27, 0xffff0000, v78
	v_mul_f32_e32 v26, v30, v26
	v_mul_f32_e32 v27, v31, v27
	v_cvt_pk_bf16_f32 v26, v26, v27
	v_lshlrev_b32_e32 v27, 16, v79
	v_and_b32_e32 v30, 0xffff0000, v79
	v_mul_f32_e32 v27, v32, v27
	v_mul_f32_e32 v30, v33, v30
	v_cvt_pk_bf16_f32 v27, v27, v30
	v_lshlrev_b32_e32 v30, 16, v80
	v_mul_f32_e32 v28, v28, v30
	v_and_b32_e32 v30, 0xffff0000, v80
	v_mul_f32_e32 v29, v29, v30
	v_cvt_pk_bf16_f32 v28, v28, v29
	v_lshlrev_b32_e32 v29, 16, v81
	v_and_b32_e32 v30, 0xffff0000, v81
	v_lshlrev_b64 v[34:35], 11, v[68:69]
	v_mul_f32_e32 v29, v36, v29
	v_mul_f32_e32 v30, v37, v30
	v_cvt_pk_bf16_f32 v29, v29, v30
	v_lshl_add_u64 v[30:31], s[74:75], 0, v[34:35]
	v_lshl_add_u64 v[30:31], v[30:31], 0, v[194:195]
	global_store_dwordx4 v[30:31], v[26:29], off
	s_nop 1
	v_pk_mul_f32 v[26:27], v[20:21], s[36:37] op_sel_hi:[1,0]
	v_pk_mul_f32 v[20:21], v[18:19], s[36:37] op_sel_hi:[1,0]
	v_lshlrev_b32_e32 v18, 16, v82
	v_and_b32_e32 v19, 0xffff0000, v82
	v_mul_f32_e32 v18, v22, v18
	v_mul_f32_e32 v19, v23, v19
	v_cvt_pk_bf16_f32 v18, v18, v19
	v_lshlrev_b32_e32 v19, 16, v83
	v_and_b32_e32 v22, 0xffff0000, v83
	v_mul_f32_e32 v19, v24, v19
	v_mul_f32_e32 v22, v25, v22
	v_cvt_pk_bf16_f32 v19, v19, v22
	v_lshlrev_b32_e32 v22, 16, v84
	v_mul_f32_e32 v20, v20, v22
	v_and_b32_e32 v22, 0xffff0000, v84
	v_mul_f32_e32 v21, v21, v22
	v_cvt_pk_bf16_f32 v20, v20, v21
	v_lshlrev_b32_e32 v21, 16, v85
	v_mul_f32_e32 v21, v26, v21
	v_and_b32_e32 v22, 0xffff0000, v85
	v_mul_f32_e32 v22, v27, v22
	v_cvt_pk_bf16_f32 v21, v21, v22
	global_store_dwordx4 v[30:31], v[18:21], off offset:256
	s_nop 1
	v_pk_mul_f32 v[20:21], v[12:13], s[36:37] op_sel_hi:[1,0]
	v_pk_mul_f32 v[12:13], v[10:11], s[36:37] op_sel_hi:[1,0]
	v_lshlrev_b32_e32 v10, 16, v54
	v_and_b32_e32 v11, 0xffff0000, v54
	v_mul_f32_e32 v10, v14, v10
	v_mul_f32_e32 v11, v15, v11
	v_cvt_pk_bf16_f32 v10, v10, v11
	v_lshlrev_b32_e32 v11, 16, v55
	v_and_b32_e32 v14, 0xffff0000, v55
	v_mul_f32_e32 v11, v16, v11
	v_mul_f32_e32 v14, v17, v14
	v_cvt_pk_bf16_f32 v11, v11, v14
	v_lshlrev_b32_e32 v14, 16, v56
	v_mul_f32_e32 v12, v12, v14
	v_and_b32_e32 v14, 0xffff0000, v56
	v_mul_f32_e32 v13, v13, v14
	v_cvt_pk_bf16_f32 v12, v12, v13
	v_lshlrev_b32_e32 v13, 16, v57
	v_and_b32_e32 v14, 0xffff0000, v57
	v_lshlrev_b64 v[18:19], 11, v[66:67]
	v_mul_f32_e32 v13, v20, v13
	v_mul_f32_e32 v14, v21, v14
	v_cvt_pk_bf16_f32 v13, v13, v14
	v_lshl_add_u64 v[14:15], s[74:75], 0, v[18:19]
	v_lshl_add_u64 v[14:15], v[14:15], 0, v[194:195]
	global_store_dwordx4 v[14:15], v[10:13], off
	s_nop 1
	v_pk_mul_f32 v[10:11], v[4:5], s[36:37] op_sel_hi:[1,0]
	v_pk_mul_f32 v[4:5], v[2:3], s[36:37] op_sel_hi:[1,0]
	v_lshlrev_b32_e32 v2, 16, v50
	v_and_b32_e32 v3, 0xffff0000, v50
	v_mul_f32_e32 v2, v6, v2
	v_mul_f32_e32 v3, v7, v3
	v_cvt_pk_bf16_f32 v2, v2, v3
	v_lshlrev_b32_e32 v3, 16, v51
	v_and_b32_e32 v6, 0xffff0000, v51
	v_mul_f32_e32 v3, v8, v3
	v_mul_f32_e32 v6, v9, v6
	v_cvt_pk_bf16_f32 v3, v3, v6
	v_lshlrev_b32_e32 v6, 16, v52
	v_mul_f32_e32 v4, v4, v6
	v_and_b32_e32 v6, 0xffff0000, v52
	v_mul_f32_e32 v5, v5, v6
	v_cvt_pk_bf16_f32 v4, v4, v5
	v_lshlrev_b32_e32 v5, 16, v53
	v_mul_f32_e32 v5, v10, v5
	v_and_b32_e32 v6, 0xffff0000, v53
	v_mul_f32_e32 v6, v11, v6
	v_cvt_pk_bf16_f32 v5, v5, v6
	global_store_dwordx4 v[14:15], v[2:5], off offset:256
	s_and_b64 vcc, exec, s[52:53]
	s_mov_b32 s28, s4
	s_cbranch_vccz .LBB0_265
	s_waitcnt vmcnt(0)
	v_readlane_b32 s28, v250, 12
	s_cmpk_gt_u32 s12, 0xff
	v_readlane_b32 s29, v250, 13
	s_mov_b32 s70, 0x800000
	s_cbranch_scc1 .LBB0_270
	s_barrier

.LBB0_368:
	v_or_b32_e32 v130, 0x10000, v201
	v_add_u32_e32 v134, 0x10400, v201
	v_add_u32_e32 v138, 0x10800, v201
	v_add_u32_e32 v142, 0x10c00, v201
	ds_read_b128 v[130:133], v130
	ds_read_b128 v[134:137], v134
	ds_read_b128 v[138:141], v138
	ds_read_b128 v[142:145], v142
	s_add_u32 s10, s8, 0xfffc0080
	s_addc_u32 s11, s9, -1
	s_cmp_eq_u32 s29, 12
	s_cselect_b32 s11, s81, s11
	s_cselect_b32 s10, s80, s10
	s_cselect_b32 s53, s83, s28
	s_cselect_b32 s52, s82, s7
	v_lshl_add_u64 v[178:179], s[8:9], 0, v[212:213]
	s_add_i32 m0, s34, 0xc000
	ds_read_b128 v[146:149], v199
	ds_read_b128 v[150:153], v199 offset:1024
	ds_read_b128 v[154:157], v199 offset:2048
	ds_read_b128 v[158:161], v199 offset:3072
	ds_read_b128 v[162:165], v199 offset:4096
	ds_read_b128 v[166:169], v199 offset:5120
	ds_read_b128 v[170:173], v199 offset:6144
	ds_read_b128 v[174:177], v199 offset:7168
	global_load_lds_dwordx4 v[178:179], off
	v_lshl_add_u64 v[178:179], s[8:9], 0, v[214:215]
	s_add_i32 m0, s34, 0xe000
	s_nop 0
	global_load_lds_dwordx4 v[178:179], off
	s_waitcnt lgkmcnt(8)
	s_barrier
	s_waitcnt lgkmcnt(0)
	s_setprio 1
	v_mfma_f32_16x16x32_bf16 v[126:129], v[130:133], v[146:149], v[126:129]
	v_mfma_f32_16x16x32_bf16 v[122:125], v[138:141], v[146:149], v[122:125]
	v_mfma_f32_16x16x32_bf16 v[118:121], v[130:133], v[154:157], v[118:121]
	v_mfma_f32_16x16x32_bf16 v[114:117], v[138:141], v[154:157], v[114:117]
	v_mfma_f32_16x16x32_bf16 v[110:113], v[130:133], v[162:165], v[110:113]
	v_mfma_f32_16x16x32_bf16 v[106:109], v[138:141], v[162:165], v[106:109]
	v_mfma_f32_16x16x32_bf16 v[102:105], v[130:133], v[170:173], v[102:105]
	v_mfma_f32_16x16x32_bf16 v[98:101], v[138:141], v[170:173], v[98:101]
	v_mfma_f32_16x16x32_bf16 v[126:129], v[134:137], v[150:153], v[126:129]
	v_mfma_f32_16x16x32_bf16 v[122:125], v[142:145], v[150:153], v[122:125]
	v_mfma_f32_16x16x32_bf16 v[118:121], v[134:137], v[158:161], v[118:121]
	v_mfma_f32_16x16x32_bf16 v[114:117], v[142:145], v[158:161], v[114:117]
	v_mfma_f32_16x16x32_bf16 v[110:113], v[134:137], v[166:169], v[110:113]
	v_mfma_f32_16x16x32_bf16 v[106:109], v[142:145], v[166:169], v[106:109]
	v_mfma_f32_16x16x32_bf16 v[102:105], v[134:137], v[174:177], v[102:105]
	v_mfma_f32_16x16x32_bf16 v[98:101], v[142:145], v[174:177], v[98:101]
	s_setprio 0
	s_barrier
	s_mov_b32 m0, s35
	v_or_b32_e32 v178, 0x14000, v201
	v_add_u32_e32 v182, 0x14400, v201
	v_add_u32_e32 v186, 0x14800, v201
	v_add_u32_e32 v190, 0x14c00, v201
	v_lshl_add_u64 v[216:217], s[52:53], 0, v[194:195]
	ds_read_b128 v[178:181], v178
	ds_read_b128 v[182:185], v182
	ds_read_b128 v[186:189], v186
	ds_read_b128 v[190:193], v190
	global_load_lds_dwordx4 v[216:217], off
	v_lshl_add_u64 v[218:219], s[52:53], 0, v[210:211]
	s_mov_b32 m0, s42
	s_nop 0
	global_load_lds_dwordx4 v[218:219], off
	s_barrier
	s_waitcnt lgkmcnt(0)
	s_setprio 1
	v_mfma_f32_16x16x32_bf16 v[94:97], v[178:181], v[146:149], v[94:97]
	v_mfma_f32_16x16x32_bf16 v[90:93], v[186:189], v[146:149], v[90:93]
	v_mfma_f32_16x16x32_bf16 v[86:89], v[178:181], v[154:157], v[86:89]
	v_mfma_f32_16x16x32_bf16 v[82:85], v[186:189], v[154:157], v[82:85]
	v_mfma_f32_16x16x32_bf16 v[78:81], v[178:181], v[162:165], v[78:81]
	v_mfma_f32_16x16x32_bf16 v[74:77], v[186:189], v[162:165], v[74:77]
	v_mfma_f32_16x16x32_bf16 v[70:73], v[178:181], v[170:173], v[70:73]
	v_mfma_f32_16x16x32_bf16 v[66:69], v[186:189], v[170:173], v[66:69]
	v_mfma_f32_16x16x32_bf16 v[94:97], v[182:185], v[150:153], v[94:97]
	v_mfma_f32_16x16x32_bf16 v[90:93], v[190:193], v[150:153], v[90:93]
	v_mfma_f32_16x16x32_bf16 v[86:89], v[182:185], v[158:161], v[86:89]
	v_mfma_f32_16x16x32_bf16 v[82:85], v[190:193], v[158:161], v[82:85]
	v_mfma_f32_16x16x32_bf16 v[78:81], v[182:185], v[166:169], v[78:81]
	v_mfma_f32_16x16x32_bf16 v[74:77], v[190:193], v[166:169], v[74:77]
	v_mfma_f32_16x16x32_bf16 v[70:73], v[182:185], v[174:177], v[70:73]
	v_mfma_f32_16x16x32_bf16 v[66:69], v[190:193], v[174:177], v[66:69]
	s_setprio 0
	s_mov_b32 m0, s34
	v_lshl_add_u64 v[220:221], s[10:11], 0, v[206:207]
	s_barrier
	ds_read_b128 v[146:149], v199 offset:16384
	ds_read_b128 v[150:153], v199 offset:17408
	ds_read_b128 v[154:157], v199 offset:18432
	ds_read_b128 v[158:161], v199 offset:19456
	ds_read_b128 v[162:165], v199 offset:20480
	ds_read_b128 v[166:169], v199 offset:21504
	ds_read_b128 v[170:173], v199 offset:22528
	ds_read_b128 v[174:177], v199 offset:23552
	global_load_lds_dwordx4 v[220:221], off
	v_lshl_add_u64 v[222:223], s[10:11], 0, v[208:209]
	s_mov_b32 m0, s56
	s_nop 0
	global_load_lds_dwordx4 v[222:223], off
	s_barrier
	s_waitcnt lgkmcnt(0)
	s_setprio 1
	v_mfma_f32_16x16x32_bf16 v[62:65], v[130:133], v[146:149], v[62:65]
	v_mfma_f32_16x16x32_bf16 v[58:61], v[138:141], v[146:149], v[58:61]
	v_mfma_f32_16x16x32_bf16 v[54:57], v[130:133], v[154:157], v[54:57]
	v_mfma_f32_16x16x32_bf16 v[50:53], v[138:141], v[154:157], v[50:53]
	v_mfma_f32_16x16x32_bf16 v[46:49], v[130:133], v[162:165], v[46:49]
	v_mfma_f32_16x16x32_bf16 v[42:45], v[138:141], v[162:165], v[42:45]
	v_mfma_f32_16x16x32_bf16 v[38:41], v[130:133], v[170:173], v[38:41]
	v_mfma_f32_16x16x32_bf16 v[34:37], v[138:141], v[170:173], v[34:37]
	v_mfma_f32_16x16x32_bf16 v[62:65], v[134:137], v[150:153], v[62:65]
	v_mfma_f32_16x16x32_bf16 v[58:61], v[142:145], v[150:153], v[58:61]
	v_mfma_f32_16x16x32_bf16 v[54:57], v[134:137], v[158:161], v[54:57]
	v_mfma_f32_16x16x32_bf16 v[50:53], v[142:145], v[158:161], v[50:53]
	v_mfma_f32_16x16x32_bf16 v[46:49], v[134:137], v[166:169], v[46:49]
	v_mfma_f32_16x16x32_bf16 v[42:45], v[142:145], v[166:169], v[42:45]
	v_mfma_f32_16x16x32_bf16 v[38:41], v[134:137], v[174:177], v[38:41]
	v_mfma_f32_16x16x32_bf16 v[34:37], v[142:145], v[174:177], v[34:37]
	s_setprio 0
	s_barrier
	s_add_u32 s86, s52, 0x40000
	s_addc_u32 s87, s53, 0
	s_mov_b32 m0, s57
	v_lshl_add_u64 v[130:131], s[86:87], 0, v[194:195]
	global_load_lds_dwordx4 v[130:131], off
	v_lshl_add_u64 v[130:131], s[86:87], 0, v[210:211]
	s_mov_b32 m0, s67
	s_nop 0
	global_load_lds_dwordx4 v[130:131], off
	s_waitcnt vmcnt(6)
	s_barrier
	s_setprio 1
	v_mfma_f32_16x16x32_bf16 v[30:33], v[178:181], v[146:149], v[30:33]
	v_mfma_f32_16x16x32_bf16 v[26:29], v[186:189], v[146:149], v[26:29]
	v_mfma_f32_16x16x32_bf16 v[22:25], v[178:181], v[154:157], v[22:25]
	v_mfma_f32_16x16x32_bf16 v[18:21], v[186:189], v[154:157], v[18:21]
	v_mfma_f32_16x16x32_bf16 v[14:17], v[178:181], v[162:165], v[14:17]
	v_mfma_f32_16x16x32_bf16 v[10:13], v[186:189], v[162:165], v[10:13]
	v_mfma_f32_16x16x32_bf16 v[6:9], v[178:181], v[170:173], v[6:9]
	v_mfma_f32_16x16x32_bf16 v[2:5], v[186:189], v[170:173], v[2:5]
	v_mfma_f32_16x16x32_bf16 v[30:33], v[182:185], v[150:153], v[30:33]
	v_mfma_f32_16x16x32_bf16 v[26:29], v[190:193], v[150:153], v[26:29]
	v_mfma_f32_16x16x32_bf16 v[22:25], v[182:185], v[158:161], v[22:25]
	v_mfma_f32_16x16x32_bf16 v[18:21], v[190:193], v[158:161], v[18:21]
	v_mfma_f32_16x16x32_bf16 v[14:17], v[182:185], v[166:169], v[14:17]
	v_mfma_f32_16x16x32_bf16 v[10:13], v[190:193], v[166:169], v[10:13]
	v_mfma_f32_16x16x32_bf16 v[6:9], v[182:185], v[174:177], v[6:9]
	v_mfma_f32_16x16x32_bf16 v[2:5], v[190:193], v[174:177], v[2:5]
	s_setprio 0
	v_or_b32_e32 v130, 0x18000, v201
	v_add_u32_e32 v134, 0x18400, v201
	v_add_u32_e32 v138, 0x18800, v201
	v_add_u32_e32 v142, 0x18c00, v201
	s_barrier
	ds_read_b128 v[130:133], v130
	ds_read_b128 v[134:137], v134
	ds_read_b128 v[138:141], v138
	ds_read_b128 v[142:145], v142
	s_add_u32 s10, s10, 0x40000
	s_addc_u32 s11, s11, 0
	s_mov_b32 m0, s70
	v_lshl_add_u64 v[178:179], s[10:11], 0, v[206:207]
	ds_read_b128 v[146:149], v199 offset:32768
	ds_read_b128 v[150:153], v199 offset:33792
	ds_read_b128 v[154:157], v199 offset:34816
	ds_read_b128 v[158:161], v199 offset:35840
	ds_read_b128 v[162:165], v199 offset:36864
	ds_read_b128 v[166:169], v199 offset:37888
	ds_read_b128 v[170:173], v199 offset:38912
	ds_read_b128 v[174:177], v199 offset:39936
	global_load_lds_dwordx4 v[178:179], off
	v_lshl_add_u64 v[178:179], s[10:11], 0, v[208:209]
	s_mov_b32 m0, s71
	s_nop 0
	global_load_lds_dwordx4 v[178:179], off
	s_waitcnt lgkmcnt(8)
	s_barrier
	s_waitcnt lgkmcnt(0)
	s_setprio 1
	v_mfma_f32_16x16x32_bf16 v[126:129], v[130:133], v[146:149], v[126:129]
	v_mfma_f32_16x16x32_bf16 v[122:125], v[138:141], v[146:149], v[122:125]
	v_mfma_f32_16x16x32_bf16 v[118:121], v[130:133], v[154:157], v[118:121]
	v_mfma_f32_16x16x32_bf16 v[114:117], v[138:141], v[154:157], v[114:117]
	v_mfma_f32_16x16x32_bf16 v[110:113], v[130:133], v[162:165], v[110:113]
	v_mfma_f32_16x16x32_bf16 v[106:109], v[138:141], v[162:165], v[106:109]
	v_mfma_f32_16x16x32_bf16 v[102:105], v[130:133], v[170:173], v[102:105]
	v_mfma_f32_16x16x32_bf16 v[98:101], v[138:141], v[170:173], v[98:101]
	v_mfma_f32_16x16x32_bf16 v[126:129], v[134:137], v[150:153], v[126:129]
	v_mfma_f32_16x16x32_bf16 v[122:125], v[142:145], v[150:153], v[122:125]
	v_mfma_f32_16x16x32_bf16 v[118:121], v[134:137], v[158:161], v[118:121]
	v_mfma_f32_16x16x32_bf16 v[114:117], v[142:145], v[158:161], v[114:117]
	v_mfma_f32_16x16x32_bf16 v[110:113], v[134:137], v[166:169], v[110:113]
	v_mfma_f32_16x16x32_bf16 v[106:109], v[142:145], v[166:169], v[106:109]
	v_mfma_f32_16x16x32_bf16 v[102:105], v[134:137], v[174:177], v[102:105]
	v_mfma_f32_16x16x32_bf16 v[98:101], v[142:145], v[174:177], v[98:101]
	s_setprio 0
	s_barrier
	s_mov_b32 m0, s78
	v_or_b32_e32 v178, 0x1c000, v201
	v_add_u32_e32 v182, 0x1c400, v201
	v_add_u32_e32 v186, 0x1c800, v201
	v_add_u32_e32 v190, 0x1cc00, v201
	v_lshl_add_u64 v[216:217], v[216:217], 0, s[76:77]
	ds_read_b128 v[178:181], v178
	ds_read_b128 v[182:185], v182
	ds_read_b128 v[186:189], v186
	ds_read_b128 v[190:193], v190
	global_load_lds_dwordx4 v[216:217], off
	v_lshl_add_u64 v[216:217], v[218:219], 0, s[76:77]
	s_mov_b32 m0, s79
	s_nop 0
	global_load_lds_dwordx4 v[216:217], off
	s_barrier
	s_waitcnt lgkmcnt(0)
	s_setprio 1
	v_mfma_f32_16x16x32_bf16 v[94:97], v[178:181], v[146:149], v[94:97]
	v_mfma_f32_16x16x32_bf16 v[90:93], v[186:189], v[146:149], v[90:93]
	v_mfma_f32_16x16x32_bf16 v[86:89], v[178:181], v[154:157], v[86:89]
	v_mfma_f32_16x16x32_bf16 v[82:85], v[186:189], v[154:157], v[82:85]
	v_mfma_f32_16x16x32_bf16 v[78:81], v[178:181], v[162:165], v[78:81]
	v_mfma_f32_16x16x32_bf16 v[74:77], v[186:189], v[162:165], v[74:77]
	v_mfma_f32_16x16x32_bf16 v[70:73], v[178:181], v[170:173], v[70:73]
	v_mfma_f32_16x16x32_bf16 v[66:69], v[186:189], v[170:173], v[66:69]
	v_mfma_f32_16x16x32_bf16 v[94:97], v[182:185], v[150:153], v[94:97]
	v_mfma_f32_16x16x32_bf16 v[90:93], v[190:193], v[150:153], v[90:93]
	v_mfma_f32_16x16x32_bf16 v[86:89], v[182:185], v[158:161], v[86:89]
	v_mfma_f32_16x16x32_bf16 v[82:85], v[190:193], v[158:161], v[82:85]
	v_mfma_f32_16x16x32_bf16 v[78:81], v[182:185], v[166:169], v[78:81]
	v_mfma_f32_16x16x32_bf16 v[74:77], v[190:193], v[166:169], v[74:77]
	v_mfma_f32_16x16x32_bf16 v[70:73], v[182:185], v[174:177], v[70:73]
	v_mfma_f32_16x16x32_bf16 v[66:69], v[190:193], v[174:177], v[66:69]
	s_setprio 0
	s_mov_b32 m0, s26
	v_lshl_add_u64 v[216:217], v[220:221], 0, s[76:77]
	s_barrier
	ds_read_b128 v[146:149], v199 offset:49152
	ds_read_b128 v[150:153], v199 offset:50176
	ds_read_b128 v[154:157], v199 offset:51200
	ds_read_b128 v[158:161], v199 offset:52224
	ds_read_b128 v[162:165], v199 offset:53248
	ds_read_b128 v[166:169], v199 offset:54272
	ds_read_b128 v[170:173], v199 offset:55296
	ds_read_b128 v[174:177], v199 offset:56320
	global_load_lds_dwordx4 v[216:217], off
	v_lshl_add_u64 v[216:217], v[222:223], 0, s[76:77]
	s_mov_b32 m0, s4
	s_nop 0
	global_load_lds_dwordx4 v[216:217], off
	s_barrier
	s_waitcnt lgkmcnt(0)
	s_setprio 1
	v_mfma_f32_16x16x32_bf16 v[62:65], v[130:133], v[146:149], v[62:65]
	v_mfma_f32_16x16x32_bf16 v[58:61], v[138:141], v[146:149], v[58:61]
	v_mfma_f32_16x16x32_bf16 v[54:57], v[130:133], v[154:157], v[54:57]
	v_mfma_f32_16x16x32_bf16 v[50:53], v[138:141], v[154:157], v[50:53]
	v_mfma_f32_16x16x32_bf16 v[46:49], v[130:133], v[162:165], v[46:49]
	v_mfma_f32_16x16x32_bf16 v[42:45], v[138:141], v[162:165], v[42:45]
	v_mfma_f32_16x16x32_bf16 v[38:41], v[130:133], v[170:173], v[38:41]
	v_mfma_f32_16x16x32_bf16 v[34:37], v[138:141], v[170:173], v[34:37]
	v_mfma_f32_16x16x32_bf16 v[62:65], v[134:137], v[150:153], v[62:65]
	v_mfma_f32_16x16x32_bf16 v[58:61], v[142:145], v[150:153], v[58:61]
	v_mfma_f32_16x16x32_bf16 v[54:57], v[134:137], v[158:161], v[54:57]
	v_mfma_f32_16x16x32_bf16 v[50:53], v[142:145], v[158:161], v[50:53]
	v_mfma_f32_16x16x32_bf16 v[46:49], v[134:137], v[166:169], v[46:49]
	v_mfma_f32_16x16x32_bf16 v[42:45], v[142:145], v[166:169], v[42:45]
	v_mfma_f32_16x16x32_bf16 v[38:41], v[134:137], v[174:177], v[38:41]
	v_mfma_f32_16x16x32_bf16 v[34:37], v[142:145], v[174:177], v[34:37]
	s_setprio 0
	s_barrier
	s_add_u32 s10, s52, 0x40080
	s_addc_u32 s11, s53, 0
	s_mov_b32 m0, s5
	v_lshl_add_u64 v[130:131], s[10:11], 0, v[194:195]
	global_load_lds_dwordx4 v[130:131], off
	v_lshl_add_u64 v[130:131], s[10:11], 0, v[210:211]
	s_mov_b32 m0, s58
	s_nop 0
	global_load_lds_dwordx4 v[130:131], off
	s_waitcnt vmcnt(6)
	s_barrier
	s_setprio 1
	v_mfma_f32_16x16x32_bf16 v[30:33], v[178:181], v[146:149], v[30:33]
	v_mfma_f32_16x16x32_bf16 v[26:29], v[186:189], v[146:149], v[26:29]
	v_mfma_f32_16x16x32_bf16 v[22:25], v[178:181], v[154:157], v[22:25]
	v_mfma_f32_16x16x32_bf16 v[18:21], v[186:189], v[154:157], v[18:21]
	v_mfma_f32_16x16x32_bf16 v[14:17], v[178:181], v[162:165], v[14:17]
	v_mfma_f32_16x16x32_bf16 v[10:13], v[186:189], v[162:165], v[10:13]
	v_mfma_f32_16x16x32_bf16 v[6:9], v[178:181], v[170:173], v[6:9]
	v_mfma_f32_16x16x32_bf16 v[2:5], v[186:189], v[170:173], v[2:5]
	v_mfma_f32_16x16x32_bf16 v[30:33], v[182:185], v[150:153], v[30:33]
	v_mfma_f32_16x16x32_bf16 v[26:29], v[190:193], v[150:153], v[26:29]
	v_mfma_f32_16x16x32_bf16 v[22:25], v[182:185], v[158:161], v[22:25]
	v_mfma_f32_16x16x32_bf16 v[18:21], v[190:193], v[158:161], v[18:21]
	v_mfma_f32_16x16x32_bf16 v[14:17], v[182:185], v[166:169], v[14:17]
	v_mfma_f32_16x16x32_bf16 v[10:13], v[190:193], v[166:169], v[10:13]
	v_mfma_f32_16x16x32_bf16 v[6:9], v[182:185], v[174:177], v[6:9]
	v_mfma_f32_16x16x32_bf16 v[2:5], v[190:193], v[174:177], v[2:5]
	s_setprio 0
	s_add_i32 s29, s29, 2
	s_add_u32 s8, s8, 0x100
	s_addc_u32 s9, s9, 0
	s_add_u32 s7, s7, 0x100
	s_addc_u32 s28, s28, 0
	s_cmp_gt_u32 s29, 13
	s_barrier
	s_cbranch_scc0 .LBB0_368
	s_cmp_gt_i32 s95, 1
	s_cselect_b64 s[52:53], -1, 0
	s_mul_i32 s7, s6, 0x680000
	s_lshl_b32 s8, s95, 12
	s_lshl_b32 s9, s54, 9
	s_add_i32 s7, s7, s8
	s_add_i32 s7, s7, s9
	s_add_i32 s7, s7, 0x3800
	s_add_u32 s20, s50, s7
	s_addc_u32 s21, s51, 0
	s_lshl_b32 s7, s6, 20
	s_add_i32 s7, s7, s9
	s_add_u32 s10, s96, s7
	s_addc_u32 s11, s97, 0
	s_mov_b32 s86, 0xbfb8aa3b
	s_mov_b32 s87, 0xbfb8aa3b
	v_mul_u32_u24_e32 v253, 0x6800, v197
	v_lshlrev_b32_e32 v255, 12, v197
	v_lshl_add_u32 v253, v203, 1, v253
	v_lshl_add_u32 v255, v203, 1, v255
	v_add_u32_e32 v254, 0x1000, v253
	s_cmp_eq_u32 s95, 2
	s_cbranch_scc1 .Lem_br2
	global_load_dwordx4 v[130:133], v253, s[20:21]
	global_load_dwordx4 v[134:137], v254, s[20:21]
	global_load_dwordx4 v[138:141], v253, s[20:21] offset:256
	global_load_dwordx4 v[142:145], v254, s[20:21] offset:256
	s_add_u32 s28, s20, 0x68000
	s_addc_u32 s29, s21, 0
	global_load_dwordx4 v[146:149], v253, s[28:29]
	global_load_dwordx4 v[150:153], v254, s[28:29]
	global_load_dwordx4 v[154:157], v253, s[28:29] offset:256
	global_load_dwordx4 v[158:161], v254, s[28:29] offset:256
	s_add_u32 s28, s20, 0xd0000
	s_addc_u32 s29, s21, 0
	global_load_dwordx4 v[162:165], v253, s[28:29]
	global_load_dwordx4 v[166:169], v254, s[28:29]
	global_load_dwordx4 v[170:173], v253, s[28:29] offset:256
	global_load_dwordx4 v[174:177], v254, s[28:29] offset:256
	s_add_u32 s28, s20, 0x138000
	s_addc_u32 s29, s21, 0
	global_load_dwordx4 v[178:181], v253, s[28:29]
	global_load_dwordx4 v[182:185], v254, s[28:29]
	global_load_dwordx4 v[186:189], v253, s[28:29] offset:256
	global_load_dwordx4 v[190:193], v254, s[28:29] offset:256
	s_waitcnt vmcnt(12)
	v_lshlrev_b32_e32 v216, 16, v130
	v_and_b32_e32 v217, 0xffff0000, v130
	v_lshlrev_b32_e32 v218, 16, v131
	v_and_b32_e32 v219, 0xffff0000, v131
	v_lshlrev_b32_e32 v220, 16, v132
	v_and_b32_e32 v221, 0xffff0000, v132
	v_lshlrev_b32_e32 v222, 16, v133
	v_and_b32_e32 v223, 0xffff0000, v133
	v_pk_mul_f32 v[216:217], v[216:217], s[86:87] op_sel_hi:[1,0]
	v_pk_mul_f32 v[218:219], v[218:219], s[86:87] op_sel_hi:[1,0]
	v_pk_mul_f32 v[220:221], v[220:221], s[86:87] op_sel_hi:[1,0]
	v_pk_mul_f32 v[222:223], v[222:223], s[86:87] op_sel_hi:[1,0]
	v_exp_f32_e32 v216, v216
	v_exp_f32_e32 v217, v217
	v_exp_f32_e32 v218, v218
	v_exp_f32_e32 v219, v219
	v_exp_f32_e32 v220, v220
	v_exp_f32_e32 v221, v221
	v_exp_f32_e32 v222, v222
	v_exp_f32_e32 v223, v223
	v_pk_add_f32 v[216:217], v[216:217], 1.0 op_sel_hi:[1,0]
	v_pk_add_f32 v[218:219], v[218:219], 1.0 op_sel_hi:[1,0]
	v_pk_add_f32 v[220:221], v[220:221], 1.0 op_sel_hi:[1,0]
	v_pk_add_f32 v[222:223], v[222:223], 1.0 op_sel_hi:[1,0]
	v_rcp_f32_e32 v216, v216
	v_rcp_f32_e32 v217, v217
	v_rcp_f32_e32 v218, v218
	v_rcp_f32_e32 v219, v219
	v_rcp_f32_e32 v220, v220
	v_rcp_f32_e32 v221, v221
	v_rcp_f32_e32 v222, v222
	v_rcp_f32_e32 v223, v223
	v_lshlrev_b32_e32 v242, 16, v134
	v_and_b32_e32 v243, 0xffff0000, v134
	v_lshlrev_b32_e32 v244, 16, v135
	v_and_b32_e32 v245, 0xffff0000, v135
	v_lshlrev_b32_e32 v246, 16, v136
	v_and_b32_e32 v247, 0xffff0000, v136
	v_lshlrev_b32_e32 v248, 16, v137
	v_and_b32_e32 v249, 0xffff0000, v137
	v_pk_mul_f32 v[242:243], v[242:243], s[86:87] op_sel_hi:[1,0]
	v_pk_mul_f32 v[244:245], v[244:245], s[86:87] op_sel_hi:[1,0]
	v_pk_mul_f32 v[246:247], v[246:247], s[86:87] op_sel_hi:[1,0]
	v_pk_mul_f32 v[248:249], v[248:249], s[86:87] op_sel_hi:[1,0]
	v_exp_f32_e32 v242, v242
	v_exp_f32_e32 v243, v243
	v_exp_f32_e32 v244, v244
	v_exp_f32_e32 v245, v245
	v_exp_f32_e32 v246, v246
	v_exp_f32_e32 v247, v247
	v_exp_f32_e32 v248, v248
	v_exp_f32_e32 v249, v249
	v_pk_add_f32 v[242:243], v[242:243], 1.0 op_sel_hi:[1,0]
	v_pk_add_f32 v[244:245], v[244:245], 1.0 op_sel_hi:[1,0]
	v_pk_add_f32 v[246:247], v[246:247], 1.0 op_sel_hi:[1,0]
	v_pk_add_f32 v[248:249], v[248:249], 1.0 op_sel_hi:[1,0]
	v_pk_mul_f32 v[216:217], v[216:217], v[242:243]
	v_pk_mul_f32 v[218:219], v[218:219], v[244:245]
	v_pk_mul_f32 v[220:221], v[220:221], v[246:247]
	v_pk_mul_f32 v[222:223], v[222:223], v[248:249]
	v_pk_mul_f32 v[126:127], v[126:127], v[216:217]
	v_pk_mul_f32 v[128:129], v[128:129], v[218:219]
	v_pk_mul_f32 v[122:123], v[122:123], v[220:221]
	v_pk_mul_f32 v[124:125], v[124:125], v[222:223]
	v_lshlrev_b32_e32 v216, 16, v138
	v_and_b32_e32 v217, 0xffff0000, v138
	v_lshlrev_b32_e32 v218, 16, v139
	v_and_b32_e32 v219, 0xffff0000, v139
	v_lshlrev_b32_e32 v220, 16, v140
	v_and_b32_e32 v221, 0xffff0000, v140
	v_lshlrev_b32_e32 v222, 16, v141
	v_and_b32_e32 v223, 0xffff0000, v141
	v_pk_mul_f32 v[216:217], v[216:217], s[86:87] op_sel_hi:[1,0]
	v_pk_mul_f32 v[218:219], v[218:219], s[86:87] op_sel_hi:[1,0]
	v_pk_mul_f32 v[220:221], v[220:221], s[86:87] op_sel_hi:[1,0]
	v_pk_mul_f32 v[222:223], v[222:223], s[86:87] op_sel_hi:[1,0]
	v_exp_f32_e32 v216, v216
	v_exp_f32_e32 v217, v217
	v_exp_f32_e32 v218, v218
	v_exp_f32_e32 v219, v219
	v_exp_f32_e32 v220, v220
	v_exp_f32_e32 v221, v221
	v_exp_f32_e32 v222, v222
	v_exp_f32_e32 v223, v223
	v_pk_add_f32 v[216:217], v[216:217], 1.0 op_sel_hi:[1,0]
	v_pk_add_f32 v[218:219], v[218:219], 1.0 op_sel_hi:[1,0]
	v_pk_add_f32 v[220:221], v[220:221], 1.0 op_sel_hi:[1,0]
	v_pk_add_f32 v[222:223], v[222:223], 1.0 op_sel_hi:[1,0]
	v_rcp_f32_e32 v216, v216
	v_rcp_f32_e32 v217, v217
	v_rcp_f32_e32 v218, v218
	v_rcp_f32_e32 v219, v219
	v_rcp_f32_e32 v220, v220
	v_rcp_f32_e32 v221, v221
	v_rcp_f32_e32 v222, v222
	v_rcp_f32_e32 v223, v223
	v_lshlrev_b32_e32 v242, 16, v142
	v_and_b32_e32 v243, 0xffff0000, v142
	v_lshlrev_b32_e32 v244, 16, v143
	v_and_b32_e32 v245, 0xffff0000, v143
	v_lshlrev_b32_e32 v246, 16, v144
	v_and_b32_e32 v247, 0xffff0000, v144
	v_lshlrev_b32_e32 v248, 16, v145
	v_and_b32_e32 v249, 0xffff0000, v145
	v_pk_mul_f32 v[242:243], v[242:243], s[86:87] op_sel_hi:[1,0]
	v_pk_mul_f32 v[244:245], v[244:245], s[86:87] op_sel_hi:[1,0]
	v_pk_mul_f32 v[246:247], v[246:247], s[86:87] op_sel_hi:[1,0]
	v_pk_mul_f32 v[248:249], v[248:249], s[86:87] op_sel_hi:[1,0]
	v_exp_f32_e32 v242, v242
	v_exp_f32_e32 v243, v243
	v_exp_f32_e32 v244, v244
	v_exp_f32_e32 v245, v245
	v_exp_f32_e32 v246, v246
	v_exp_f32_e32 v247, v247
	v_exp_f32_e32 v248, v248
	v_exp_f32_e32 v249, v249
	v_pk_add_f32 v[242:243], v[242:243], 1.0 op_sel_hi:[1,0]
	v_pk_add_f32 v[244:245], v[244:245], 1.0 op_sel_hi:[1,0]
	v_pk_add_f32 v[246:247], v[246:247], 1.0 op_sel_hi:[1,0]
	v_pk_add_f32 v[248:249], v[248:249], 1.0 op_sel_hi:[1,0]
	v_pk_mul_f32 v[216:217], v[216:217], v[242:243]
	v_pk_mul_f32 v[218:219], v[218:219], v[244:245]
	v_pk_mul_f32 v[220:221], v[220:221], v[246:247]
	v_pk_mul_f32 v[222:223], v[222:223], v[248:249]
	v_pk_mul_f32 v[94:95], v[94:95], v[216:217]
	v_pk_mul_f32 v[96:97], v[96:97], v[218:219]
	v_pk_mul_f32 v[90:91], v[90:91], v[220:221]
	v_pk_mul_f32 v[92:93], v[92:93], v[222:223]
	s_add_u32 s28, s20, 0x340000
	s_addc_u32 s29, s21, 0
	global_load_dwordx4 v[130:133], v253, s[28:29]
	global_load_dwordx4 v[134:137], v254, s[28:29]
	global_load_dwordx4 v[138:141], v253, s[28:29] offset:256
	global_load_dwordx4 v[142:145], v254, s[28:29] offset:256
	s_waitcnt vmcnt(12)
	v_lshlrev_b32_e32 v216, 16, v146
	v_and_b32_e32 v217, 0xffff0000, v146
	v_lshlrev_b32_e32 v218, 16, v147
	v_and_b32_e32 v219, 0xffff0000, v147
	v_lshlrev_b32_e32 v220, 16, v148
	v_and_b32_e32 v221, 0xffff0000, v148
	v_lshlrev_b32_e32 v222, 16, v149
	v_and_b32_e32 v223, 0xffff0000, v149
	v_pk_mul_f32 v[216:217], v[216:217], s[86:87] op_sel_hi:[1,0]
	v_pk_mul_f32 v[218:219], v[218:219], s[86:87] op_sel_hi:[1,0]
	v_pk_mul_f32 v[220:221], v[220:221], s[86:87] op_sel_hi:[1,0]
	v_pk_mul_f32 v[222:223], v[222:223], s[86:87] op_sel_hi:[1,0]
	v_exp_f32_e32 v216, v216
	v_exp_f32_e32 v217, v217
	v_exp_f32_e32 v218, v218
	v_exp_f32_e32 v219, v219
	v_exp_f32_e32 v220, v220
	v_exp_f32_e32 v221, v221
	v_exp_f32_e32 v222, v222
	v_exp_f32_e32 v223, v223
	v_pk_add_f32 v[216:217], v[216:217], 1.0 op_sel_hi:[1,0]
	v_pk_add_f32 v[218:219], v[218:219], 1.0 op_sel_hi:[1,0]
	v_pk_add_f32 v[220:221], v[220:221], 1.0 op_sel_hi:[1,0]
	v_pk_add_f32 v[222:223], v[222:223], 1.0 op_sel_hi:[1,0]
	v_rcp_f32_e32 v216, v216
	v_rcp_f32_e32 v217, v217
	v_rcp_f32_e32 v218, v218
	v_rcp_f32_e32 v219, v219
	v_rcp_f32_e32 v220, v220
	v_rcp_f32_e32 v221, v221
	v_rcp_f32_e32 v222, v222
	v_rcp_f32_e32 v223, v223
	v_lshlrev_b32_e32 v242, 16, v150
	v_and_b32_e32 v243, 0xffff0000, v150
	v_lshlrev_b32_e32 v244, 16, v151
	v_and_b32_e32 v245, 0xffff0000, v151
	v_lshlrev_b32_e32 v246, 16, v152
	v_and_b32_e32 v247, 0xffff0000, v152
	v_lshlrev_b32_e32 v248, 16, v153
	v_and_b32_e32 v249, 0xffff0000, v153
	v_pk_mul_f32 v[242:243], v[242:243], s[86:87] op_sel_hi:[1,0]
	v_pk_mul_f32 v[244:245], v[244:245], s[86:87] op_sel_hi:[1,0]
	v_pk_mul_f32 v[246:247], v[246:247], s[86:87] op_sel_hi:[1,0]
	v_pk_mul_f32 v[248:249], v[248:249], s[86:87] op_sel_hi:[1,0]
	v_exp_f32_e32 v242, v242
	v_exp_f32_e32 v243, v243
	v_exp_f32_e32 v244, v244
	v_exp_f32_e32 v245, v245
	v_exp_f32_e32 v246, v246
	v_exp_f32_e32 v247, v247
	v_exp_f32_e32 v248, v248
	v_exp_f32_e32 v249, v249
	v_pk_add_f32 v[242:243], v[242:243], 1.0 op_sel_hi:[1,0]
	v_pk_add_f32 v[244:245], v[244:245], 1.0 op_sel_hi:[1,0]
	v_pk_add_f32 v[246:247], v[246:247], 1.0 op_sel_hi:[1,0]
	v_pk_add_f32 v[248:249], v[248:249], 1.0 op_sel_hi:[1,0]
	v_pk_mul_f32 v[216:217], v[216:217], v[242:243]
	v_pk_mul_f32 v[218:219], v[218:219], v[244:245]
	v_pk_mul_f32 v[220:221], v[220:221], v[246:247]
	v_pk_mul_f32 v[222:223], v[222:223], v[248:249]
	v_pk_mul_f32 v[118:119], v[118:119], v[216:217]
	v_pk_mul_f32 v[120:121], v[120:121], v[218:219]
	v_pk_mul_f32 v[114:115], v[114:115], v[220:221]
	v_pk_mul_f32 v[116:117], v[116:117], v[222:223]
	v_lshlrev_b32_e32 v216, 16, v154
	v_and_b32_e32 v217, 0xffff0000, v154
	v_lshlrev_b32_e32 v218, 16, v155
	v_and_b32_e32 v219, 0xffff0000, v155
	v_lshlrev_b32_e32 v220, 16, v156
	v_and_b32_e32 v221, 0xffff0000, v156
	v_lshlrev_b32_e32 v222, 16, v157
	v_and_b32_e32 v223, 0xffff0000, v157
	v_pk_mul_f32 v[216:217], v[216:217], s[86:87] op_sel_hi:[1,0]
	v_pk_mul_f32 v[218:219], v[218:219], s[86:87] op_sel_hi:[1,0]
	v_pk_mul_f32 v[220:221], v[220:221], s[86:87] op_sel_hi:[1,0]
	v_pk_mul_f32 v[222:223], v[222:223], s[86:87] op_sel_hi:[1,0]
	v_exp_f32_e32 v216, v216
	v_exp_f32_e32 v217, v217
	v_exp_f32_e32 v218, v218
	v_exp_f32_e32 v219, v219
	v_exp_f32_e32 v220, v220
	v_exp_f32_e32 v221, v221
	v_exp_f32_e32 v222, v222
	v_exp_f32_e32 v223, v223
	v_pk_add_f32 v[216:217], v[216:217], 1.0 op_sel_hi:[1,0]
	v_pk_add_f32 v[218:219], v[218:219], 1.0 op_sel_hi:[1,0]
	v_pk_add_f32 v[220:221], v[220:221], 1.0 op_sel_hi:[1,0]
	v_pk_add_f32 v[222:223], v[222:223], 1.0 op_sel_hi:[1,0]
	v_rcp_f32_e32 v216, v216
	v_rcp_f32_e32 v217, v217
	v_rcp_f32_e32 v218, v218
	v_rcp_f32_e32 v219, v219
	v_rcp_f32_e32 v220, v220
	v_rcp_f32_e32 v221, v221
	v_rcp_f32_e32 v222, v222
	v_rcp_f32_e32 v223, v223
	v_lshlrev_b32_e32 v242, 16, v158
	v_and_b32_e32 v243, 0xffff0000, v158
	v_lshlrev_b32_e32 v244, 16, v159
	v_and_b32_e32 v245, 0xffff0000, v159
	v_lshlrev_b32_e32 v246, 16, v160
	v_and_b32_e32 v247, 0xffff0000, v160
	v_lshlrev_b32_e32 v248, 16, v161
	v_and_b32_e32 v249, 0xffff0000, v161
	v_pk_mul_f32 v[242:243], v[242:243], s[86:87] op_sel_hi:[1,0]
	v_pk_mul_f32 v[244:245], v[244:245], s[86:87] op_sel_hi:[1,0]
	v_pk_mul_f32 v[246:247], v[246:247], s[86:87] op_sel_hi:[1,0]
	v_pk_mul_f32 v[248:249], v[248:249], s[86:87] op_sel_hi:[1,0]
	v_exp_f32_e32 v242, v242
	v_exp_f32_e32 v243, v243
	v_exp_f32_e32 v244, v244
	v_exp_f32_e32 v245, v245
	v_exp_f32_e32 v246, v246
	v_exp_f32_e32 v247, v247
	v_exp_f32_e32 v248, v248
	v_exp_f32_e32 v249, v249
	v_pk_add_f32 v[242:243], v[242:243], 1.0 op_sel_hi:[1,0]
	v_pk_add_f32 v[244:245], v[244:245], 1.0 op_sel_hi:[1,0]
	v_pk_add_f32 v[246:247], v[246:247], 1.0 op_sel_hi:[1,0]
	v_pk_add_f32 v[248:249], v[248:249], 1.0 op_sel_hi:[1,0]
	v_pk_mul_f32 v[216:217], v[216:217], v[242:243]
	v_pk_mul_f32 v[218:219], v[218:219], v[244:245]
	v_pk_mul_f32 v[220:221], v[220:221], v[246:247]
	v_pk_mul_f32 v[222:223], v[222:223], v[248:249]
	v_pk_mul_f32 v[86:87], v[86:87], v[216:217]
	v_pk_mul_f32 v[88:89], v[88:89], v[218:219]
	v_pk_mul_f32 v[82:83], v[82:83], v[220:221]
	v_pk_mul_f32 v[84:85], v[84:85], v[222:223]
	s_add_u32 s28, s20, 0x3a8000
	s_addc_u32 s29, s21, 0
	global_load_dwordx4 v[146:149], v253, s[28:29]
	global_load_dwordx4 v[150:153], v254, s[28:29]
	global_load_dwordx4 v[154:157], v253, s[28:29] offset:256
	global_load_dwordx4 v[158:161], v254, s[28:29] offset:256
	s_waitcnt vmcnt(12)
	v_lshlrev_b32_e32 v216, 16, v162
	v_and_b32_e32 v217, 0xffff0000, v162
	v_lshlrev_b32_e32 v218, 16, v163
	v_and_b32_e32 v219, 0xffff0000, v163
	v_lshlrev_b32_e32 v220, 16, v164
	v_and_b32_e32 v221, 0xffff0000, v164
	v_lshlrev_b32_e32 v222, 16, v165
	v_and_b32_e32 v223, 0xffff0000, v165
	v_pk_mul_f32 v[216:217], v[216:217], s[86:87] op_sel_hi:[1,0]
	v_pk_mul_f32 v[218:219], v[218:219], s[86:87] op_sel_hi:[1,0]
	v_pk_mul_f32 v[220:221], v[220:221], s[86:87] op_sel_hi:[1,0]
	v_pk_mul_f32 v[222:223], v[222:223], s[86:87] op_sel_hi:[1,0]
	v_exp_f32_e32 v216, v216
	v_exp_f32_e32 v217, v217
	v_exp_f32_e32 v218, v218
	v_exp_f32_e32 v219, v219
	v_exp_f32_e32 v220, v220
	v_exp_f32_e32 v221, v221
	v_exp_f32_e32 v222, v222
	v_exp_f32_e32 v223, v223
	v_pk_add_f32 v[216:217], v[216:217], 1.0 op_sel_hi:[1,0]
	v_pk_add_f32 v[218:219], v[218:219], 1.0 op_sel_hi:[1,0]
	v_pk_add_f32 v[220:221], v[220:221], 1.0 op_sel_hi:[1,0]
	v_pk_add_f32 v[222:223], v[222:223], 1.0 op_sel_hi:[1,0]
	v_rcp_f32_e32 v216, v216
	v_rcp_f32_e32 v217, v217
	v_rcp_f32_e32 v218, v218
	v_rcp_f32_e32 v219, v219
	v_rcp_f32_e32 v220, v220
	v_rcp_f32_e32 v221, v221
	v_rcp_f32_e32 v222, v222
	v_rcp_f32_e32 v223, v223
	v_lshlrev_b32_e32 v242, 16, v166
	v_and_b32_e32 v243, 0xffff0000, v166
	v_lshlrev_b32_e32 v244, 16, v167
	v_and_b32_e32 v245, 0xffff0000, v167
	v_lshlrev_b32_e32 v246, 16, v168
	v_and_b32_e32 v247, 0xffff0000, v168
	v_lshlrev_b32_e32 v248, 16, v169
	v_and_b32_e32 v249, 0xffff0000, v169
	v_pk_mul_f32 v[242:243], v[242:243], s[86:87] op_sel_hi:[1,0]
	v_pk_mul_f32 v[244:245], v[244:245], s[86:87] op_sel_hi:[1,0]
	v_pk_mul_f32 v[246:247], v[246:247], s[86:87] op_sel_hi:[1,0]
	v_pk_mul_f32 v[248:249], v[248:249], s[86:87] op_sel_hi:[1,0]
	v_exp_f32_e32 v242, v242
	v_exp_f32_e32 v243, v243
	v_exp_f32_e32 v244, v244
	v_exp_f32_e32 v245, v245
	v_exp_f32_e32 v246, v246
	v_exp_f32_e32 v247, v247
	v_exp_f32_e32 v248, v248
	v_exp_f32_e32 v249, v249
	v_pk_add_f32 v[242:243], v[242:243], 1.0 op_sel_hi:[1,0]
	v_pk_add_f32 v[244:245], v[244:245], 1.0 op_sel_hi:[1,0]
	v_pk_add_f32 v[246:247], v[246:247], 1.0 op_sel_hi:[1,0]
	v_pk_add_f32 v[248:249], v[248:249], 1.0 op_sel_hi:[1,0]
	v_pk_mul_f32 v[216:217], v[216:217], v[242:243]
	v_pk_mul_f32 v[218:219], v[218:219], v[244:245]
	v_pk_mul_f32 v[220:221], v[220:221], v[246:247]
	v_pk_mul_f32 v[222:223], v[222:223], v[248:249]
	v_pk_mul_f32 v[110:111], v[110:111], v[216:217]
	v_pk_mul_f32 v[112:113], v[112:113], v[218:219]
	v_pk_mul_f32 v[106:107], v[106:107], v[220:221]
	v_pk_mul_f32 v[108:109], v[108:109], v[222:223]
	v_lshlrev_b32_e32 v216, 16, v170
	v_and_b32_e32 v217, 0xffff0000, v170
	v_lshlrev_b32_e32 v218, 16, v171
	v_and_b32_e32 v219, 0xffff0000, v171
	v_lshlrev_b32_e32 v220, 16, v172
	v_and_b32_e32 v221, 0xffff0000, v172
	v_lshlrev_b32_e32 v222, 16, v173
	v_and_b32_e32 v223, 0xffff0000, v173
	v_pk_mul_f32 v[216:217], v[216:217], s[86:87] op_sel_hi:[1,0]
	v_pk_mul_f32 v[218:219], v[218:219], s[86:87] op_sel_hi:[1,0]
	v_pk_mul_f32 v[220:221], v[220:221], s[86:87] op_sel_hi:[1,0]
	v_pk_mul_f32 v[222:223], v[222:223], s[86:87] op_sel_hi:[1,0]
	v_exp_f32_e32 v216, v216
	v_exp_f32_e32 v217, v217
	v_exp_f32_e32 v218, v218
	v_exp_f32_e32 v219, v219
	v_exp_f32_e32 v220, v220
	v_exp_f32_e32 v221, v221
	v_exp_f32_e32 v222, v222
	v_exp_f32_e32 v223, v223
	v_pk_add_f32 v[216:217], v[216:217], 1.0 op_sel_hi:[1,0]
	v_pk_add_f32 v[218:219], v[218:219], 1.0 op_sel_hi:[1,0]
	v_pk_add_f32 v[220:221], v[220:221], 1.0 op_sel_hi:[1,0]
	v_pk_add_f32 v[222:223], v[222:223], 1.0 op_sel_hi:[1,0]
	v_rcp_f32_e32 v216, v216
	v_rcp_f32_e32 v217, v217
	v_rcp_f32_e32 v218, v218
	v_rcp_f32_e32 v219, v219
	v_rcp_f32_e32 v220, v220
	v_rcp_f32_e32 v221, v221
	v_rcp_f32_e32 v222, v222
	v_rcp_f32_e32 v223, v223
	v_lshlrev_b32_e32 v242, 16, v174
	v_and_b32_e32 v243, 0xffff0000, v174
	v_lshlrev_b32_e32 v244, 16, v175
	v_and_b32_e32 v245, 0xffff0000, v175
	v_lshlrev_b32_e32 v246, 16, v176
	v_and_b32_e32 v247, 0xffff0000, v176
	v_lshlrev_b32_e32 v248, 16, v177
	v_and_b32_e32 v249, 0xffff0000, v177
	v_pk_mul_f32 v[242:243], v[242:243], s[86:87] op_sel_hi:[1,0]
	v_pk_mul_f32 v[244:245], v[244:245], s[86:87] op_sel_hi:[1,0]
	v_pk_mul_f32 v[246:247], v[246:247], s[86:87] op_sel_hi:[1,0]
	v_pk_mul_f32 v[248:249], v[248:249], s[86:87] op_sel_hi:[1,0]
	v_exp_f32_e32 v242, v242
	v_exp_f32_e32 v243, v243
	v_exp_f32_e32 v244, v244
	v_exp_f32_e32 v245, v245
	v_exp_f32_e32 v246, v246
	v_exp_f32_e32 v247, v247
	v_exp_f32_e32 v248, v248
	v_exp_f32_e32 v249, v249
	v_pk_add_f32 v[242:243], v[242:243], 1.0 op_sel_hi:[1,0]
	v_pk_add_f32 v[244:245], v[244:245], 1.0 op_sel_hi:[1,0]
	v_pk_add_f32 v[246:247], v[246:247], 1.0 op_sel_hi:[1,0]
	v_pk_add_f32 v[248:249], v[248:249], 1.0 op_sel_hi:[1,0]
	v_pk_mul_f32 v[216:217], v[216:217], v[242:243]
	v_pk_mul_f32 v[218:219], v[218:219], v[244:245]
	v_pk_mul_f32 v[220:221], v[220:221], v[246:247]
	v_pk_mul_f32 v[222:223], v[222:223], v[248:249]
	v_pk_mul_f32 v[78:79], v[78:79], v[216:217]
	v_pk_mul_f32 v[80:81], v[80:81], v[218:219]
	v_pk_mul_f32 v[74:75], v[74:75], v[220:221]
	v_pk_mul_f32 v[76:77], v[76:77], v[222:223]
	s_add_u32 s28, s20, 0x410000
	s_addc_u32 s29, s21, 0
	global_load_dwordx4 v[162:165], v253, s[28:29]
	global_load_dwordx4 v[166:169], v254, s[28:29]
	global_load_dwordx4 v[170:173], v253, s[28:29] offset:256
	global_load_dwordx4 v[174:177], v254, s[28:29] offset:256
	s_waitcnt vmcnt(12)
	v_lshlrev_b32_e32 v216, 16, v178
	v_and_b32_e32 v217, 0xffff0000, v178
	v_lshlrev_b32_e32 v218, 16, v179
	v_and_b32_e32 v219, 0xffff0000, v179
	v_lshlrev_b32_e32 v220, 16, v180
	v_and_b32_e32 v221, 0xffff0000, v180
	v_lshlrev_b32_e32 v222, 16, v181
	v_and_b32_e32 v223, 0xffff0000, v181
	v_pk_mul_f32 v[216:217], v[216:217], s[86:87] op_sel_hi:[1,0]
	v_pk_mul_f32 v[218:219], v[218:219], s[86:87] op_sel_hi:[1,0]
	v_pk_mul_f32 v[220:221], v[220:221], s[86:87] op_sel_hi:[1,0]
	v_pk_mul_f32 v[222:223], v[222:223], s[86:87] op_sel_hi:[1,0]
	v_exp_f32_e32 v216, v216
	v_exp_f32_e32 v217, v217
	v_exp_f32_e32 v218, v218
	v_exp_f32_e32 v219, v219
	v_exp_f32_e32 v220, v220
	v_exp_f32_e32 v221, v221
	v_exp_f32_e32 v222, v222
	v_exp_f32_e32 v223, v223
	v_pk_add_f32 v[216:217], v[216:217], 1.0 op_sel_hi:[1,0]
	v_pk_add_f32 v[218:219], v[218:219], 1.0 op_sel_hi:[1,0]
	v_pk_add_f32 v[220:221], v[220:221], 1.0 op_sel_hi:[1,0]
	v_pk_add_f32 v[222:223], v[222:223], 1.0 op_sel_hi:[1,0]
	v_rcp_f32_e32 v216, v216
	v_rcp_f32_e32 v217, v217
	v_rcp_f32_e32 v218, v218
	v_rcp_f32_e32 v219, v219
	v_rcp_f32_e32 v220, v220
	v_rcp_f32_e32 v221, v221
	v_rcp_f32_e32 v222, v222
	v_rcp_f32_e32 v223, v223
	v_lshlrev_b32_e32 v242, 16, v182
	v_and_b32_e32 v243, 0xffff0000, v182
	v_lshlrev_b32_e32 v244, 16, v183
	v_and_b32_e32 v245, 0xffff0000, v183
	v_lshlrev_b32_e32 v246, 16, v184
	v_and_b32_e32 v247, 0xffff0000, v184
	v_lshlrev_b32_e32 v248, 16, v185
	v_and_b32_e32 v249, 0xffff0000, v185
	v_pk_mul_f32 v[242:243], v[242:243], s[86:87] op_sel_hi:[1,0]
	v_pk_mul_f32 v[244:245], v[244:245], s[86:87] op_sel_hi:[1,0]
	v_pk_mul_f32 v[246:247], v[246:247], s[86:87] op_sel_hi:[1,0]
	v_pk_mul_f32 v[248:249], v[248:249], s[86:87] op_sel_hi:[1,0]
	v_exp_f32_e32 v242, v242
	v_exp_f32_e32 v243, v243
	v_exp_f32_e32 v244, v244
	v_exp_f32_e32 v245, v245
	v_exp_f32_e32 v246, v246
	v_exp_f32_e32 v247, v247
	v_exp_f32_e32 v248, v248
	v_exp_f32_e32 v249, v249
	v_pk_add_f32 v[242:243], v[242:243], 1.0 op_sel_hi:[1,0]
	v_pk_add_f32 v[244:245], v[244:245], 1.0 op_sel_hi:[1,0]
	v_pk_add_f32 v[246:247], v[246:247], 1.0 op_sel_hi:[1,0]
	v_pk_add_f32 v[248:249], v[248:249], 1.0 op_sel_hi:[1,0]
	v_pk_mul_f32 v[216:217], v[216:217], v[242:243]
	v_pk_mul_f32 v[218:219], v[218:219], v[244:245]
	v_pk_mul_f32 v[220:221], v[220:221], v[246:247]
	v_pk_mul_f32 v[222:223], v[222:223], v[248:249]
	v_pk_mul_f32 v[102:103], v[102:103], v[216:217]
	v_pk_mul_f32 v[104:105], v[104:105], v[218:219]
	v_pk_mul_f32 v[98:99], v[98:99], v[220:221]
	v_pk_mul_f32 v[100:101], v[100:101], v[222:223]
	v_lshlrev_b32_e32 v216, 16, v186
	v_and_b32_e32 v217, 0xffff0000, v186
	v_lshlrev_b32_e32 v218, 16, v187
	v_and_b32_e32 v219, 0xffff0000, v187
	v_lshlrev_b32_e32 v220, 16, v188
	v_and_b32_e32 v221, 0xffff0000, v188
	v_lshlrev_b32_e32 v222, 16, v189
	v_and_b32_e32 v223, 0xffff0000, v189
	v_pk_mul_f32 v[216:217], v[216:217], s[86:87] op_sel_hi:[1,0]
	v_pk_mul_f32 v[218:219], v[218:219], s[86:87] op_sel_hi:[1,0]
	v_pk_mul_f32 v[220:221], v[220:221], s[86:87] op_sel_hi:[1,0]
	v_pk_mul_f32 v[222:223], v[222:223], s[86:87] op_sel_hi:[1,0]
	v_exp_f32_e32 v216, v216
	v_exp_f32_e32 v217, v217
	v_exp_f32_e32 v218, v218
	v_exp_f32_e32 v219, v219
	v_exp_f32_e32 v220, v220
	v_exp_f32_e32 v221, v221
	v_exp_f32_e32 v222, v222
	v_exp_f32_e32 v223, v223
	v_pk_add_f32 v[216:217], v[216:217], 1.0 op_sel_hi:[1,0]
	v_pk_add_f32 v[218:219], v[218:219], 1.0 op_sel_hi:[1,0]
	v_pk_add_f32 v[220:221], v[220:221], 1.0 op_sel_hi:[1,0]
	v_pk_add_f32 v[222:223], v[222:223], 1.0 op_sel_hi:[1,0]
	v_rcp_f32_e32 v216, v216
	v_rcp_f32_e32 v217, v217
	v_rcp_f32_e32 v218, v218
	v_rcp_f32_e32 v219, v219
	v_rcp_f32_e32 v220, v220
	v_rcp_f32_e32 v221, v221
	v_rcp_f32_e32 v222, v222
	v_rcp_f32_e32 v223, v223
	v_lshlrev_b32_e32 v242, 16, v190
	v_and_b32_e32 v243, 0xffff0000, v190
	v_lshlrev_b32_e32 v244, 16, v191
	v_and_b32_e32 v245, 0xffff0000, v191
	v_lshlrev_b32_e32 v246, 16, v192
	v_and_b32_e32 v247, 0xffff0000, v192
	v_lshlrev_b32_e32 v248, 16, v193
	v_and_b32_e32 v249, 0xffff0000, v193
	v_pk_mul_f32 v[242:243], v[242:243], s[86:87] op_sel_hi:[1,0]
	v_pk_mul_f32 v[244:245], v[244:245], s[86:87] op_sel_hi:[1,0]
	v_pk_mul_f32 v[246:247], v[246:247], s[86:87] op_sel_hi:[1,0]
	v_pk_mul_f32 v[248:249], v[248:249], s[86:87] op_sel_hi:[1,0]
	v_exp_f32_e32 v242, v242
	v_exp_f32_e32 v243, v243
	v_exp_f32_e32 v244, v244
	v_exp_f32_e32 v245, v245
	v_exp_f32_e32 v246, v246
	v_exp_f32_e32 v247, v247
	v_exp_f32_e32 v248, v248
	v_exp_f32_e32 v249, v249
	v_pk_add_f32 v[242:243], v[242:243], 1.0 op_sel_hi:[1,0]
	v_pk_add_f32 v[244:245], v[244:245], 1.0 op_sel_hi:[1,0]
	v_pk_add_f32 v[246:247], v[246:247], 1.0 op_sel_hi:[1,0]
	v_pk_add_f32 v[248:249], v[248:249], 1.0 op_sel_hi:[1,0]
	v_pk_mul_f32 v[216:217], v[216:217], v[242:243]
	v_pk_mul_f32 v[218:219], v[218:219], v[244:245]
	v_pk_mul_f32 v[220:221], v[220:221], v[246:247]
	v_pk_mul_f32 v[222:223], v[222:223], v[248:249]
	v_pk_mul_f32 v[70:71], v[70:71], v[216:217]
	v_pk_mul_f32 v[72:73], v[72:73], v[218:219]
	v_pk_mul_f32 v[66:67], v[66:67], v[220:221]
	v_pk_mul_f32 v[68:69], v[68:69], v[222:223]
	s_add_u32 s28, s20, 0x478000
	s_addc_u32 s29, s21, 0
	global_load_dwordx4 v[178:181], v253, s[28:29]
	global_load_dwordx4 v[182:185], v254, s[28:29]
	global_load_dwordx4 v[186:189], v253, s[28:29] offset:256
	global_load_dwordx4 v[190:193], v254, s[28:29] offset:256
	s_waitcnt vmcnt(12)
	v_lshlrev_b32_e32 v216, 16, v130
	v_and_b32_e32 v217, 0xffff0000, v130
	v_lshlrev_b32_e32 v218, 16, v131
	v_and_b32_e32 v219, 0xffff0000, v131
	v_lshlrev_b32_e32 v220, 16, v132
	v_and_b32_e32 v221, 0xffff0000, v132
	v_lshlrev_b32_e32 v222, 16, v133
	v_and_b32_e32 v223, 0xffff0000, v133
	v_pk_mul_f32 v[216:217], v[216:217], s[86:87] op_sel_hi:[1,0]
	v_pk_mul_f32 v[218:219], v[218:219], s[86:87] op_sel_hi:[1,0]
	v_pk_mul_f32 v[220:221], v[220:221], s[86:87] op_sel_hi:[1,0]
	v_pk_mul_f32 v[222:223], v[222:223], s[86:87] op_sel_hi:[1,0]
	v_exp_f32_e32 v216, v216
	v_exp_f32_e32 v217, v217
	v_exp_f32_e32 v218, v218
	v_exp_f32_e32 v219, v219
	v_exp_f32_e32 v220, v220
	v_exp_f32_e32 v221, v221
	v_exp_f32_e32 v222, v222
	v_exp_f32_e32 v223, v223
	v_pk_add_f32 v[216:217], v[216:217], 1.0 op_sel_hi:[1,0]
	v_pk_add_f32 v[218:219], v[218:219], 1.0 op_sel_hi:[1,0]
	v_pk_add_f32 v[220:221], v[220:221], 1.0 op_sel_hi:[1,0]
	v_pk_add_f32 v[222:223], v[222:223], 1.0 op_sel_hi:[1,0]
	v_rcp_f32_e32 v216, v216
	v_rcp_f32_e32 v217, v217
	v_rcp_f32_e32 v218, v218
	v_rcp_f32_e32 v219, v219
	v_rcp_f32_e32 v220, v220
	v_rcp_f32_e32 v221, v221
	v_rcp_f32_e32 v222, v222
	v_rcp_f32_e32 v223, v223
	v_lshlrev_b32_e32 v242, 16, v134
	v_and_b32_e32 v243, 0xffff0000, v134
	v_lshlrev_b32_e32 v244, 16, v135
	v_and_b32_e32 v245, 0xffff0000, v135
	v_lshlrev_b32_e32 v246, 16, v136
	v_and_b32_e32 v247, 0xffff0000, v136
	v_lshlrev_b32_e32 v248, 16, v137
	v_and_b32_e32 v249, 0xffff0000, v137
	v_pk_mul_f32 v[242:243], v[242:243], s[86:87] op_sel_hi:[1,0]
	v_pk_mul_f32 v[244:245], v[244:245], s[86:87] op_sel_hi:[1,0]
	v_pk_mul_f32 v[246:247], v[246:247], s[86:87] op_sel_hi:[1,0]
	v_pk_mul_f32 v[248:249], v[248:249], s[86:87] op_sel_hi:[1,0]
	v_exp_f32_e32 v242, v242
	v_exp_f32_e32 v243, v243
	v_exp_f32_e32 v244, v244
	v_exp_f32_e32 v245, v245
	v_exp_f32_e32 v246, v246
	v_exp_f32_e32 v247, v247
	v_exp_f32_e32 v248, v248
	v_exp_f32_e32 v249, v249
	v_pk_add_f32 v[242:243], v[242:243], 1.0 op_sel_hi:[1,0]
	v_pk_add_f32 v[244:245], v[244:245], 1.0 op_sel_hi:[1,0]
	v_pk_add_f32 v[246:247], v[246:247], 1.0 op_sel_hi:[1,0]
	v_pk_add_f32 v[248:249], v[248:249], 1.0 op_sel_hi:[1,0]
	v_pk_mul_f32 v[216:217], v[216:217], v[242:243]
	v_pk_mul_f32 v[218:219], v[218:219], v[244:245]
	v_pk_mul_f32 v[220:221], v[220:221], v[246:247]
	v_pk_mul_f32 v[222:223], v[222:223], v[248:249]
	v_pk_mul_f32 v[62:63], v[62:63], v[216:217]
	v_pk_mul_f32 v[64:65], v[64:65], v[218:219]
	v_pk_mul_f32 v[58:59], v[58:59], v[220:221]
	v_pk_mul_f32 v[60:61], v[60:61], v[222:223]
	v_lshlrev_b32_e32 v216, 16, v138
	v_and_b32_e32 v217, 0xffff0000, v138
	v_lshlrev_b32_e32 v218, 16, v139
	v_and_b32_e32 v219, 0xffff0000, v139
	v_lshlrev_b32_e32 v220, 16, v140
	v_and_b32_e32 v221, 0xffff0000, v140
	v_lshlrev_b32_e32 v222, 16, v141
	v_and_b32_e32 v223, 0xffff0000, v141
	v_pk_mul_f32 v[216:217], v[216:217], s[86:87] op_sel_hi:[1,0]
	v_pk_mul_f32 v[218:219], v[218:219], s[86:87] op_sel_hi:[1,0]
	v_pk_mul_f32 v[220:221], v[220:221], s[86:87] op_sel_hi:[1,0]
	v_pk_mul_f32 v[222:223], v[222:223], s[86:87] op_sel_hi:[1,0]
	v_exp_f32_e32 v216, v216
	v_exp_f32_e32 v217, v217
	v_exp_f32_e32 v218, v218
	v_exp_f32_e32 v219, v219
	v_exp_f32_e32 v220, v220
	v_exp_f32_e32 v221, v221
	v_exp_f32_e32 v222, v222
	v_exp_f32_e32 v223, v223
	v_pk_add_f32 v[216:217], v[216:217], 1.0 op_sel_hi:[1,0]
	v_pk_add_f32 v[218:219], v[218:219], 1.0 op_sel_hi:[1,0]
	v_pk_add_f32 v[220:221], v[220:221], 1.0 op_sel_hi:[1,0]
	v_pk_add_f32 v[222:223], v[222:223], 1.0 op_sel_hi:[1,0]
	v_rcp_f32_e32 v216, v216
	v_rcp_f32_e32 v217, v217
	v_rcp_f32_e32 v218, v218
	v_rcp_f32_e32 v219, v219
	v_rcp_f32_e32 v220, v220
	v_rcp_f32_e32 v221, v221
	v_rcp_f32_e32 v222, v222
	v_rcp_f32_e32 v223, v223
	v_lshlrev_b32_e32 v242, 16, v142
	v_and_b32_e32 v243, 0xffff0000, v142
	v_lshlrev_b32_e32 v244, 16, v143
	v_and_b32_e32 v245, 0xffff0000, v143
	v_lshlrev_b32_e32 v246, 16, v144
	v_and_b32_e32 v247, 0xffff0000, v144
	v_lshlrev_b32_e32 v248, 16, v145
	v_and_b32_e32 v249, 0xffff0000, v145
	v_pk_mul_f32 v[242:243], v[242:243], s[86:87] op_sel_hi:[1,0]
	v_pk_mul_f32 v[244:245], v[244:245], s[86:87] op_sel_hi:[1,0]
	v_pk_mul_f32 v[246:247], v[246:247], s[86:87] op_sel_hi:[1,0]
	v_pk_mul_f32 v[248:249], v[248:249], s[86:87] op_sel_hi:[1,0]
	v_exp_f32_e32 v242, v242
	v_exp_f32_e32 v243, v243
	v_exp_f32_e32 v244, v244
	v_exp_f32_e32 v245, v245
	v_exp_f32_e32 v246, v246
	v_exp_f32_e32 v247, v247
	v_exp_f32_e32 v248, v248
	v_exp_f32_e32 v249, v249
	v_pk_add_f32 v[242:243], v[242:243], 1.0 op_sel_hi:[1,0]
	v_pk_add_f32 v[244:245], v[244:245], 1.0 op_sel_hi:[1,0]
	v_pk_add_f32 v[246:247], v[246:247], 1.0 op_sel_hi:[1,0]
	v_pk_add_f32 v[248:249], v[248:249], 1.0 op_sel_hi:[1,0]
	v_pk_mul_f32 v[216:217], v[216:217], v[242:243]
	v_pk_mul_f32 v[218:219], v[218:219], v[244:245]
	v_pk_mul_f32 v[220:221], v[220:221], v[246:247]
	v_pk_mul_f32 v[222:223], v[222:223], v[248:249]
	v_pk_mul_f32 v[30:31], v[30:31], v[216:217]
	v_pk_mul_f32 v[32:33], v[32:33], v[218:219]
	v_pk_mul_f32 v[26:27], v[26:27], v[220:221]
	v_pk_mul_f32 v[28:29], v[28:29], v[222:223]
	s_waitcnt vmcnt(8)
	v_lshlrev_b32_e32 v216, 16, v146
	v_and_b32_e32 v217, 0xffff0000, v146
	v_lshlrev_b32_e32 v218, 16, v147
	v_and_b32_e32 v219, 0xffff0000, v147
	v_lshlrev_b32_e32 v220, 16, v148
	v_and_b32_e32 v221, 0xffff0000, v148
	v_lshlrev_b32_e32 v222, 16, v149
	v_and_b32_e32 v223, 0xffff0000, v149
	v_pk_mul_f32 v[216:217], v[216:217], s[86:87] op_sel_hi:[1,0]
	v_pk_mul_f32 v[218:219], v[218:219], s[86:87] op_sel_hi:[1,0]
	v_pk_mul_f32 v[220:221], v[220:221], s[86:87] op_sel_hi:[1,0]
	v_pk_mul_f32 v[222:223], v[222:223], s[86:87] op_sel_hi:[1,0]
	v_exp_f32_e32 v216, v216
	v_exp_f32_e32 v217, v217
	v_exp_f32_e32 v218, v218
	v_exp_f32_e32 v219, v219
	v_exp_f32_e32 v220, v220
	v_exp_f32_e32 v221, v221
	v_exp_f32_e32 v222, v222
	v_exp_f32_e32 v223, v223
	v_pk_add_f32 v[216:217], v[216:217], 1.0 op_sel_hi:[1,0]
	v_pk_add_f32 v[218:219], v[218:219], 1.0 op_sel_hi:[1,0]
	v_pk_add_f32 v[220:221], v[220:221], 1.0 op_sel_hi:[1,0]
	v_pk_add_f32 v[222:223], v[222:223], 1.0 op_sel_hi:[1,0]
	v_rcp_f32_e32 v216, v216
	v_rcp_f32_e32 v217, v217
	v_rcp_f32_e32 v218, v218
	v_rcp_f32_e32 v219, v219
	v_rcp_f32_e32 v220, v220
	v_rcp_f32_e32 v221, v221
	v_rcp_f32_e32 v222, v222
	v_rcp_f32_e32 v223, v223
	v_lshlrev_b32_e32 v242, 16, v150
	v_and_b32_e32 v243, 0xffff0000, v150
	v_lshlrev_b32_e32 v244, 16, v151
	v_and_b32_e32 v245, 0xffff0000, v151
	v_lshlrev_b32_e32 v246, 16, v152
	v_and_b32_e32 v247, 0xffff0000, v152
	v_lshlrev_b32_e32 v248, 16, v153
	v_and_b32_e32 v249, 0xffff0000, v153
	v_pk_mul_f32 v[242:243], v[242:243], s[86:87] op_sel_hi:[1,0]
	v_pk_mul_f32 v[244:245], v[244:245], s[86:87] op_sel_hi:[1,0]
	v_pk_mul_f32 v[246:247], v[246:247], s[86:87] op_sel_hi:[1,0]
	v_pk_mul_f32 v[248:249], v[248:249], s[86:87] op_sel_hi:[1,0]
	v_exp_f32_e32 v242, v242
	v_exp_f32_e32 v243, v243
	v_exp_f32_e32 v244, v244
	v_exp_f32_e32 v245, v245
	v_exp_f32_e32 v246, v246
	v_exp_f32_e32 v247, v247
	v_exp_f32_e32 v248, v248
	v_exp_f32_e32 v249, v249
	v_pk_add_f32 v[242:243], v[242:243], 1.0 op_sel_hi:[1,0]
	v_pk_add_f32 v[244:245], v[244:245], 1.0 op_sel_hi:[1,0]
	v_pk_add_f32 v[246:247], v[246:247], 1.0 op_sel_hi:[1,0]
	v_pk_add_f32 v[248:249], v[248:249], 1.0 op_sel_hi:[1,0]
	v_pk_mul_f32 v[216:217], v[216:217], v[242:243]
	v_pk_mul_f32 v[218:219], v[218:219], v[244:245]
	v_pk_mul_f32 v[220:221], v[220:221], v[246:247]
	v_pk_mul_f32 v[222:223], v[222:223], v[248:249]
	v_pk_mul_f32 v[54:55], v[54:55], v[216:217]
	v_pk_mul_f32 v[56:57], v[56:57], v[218:219]
	v_pk_mul_f32 v[50:51], v[50:51], v[220:221]
	v_pk_mul_f32 v[52:53], v[52:53], v[222:223]
	v_lshlrev_b32_e32 v216, 16, v154
	v_and_b32_e32 v217, 0xffff0000, v154
	v_lshlrev_b32_e32 v218, 16, v155
	v_and_b32_e32 v219, 0xffff0000, v155
	v_lshlrev_b32_e32 v220, 16, v156
	v_and_b32_e32 v221, 0xffff0000, v156
	v_lshlrev_b32_e32 v222, 16, v157
	v_and_b32_e32 v223, 0xffff0000, v157
	v_pk_mul_f32 v[216:217], v[216:217], s[86:87] op_sel_hi:[1,0]
	v_pk_mul_f32 v[218:219], v[218:219], s[86:87] op_sel_hi:[1,0]
	v_pk_mul_f32 v[220:221], v[220:221], s[86:87] op_sel_hi:[1,0]
	v_pk_mul_f32 v[222:223], v[222:223], s[86:87] op_sel_hi:[1,0]
	v_exp_f32_e32 v216, v216
	v_exp_f32_e32 v217, v217
	v_exp_f32_e32 v218, v218
	v_exp_f32_e32 v219, v219
	v_exp_f32_e32 v220, v220
	v_exp_f32_e32 v221, v221
	v_exp_f32_e32 v222, v222
	v_exp_f32_e32 v223, v223
	v_pk_add_f32 v[216:217], v[216:217], 1.0 op_sel_hi:[1,0]
	v_pk_add_f32 v[218:219], v[218:219], 1.0 op_sel_hi:[1,0]
	v_pk_add_f32 v[220:221], v[220:221], 1.0 op_sel_hi:[1,0]
	v_pk_add_f32 v[222:223], v[222:223], 1.0 op_sel_hi:[1,0]
	v_rcp_f32_e32 v216, v216
	v_rcp_f32_e32 v217, v217
	v_rcp_f32_e32 v218, v218
	v_rcp_f32_e32 v219, v219
	v_rcp_f32_e32 v220, v220
	v_rcp_f32_e32 v221, v221
	v_rcp_f32_e32 v222, v222
	v_rcp_f32_e32 v223, v223
	v_lshlrev_b32_e32 v242, 16, v158
	v_and_b32_e32 v243, 0xffff0000, v158
	v_lshlrev_b32_e32 v244, 16, v159
	v_and_b32_e32 v245, 0xffff0000, v159
	v_lshlrev_b32_e32 v246, 16, v160
	v_and_b32_e32 v247, 0xffff0000, v160
	v_lshlrev_b32_e32 v248, 16, v161
	v_and_b32_e32 v249, 0xffff0000, v161
	v_pk_mul_f32 v[242:243], v[242:243], s[86:87] op_sel_hi:[1,0]
	v_pk_mul_f32 v[244:245], v[244:245], s[86:87] op_sel_hi:[1,0]
	v_pk_mul_f32 v[246:247], v[246:247], s[86:87] op_sel_hi:[1,0]
	v_pk_mul_f32 v[248:249], v[248:249], s[86:87] op_sel_hi:[1,0]
	v_exp_f32_e32 v242, v242
	v_exp_f32_e32 v243, v243
	v_exp_f32_e32 v244, v244
	v_exp_f32_e32 v245, v245
	v_exp_f32_e32 v246, v246
	v_exp_f32_e32 v247, v247
	v_exp_f32_e32 v248, v248
	v_exp_f32_e32 v249, v249
	v_pk_add_f32 v[242:243], v[242:243], 1.0 op_sel_hi:[1,0]
	v_pk_add_f32 v[244:245], v[244:245], 1.0 op_sel_hi:[1,0]
	v_pk_add_f32 v[246:247], v[246:247], 1.0 op_sel_hi:[1,0]
	v_pk_add_f32 v[248:249], v[248:249], 1.0 op_sel_hi:[1,0]
	v_pk_mul_f32 v[216:217], v[216:217], v[242:243]
	v_pk_mul_f32 v[218:219], v[218:219], v[244:245]
	v_pk_mul_f32 v[220:221], v[220:221], v[246:247]
	v_pk_mul_f32 v[222:223], v[222:223], v[248:249]
	v_pk_mul_f32 v[22:23], v[22:23], v[216:217]
	v_pk_mul_f32 v[24:25], v[24:25], v[218:219]
	v_pk_mul_f32 v[18:19], v[18:19], v[220:221]
	v_pk_mul_f32 v[20:21], v[20:21], v[222:223]
	s_waitcnt vmcnt(4)
	v_lshlrev_b32_e32 v216, 16, v162
	v_and_b32_e32 v217, 0xffff0000, v162
	v_lshlrev_b32_e32 v218, 16, v163
	v_and_b32_e32 v219, 0xffff0000, v163
	v_lshlrev_b32_e32 v220, 16, v164
	v_and_b32_e32 v221, 0xffff0000, v164
	v_lshlrev_b32_e32 v222, 16, v165
	v_and_b32_e32 v223, 0xffff0000, v165
	v_pk_mul_f32 v[216:217], v[216:217], s[86:87] op_sel_hi:[1,0]
	v_pk_mul_f32 v[218:219], v[218:219], s[86:87] op_sel_hi:[1,0]
	v_pk_mul_f32 v[220:221], v[220:221], s[86:87] op_sel_hi:[1,0]
	v_pk_mul_f32 v[222:223], v[222:223], s[86:87] op_sel_hi:[1,0]
	v_exp_f32_e32 v216, v216
	v_exp_f32_e32 v217, v217
	v_exp_f32_e32 v218, v218
	v_exp_f32_e32 v219, v219
	v_exp_f32_e32 v220, v220
	v_exp_f32_e32 v221, v221
	v_exp_f32_e32 v222, v222
	v_exp_f32_e32 v223, v223
	v_pk_add_f32 v[216:217], v[216:217], 1.0 op_sel_hi:[1,0]
	v_pk_add_f32 v[218:219], v[218:219], 1.0 op_sel_hi:[1,0]
	v_pk_add_f32 v[220:221], v[220:221], 1.0 op_sel_hi:[1,0]
	v_pk_add_f32 v[222:223], v[222:223], 1.0 op_sel_hi:[1,0]
	v_rcp_f32_e32 v216, v216
	v_rcp_f32_e32 v217, v217
	v_rcp_f32_e32 v218, v218
	v_rcp_f32_e32 v219, v219
	v_rcp_f32_e32 v220, v220
	v_rcp_f32_e32 v221, v221
	v_rcp_f32_e32 v222, v222
	v_rcp_f32_e32 v223, v223
	v_lshlrev_b32_e32 v242, 16, v166
	v_and_b32_e32 v243, 0xffff0000, v166
	v_lshlrev_b32_e32 v244, 16, v167
	v_and_b32_e32 v245, 0xffff0000, v167
	v_lshlrev_b32_e32 v246, 16, v168
	v_and_b32_e32 v247, 0xffff0000, v168
	v_lshlrev_b32_e32 v248, 16, v169
	v_and_b32_e32 v249, 0xffff0000, v169
	v_pk_mul_f32 v[242:243], v[242:243], s[86:87] op_sel_hi:[1,0]
	v_pk_mul_f32 v[244:245], v[244:245], s[86:87] op_sel_hi:[1,0]
	v_pk_mul_f32 v[246:247], v[246:247], s[86:87] op_sel_hi:[1,0]
	v_pk_mul_f32 v[248:249], v[248:249], s[86:87] op_sel_hi:[1,0]
	v_exp_f32_e32 v242, v242
	v_exp_f32_e32 v243, v243
	v_exp_f32_e32 v244, v244
	v_exp_f32_e32 v245, v245
	v_exp_f32_e32 v246, v246
	v_exp_f32_e32 v247, v247
	v_exp_f32_e32 v248, v248
	v_exp_f32_e32 v249, v249
	v_pk_add_f32 v[242:243], v[242:243], 1.0 op_sel_hi:[1,0]
	v_pk_add_f32 v[244:245], v[244:245], 1.0 op_sel_hi:[1,0]
	v_pk_add_f32 v[246:247], v[246:247], 1.0 op_sel_hi:[1,0]
	v_pk_add_f32 v[248:249], v[248:249], 1.0 op_sel_hi:[1,0]
	v_pk_mul_f32 v[216:217], v[216:217], v[242:243]
	v_pk_mul_f32 v[218:219], v[218:219], v[244:245]
	v_pk_mul_f32 v[220:221], v[220:221], v[246:247]
	v_pk_mul_f32 v[222:223], v[222:223], v[248:249]
	v_pk_mul_f32 v[46:47], v[46:47], v[216:217]
	v_pk_mul_f32 v[48:49], v[48:49], v[218:219]
	v_pk_mul_f32 v[42:43], v[42:43], v[220:221]
	v_pk_mul_f32 v[44:45], v[44:45], v[222:223]
	v_lshlrev_b32_e32 v216, 16, v170
	v_and_b32_e32 v217, 0xffff0000, v170
	v_lshlrev_b32_e32 v218, 16, v171
	v_and_b32_e32 v219, 0xffff0000, v171
	v_lshlrev_b32_e32 v220, 16, v172
	v_and_b32_e32 v221, 0xffff0000, v172
	v_lshlrev_b32_e32 v222, 16, v173
	v_and_b32_e32 v223, 0xffff0000, v173
	v_pk_mul_f32 v[216:217], v[216:217], s[86:87] op_sel_hi:[1,0]
	v_pk_mul_f32 v[218:219], v[218:219], s[86:87] op_sel_hi:[1,0]
	v_pk_mul_f32 v[220:221], v[220:221], s[86:87] op_sel_hi:[1,0]
	v_pk_mul_f32 v[222:223], v[222:223], s[86:87] op_sel_hi:[1,0]
	v_exp_f32_e32 v216, v216
	v_exp_f32_e32 v217, v217
	v_exp_f32_e32 v218, v218
	v_exp_f32_e32 v219, v219
	v_exp_f32_e32 v220, v220
	v_exp_f32_e32 v221, v221
	v_exp_f32_e32 v222, v222
	v_exp_f32_e32 v223, v223
	v_pk_add_f32 v[216:217], v[216:217], 1.0 op_sel_hi:[1,0]
	v_pk_add_f32 v[218:219], v[218:219], 1.0 op_sel_hi:[1,0]
	v_pk_add_f32 v[220:221], v[220:221], 1.0 op_sel_hi:[1,0]
	v_pk_add_f32 v[222:223], v[222:223], 1.0 op_sel_hi:[1,0]
	v_rcp_f32_e32 v216, v216
	v_rcp_f32_e32 v217, v217
	v_rcp_f32_e32 v218, v218
	v_rcp_f32_e32 v219, v219
	v_rcp_f32_e32 v220, v220
	v_rcp_f32_e32 v221, v221
	v_rcp_f32_e32 v222, v222
	v_rcp_f32_e32 v223, v223
	v_lshlrev_b32_e32 v242, 16, v174
	v_and_b32_e32 v243, 0xffff0000, v174
	v_lshlrev_b32_e32 v244, 16, v175
	v_and_b32_e32 v245, 0xffff0000, v175
	v_lshlrev_b32_e32 v246, 16, v176
	v_and_b32_e32 v247, 0xffff0000, v176
	v_lshlrev_b32_e32 v248, 16, v177
	v_and_b32_e32 v249, 0xffff0000, v177
	v_pk_mul_f32 v[242:243], v[242:243], s[86:87] op_sel_hi:[1,0]
	v_pk_mul_f32 v[244:245], v[244:245], s[86:87] op_sel_hi:[1,0]
	v_pk_mul_f32 v[246:247], v[246:247], s[86:87] op_sel_hi:[1,0]
	v_pk_mul_f32 v[248:249], v[248:249], s[86:87] op_sel_hi:[1,0]
	v_exp_f32_e32 v242, v242
	v_exp_f32_e32 v243, v243
	v_exp_f32_e32 v244, v244
	v_exp_f32_e32 v245, v245
	v_exp_f32_e32 v246, v246
	v_exp_f32_e32 v247, v247
	v_exp_f32_e32 v248, v248
	v_exp_f32_e32 v249, v249
	v_pk_add_f32 v[242:243], v[242:243], 1.0 op_sel_hi:[1,0]
	v_pk_add_f32 v[244:245], v[244:245], 1.0 op_sel_hi:[1,0]
	v_pk_add_f32 v[246:247], v[246:247], 1.0 op_sel_hi:[1,0]
	v_pk_add_f32 v[248:249], v[248:249], 1.0 op_sel_hi:[1,0]
	v_pk_mul_f32 v[216:217], v[216:217], v[242:243]
	v_pk_mul_f32 v[218:219], v[218:219], v[244:245]
	v_pk_mul_f32 v[220:221], v[220:221], v[246:247]
	v_pk_mul_f32 v[222:223], v[222:223], v[248:249]
	v_pk_mul_f32 v[14:15], v[14:15], v[216:217]
	v_pk_mul_f32 v[16:17], v[16:17], v[218:219]
	v_pk_mul_f32 v[10:11], v[10:11], v[220:221]
	v_pk_mul_f32 v[12:13], v[12:13], v[222:223]
	s_waitcnt vmcnt(0)
	v_lshlrev_b32_e32 v216, 16, v178
	v_and_b32_e32 v217, 0xffff0000, v178
	v_lshlrev_b32_e32 v218, 16, v179
	v_and_b32_e32 v219, 0xffff0000, v179
	v_lshlrev_b32_e32 v220, 16, v180
	v_and_b32_e32 v221, 0xffff0000, v180
	v_lshlrev_b32_e32 v222, 16, v181
	v_and_b32_e32 v223, 0xffff0000, v181
	v_pk_mul_f32 v[216:217], v[216:217], s[86:87] op_sel_hi:[1,0]
	v_pk_mul_f32 v[218:219], v[218:219], s[86:87] op_sel_hi:[1,0]
	v_pk_mul_f32 v[220:221], v[220:221], s[86:87] op_sel_hi:[1,0]
	v_pk_mul_f32 v[222:223], v[222:223], s[86:87] op_sel_hi:[1,0]
	v_exp_f32_e32 v216, v216
	v_exp_f32_e32 v217, v217
	v_exp_f32_e32 v218, v218
	v_exp_f32_e32 v219, v219
	v_exp_f32_e32 v220, v220
	v_exp_f32_e32 v221, v221
	v_exp_f32_e32 v222, v222
	v_exp_f32_e32 v223, v223
	v_pk_add_f32 v[216:217], v[216:217], 1.0 op_sel_hi:[1,0]
	v_pk_add_f32 v[218:219], v[218:219], 1.0 op_sel_hi:[1,0]
	v_pk_add_f32 v[220:221], v[220:221], 1.0 op_sel_hi:[1,0]
	v_pk_add_f32 v[222:223], v[222:223], 1.0 op_sel_hi:[1,0]
	v_rcp_f32_e32 v216, v216
	v_rcp_f32_e32 v217, v217
	v_rcp_f32_e32 v218, v218
	v_rcp_f32_e32 v219, v219
	v_rcp_f32_e32 v220, v220
	v_rcp_f32_e32 v221, v221
	v_rcp_f32_e32 v222, v222
	v_rcp_f32_e32 v223, v223
	v_lshlrev_b32_e32 v242, 16, v182
	v_and_b32_e32 v243, 0xffff0000, v182
	v_lshlrev_b32_e32 v244, 16, v183
	v_and_b32_e32 v245, 0xffff0000, v183
	v_lshlrev_b32_e32 v246, 16, v184
	v_and_b32_e32 v247, 0xffff0000, v184
	v_lshlrev_b32_e32 v248, 16, v185
	v_and_b32_e32 v249, 0xffff0000, v185
	v_pk_mul_f32 v[242:243], v[242:243], s[86:87] op_sel_hi:[1,0]
	v_pk_mul_f32 v[244:245], v[244:245], s[86:87] op_sel_hi:[1,0]
	v_pk_mul_f32 v[246:247], v[246:247], s[86:87] op_sel_hi:[1,0]
	v_pk_mul_f32 v[248:249], v[248:249], s[86:87] op_sel_hi:[1,0]
	v_exp_f32_e32 v242, v242
	v_exp_f32_e32 v243, v243
	v_exp_f32_e32 v244, v244
	v_exp_f32_e32 v245, v245
	v_exp_f32_e32 v246, v246
	v_exp_f32_e32 v247, v247
	v_exp_f32_e32 v248, v248
	v_exp_f32_e32 v249, v249
	v_pk_add_f32 v[242:243], v[242:243], 1.0 op_sel_hi:[1,0]
	v_pk_add_f32 v[244:245], v[244:245], 1.0 op_sel_hi:[1,0]
	v_pk_add_f32 v[246:247], v[246:247], 1.0 op_sel_hi:[1,0]
	v_pk_add_f32 v[248:249], v[248:249], 1.0 op_sel_hi:[1,0]
	v_pk_mul_f32 v[216:217], v[216:217], v[242:243]
	v_pk_mul_f32 v[218:219], v[218:219], v[244:245]
	v_pk_mul_f32 v[220:221], v[220:221], v[246:247]
	v_pk_mul_f32 v[222:223], v[222:223], v[248:249]
	v_pk_mul_f32 v[38:39], v[38:39], v[216:217]
	v_pk_mul_f32 v[40:41], v[40:41], v[218:219]
	v_pk_mul_f32 v[34:35], v[34:35], v[220:221]
	v_pk_mul_f32 v[36:37], v[36:37], v[222:223]
	v_lshlrev_b32_e32 v216, 16, v186
	v_and_b32_e32 v217, 0xffff0000, v186
	v_lshlrev_b32_e32 v218, 16, v187
	v_and_b32_e32 v219, 0xffff0000, v187
	v_lshlrev_b32_e32 v220, 16, v188
	v_and_b32_e32 v221, 0xffff0000, v188
	v_lshlrev_b32_e32 v222, 16, v189
	v_and_b32_e32 v223, 0xffff0000, v189
	v_pk_mul_f32 v[216:217], v[216:217], s[86:87] op_sel_hi:[1,0]
	v_pk_mul_f32 v[218:219], v[218:219], s[86:87] op_sel_hi:[1,0]
	v_pk_mul_f32 v[220:221], v[220:221], s[86:87] op_sel_hi:[1,0]
	v_pk_mul_f32 v[222:223], v[222:223], s[86:87] op_sel_hi:[1,0]
	v_exp_f32_e32 v216, v216
	v_exp_f32_e32 v217, v217
	v_exp_f32_e32 v218, v218
	v_exp_f32_e32 v219, v219
	v_exp_f32_e32 v220, v220
	v_exp_f32_e32 v221, v221
	v_exp_f32_e32 v222, v222
	v_exp_f32_e32 v223, v223
	v_pk_add_f32 v[216:217], v[216:217], 1.0 op_sel_hi:[1,0]
	v_pk_add_f32 v[218:219], v[218:219], 1.0 op_sel_hi:[1,0]
	v_pk_add_f32 v[220:221], v[220:221], 1.0 op_sel_hi:[1,0]
	v_pk_add_f32 v[222:223], v[222:223], 1.0 op_sel_hi:[1,0]
	v_rcp_f32_e32 v216, v216
	v_rcp_f32_e32 v217, v217
	v_rcp_f32_e32 v218, v218
	v_rcp_f32_e32 v219, v219
	v_rcp_f32_e32 v220, v220
	v_rcp_f32_e32 v221, v221
	v_rcp_f32_e32 v222, v222
	v_rcp_f32_e32 v223, v223
	v_lshlrev_b32_e32 v242, 16, v190
	v_and_b32_e32 v243, 0xffff0000, v190
	v_lshlrev_b32_e32 v244, 16, v191
	v_and_b32_e32 v245, 0xffff0000, v191
	v_lshlrev_b32_e32 v246, 16, v192
	v_and_b32_e32 v247, 0xffff0000, v192
	v_lshlrev_b32_e32 v248, 16, v193
	v_and_b32_e32 v249, 0xffff0000, v193
	v_pk_mul_f32 v[242:243], v[242:243], s[86:87] op_sel_hi:[1,0]
	v_pk_mul_f32 v[244:245], v[244:245], s[86:87] op_sel_hi:[1,0]
	v_pk_mul_f32 v[246:247], v[246:247], s[86:87] op_sel_hi:[1,0]
	v_pk_mul_f32 v[248:249], v[248:249], s[86:87] op_sel_hi:[1,0]
	v_exp_f32_e32 v242, v242
	v_exp_f32_e32 v243, v243
	v_exp_f32_e32 v244, v244
	v_exp_f32_e32 v245, v245
	v_exp_f32_e32 v246, v246
	v_exp_f32_e32 v247, v247
	v_exp_f32_e32 v248, v248
	v_exp_f32_e32 v249, v249
	v_pk_add_f32 v[242:243], v[242:243], 1.0 op_sel_hi:[1,0]
	v_pk_add_f32 v[244:245], v[244:245], 1.0 op_sel_hi:[1,0]
	v_pk_add_f32 v[246:247], v[246:247], 1.0 op_sel_hi:[1,0]
	v_pk_add_f32 v[248:249], v[248:249], 1.0 op_sel_hi:[1,0]
	v_pk_mul_f32 v[216:217], v[216:217], v[242:243]
	v_pk_mul_f32 v[218:219], v[218:219], v[244:245]
	v_pk_mul_f32 v[220:221], v[220:221], v[246:247]
	v_pk_mul_f32 v[222:223], v[222:223], v[248:249]
	v_pk_mul_f32 v[6:7], v[6:7], v[216:217]
	v_pk_mul_f32 v[8:9], v[8:9], v[218:219]
	v_pk_mul_f32 v[2:3], v[2:3], v[220:221]
	v_pk_mul_f32 v[4:5], v[4:5], v[222:223]
	s_branch .Lem_done

.LBB0_504:
	v_or_b32_e32 v130, 0x10000, v163
	v_add_u32_e32 v134, 0x10400, v163
	v_add_u32_e32 v150, 0x10800, v163
	v_add_u32_e32 v154, 0x10c00, v163
	ds_read_b128 v[130:133], v130
	ds_read_b128 v[134:137], v134
	ds_read_b128 v[150:153], v150
	ds_read_b128 v[154:157], v154
	s_add_u32 s10, s52, 0xfff80080
	s_addc_u32 s11, s53, -1
	s_cmp_eq_u32 s29, 28
	s_cselect_b32 s11, s9, s11
	s_cselect_b32 s10, s8, s10
	s_cselect_b32 s55, s35, s7
	s_cselect_b32 s54, s34, s5
	v_lshl_add_u64 v[206:207], s[52:53], 0, v[146:147]
	s_add_i32 m0, s42, 0xc000
	ds_read_b128 v[158:161], v162
	ds_read_b128 v[166:169], v162 offset:1024
	ds_read_b128 v[170:173], v162 offset:2048
	ds_read_b128 v[174:177], v162 offset:3072
	ds_read_b128 v[178:181], v162 offset:4096
	ds_read_b128 v[182:185], v162 offset:5120
	ds_read_b128 v[186:189], v162 offset:6144
	ds_read_b128 v[190:193], v162 offset:7168
	global_load_lds_dwordx4 v[206:207], off
	v_lshl_add_u64 v[206:207], s[52:53], 0, v[148:149]
	s_add_i32 m0, s42, 0xe000
	s_nop 0
	global_load_lds_dwordx4 v[206:207], off
	s_waitcnt lgkmcnt(8)
	s_barrier
	s_waitcnt lgkmcnt(0)
	s_setprio 1
	v_mfma_f32_16x16x32_bf16 v[126:129], v[130:133], v[158:161], v[126:129]
	v_mfma_f32_16x16x32_bf16 v[122:125], v[150:153], v[158:161], v[122:125]
	v_mfma_f32_16x16x32_bf16 v[118:121], v[130:133], v[170:173], v[118:121]
	v_mfma_f32_16x16x32_bf16 v[114:117], v[150:153], v[170:173], v[114:117]
	v_mfma_f32_16x16x32_bf16 v[110:113], v[130:133], v[178:181], v[110:113]
	v_mfma_f32_16x16x32_bf16 v[106:109], v[150:153], v[178:181], v[106:109]
	v_mfma_f32_16x16x32_bf16 v[102:105], v[130:133], v[186:189], v[102:105]
	v_mfma_f32_16x16x32_bf16 v[98:101], v[150:153], v[186:189], v[98:101]
	v_mfma_f32_16x16x32_bf16 v[126:129], v[134:137], v[166:169], v[126:129]
	v_mfma_f32_16x16x32_bf16 v[122:125], v[154:157], v[166:169], v[122:125]
	v_mfma_f32_16x16x32_bf16 v[118:121], v[134:137], v[174:177], v[118:121]
	v_mfma_f32_16x16x32_bf16 v[114:117], v[154:157], v[174:177], v[114:117]
	v_mfma_f32_16x16x32_bf16 v[110:113], v[134:137], v[182:185], v[110:113]
	v_mfma_f32_16x16x32_bf16 v[106:109], v[154:157], v[182:185], v[106:109]
	v_mfma_f32_16x16x32_bf16 v[102:105], v[134:137], v[190:193], v[102:105]
	v_mfma_f32_16x16x32_bf16 v[98:101], v[154:157], v[190:193], v[98:101]
	s_setprio 0
	s_barrier
	v_or_b32_e32 v165, 0x14000, v163
	s_mov_b32 m0, s41
	v_add_u32_e32 v197, 0x14400, v163
	ds_read_b128 v[206:209], v165
	ds_read_b128 v[210:213], v197
	v_add_u32_e32 v165, 0x14800, v163
	v_lshl_add_u64 v[222:223], s[54:55], 0, v[194:195]
	v_add_u32_e32 v197, 0x14c00, v163
	ds_read_b128 v[214:217], v165
	ds_read_b128 v[218:221], v197
	global_load_lds_dwordx4 v[222:223], off
	v_lshl_add_u64 v[224:225], s[54:55], 0, v[138:139]
	s_mov_b32 m0, s57
	s_nop 0
	global_load_lds_dwordx4 v[224:225], off
	s_barrier
	s_waitcnt lgkmcnt(0)
	s_setprio 1
	v_mfma_f32_16x16x32_bf16 v[62:65], v[206:209], v[158:161], v[62:65]
	v_mfma_f32_16x16x32_bf16 v[58:61], v[214:217], v[158:161], v[58:61]
	v_mfma_f32_16x16x32_bf16 v[54:57], v[206:209], v[170:173], v[54:57]
	v_mfma_f32_16x16x32_bf16 v[46:49], v[214:217], v[170:173], v[46:49]
	v_mfma_f32_16x16x32_bf16 v[50:53], v[206:209], v[178:181], v[50:53]
	v_mfma_f32_16x16x32_bf16 v[42:45], v[214:217], v[178:181], v[42:45]
	v_mfma_f32_16x16x32_bf16 v[38:41], v[206:209], v[186:189], v[38:41]
	v_mfma_f32_16x16x32_bf16 v[34:37], v[214:217], v[186:189], v[34:37]
	v_mfma_f32_16x16x32_bf16 v[62:65], v[210:213], v[166:169], v[62:65]
	v_mfma_f32_16x16x32_bf16 v[58:61], v[218:221], v[166:169], v[58:61]
	v_mfma_f32_16x16x32_bf16 v[54:57], v[210:213], v[174:177], v[54:57]
	v_mfma_f32_16x16x32_bf16 v[46:49], v[218:221], v[174:177], v[46:49]
	v_mfma_f32_16x16x32_bf16 v[50:53], v[210:213], v[182:185], v[50:53]
	v_mfma_f32_16x16x32_bf16 v[42:45], v[218:221], v[182:185], v[42:45]
	v_mfma_f32_16x16x32_bf16 v[38:41], v[210:213], v[190:193], v[38:41]
	v_mfma_f32_16x16x32_bf16 v[34:37], v[218:221], v[190:193], v[34:37]
	s_setprio 0
	s_mov_b32 m0, s42
	v_lshl_add_u64 v[226:227], s[10:11], 0, v[142:143]
	s_barrier
	ds_read_b128 v[158:161], v162 offset:16384
	ds_read_b128 v[166:169], v162 offset:17408
	ds_read_b128 v[170:173], v162 offset:18432
	ds_read_b128 v[174:177], v162 offset:19456
	ds_read_b128 v[178:181], v162 offset:20480
	ds_read_b128 v[182:185], v162 offset:21504
	ds_read_b128 v[186:189], v162 offset:22528
	ds_read_b128 v[190:193], v162 offset:23552
	global_load_lds_dwordx4 v[226:227], off
	v_lshl_add_u64 v[228:229], s[10:11], 0, v[140:141]
	s_mov_b32 m0, s58
	s_nop 0
	global_load_lds_dwordx4 v[228:229], off
	s_barrier
	s_waitcnt lgkmcnt(0)
	s_setprio 1
	v_mfma_f32_16x16x32_bf16 v[94:97], v[130:133], v[158:161], v[94:97]
	v_mfma_f32_16x16x32_bf16 v[90:93], v[150:153], v[158:161], v[90:93]
	v_mfma_f32_16x16x32_bf16 v[86:89], v[130:133], v[170:173], v[86:89]
	v_mfma_f32_16x16x32_bf16 v[82:85], v[150:153], v[170:173], v[82:85]
	v_mfma_f32_16x16x32_bf16 v[78:81], v[130:133], v[178:181], v[78:81]
	v_mfma_f32_16x16x32_bf16 v[74:77], v[150:153], v[178:181], v[74:77]
	v_mfma_f32_16x16x32_bf16 v[70:73], v[130:133], v[186:189], v[70:73]
	v_mfma_f32_16x16x32_bf16 v[66:69], v[150:153], v[186:189], v[66:69]
	v_mfma_f32_16x16x32_bf16 v[94:97], v[134:137], v[166:169], v[94:97]
	v_mfma_f32_16x16x32_bf16 v[90:93], v[154:157], v[166:169], v[90:93]
	v_mfma_f32_16x16x32_bf16 v[86:89], v[134:137], v[174:177], v[86:89]
	v_mfma_f32_16x16x32_bf16 v[82:85], v[154:157], v[174:177], v[82:85]
	v_mfma_f32_16x16x32_bf16 v[78:81], v[134:137], v[182:185], v[78:81]
	v_mfma_f32_16x16x32_bf16 v[74:77], v[154:157], v[182:185], v[74:77]
	v_mfma_f32_16x16x32_bf16 v[70:73], v[134:137], v[190:193], v[70:73]
	v_mfma_f32_16x16x32_bf16 v[66:69], v[154:157], v[190:193], v[66:69]
	s_setprio 0
	s_barrier
	s_add_u32 s86, s54, 0x80000
	s_addc_u32 s87, s55, 0
	s_mov_b32 m0, s59
	v_lshl_add_u64 v[130:131], s[86:87], 0, v[194:195]
	global_load_lds_dwordx4 v[130:131], off
	v_lshl_add_u64 v[130:131], s[86:87], 0, v[138:139]
	s_mov_b32 m0, s60
	s_nop 0
	global_load_lds_dwordx4 v[130:131], off
	s_waitcnt vmcnt(6)
	s_barrier
	s_setprio 1
	v_mfma_f32_16x16x32_bf16 v[30:33], v[206:209], v[158:161], v[30:33]
	v_mfma_f32_16x16x32_bf16 v[18:21], v[214:217], v[158:161], v[18:21]
	v_mfma_f32_16x16x32_bf16 v[26:29], v[206:209], v[170:173], v[26:29]
	v_mfma_f32_16x16x32_bf16 v[14:17], v[214:217], v[170:173], v[14:17]
	v_mfma_f32_16x16x32_bf16 v[22:25], v[206:209], v[178:181], v[22:25]
	v_mfma_f32_16x16x32_bf16 v[6:9], v[214:217], v[178:181], v[6:9]
	v_mfma_f32_16x16x32_bf16 v[10:13], v[206:209], v[186:189], v[10:13]
	v_mfma_f32_16x16x32_bf16 v[2:5], v[214:217], v[186:189], v[2:5]
	v_mfma_f32_16x16x32_bf16 v[30:33], v[210:213], v[166:169], v[30:33]
	v_mfma_f32_16x16x32_bf16 v[18:21], v[218:221], v[166:169], v[18:21]
	v_mfma_f32_16x16x32_bf16 v[26:29], v[210:213], v[174:177], v[26:29]
	v_mfma_f32_16x16x32_bf16 v[14:17], v[218:221], v[174:177], v[14:17]
	v_mfma_f32_16x16x32_bf16 v[22:25], v[210:213], v[182:185], v[22:25]
	v_mfma_f32_16x16x32_bf16 v[6:9], v[218:221], v[182:185], v[6:9]
	v_mfma_f32_16x16x32_bf16 v[10:13], v[210:213], v[190:193], v[10:13]
	v_mfma_f32_16x16x32_bf16 v[2:5], v[218:221], v[190:193], v[2:5]
	s_setprio 0
	v_or_b32_e32 v130, 0x18000, v163
	v_add_u32_e32 v134, 0x18400, v163
	v_add_u32_e32 v150, 0x18800, v163
	v_add_u32_e32 v154, 0x18c00, v163
	s_barrier
	ds_read_b128 v[130:133], v130
	ds_read_b128 v[134:137], v134
	ds_read_b128 v[150:153], v150
	ds_read_b128 v[154:157], v154
	s_add_u32 s10, s10, 0x80000
	s_addc_u32 s11, s11, 0
	s_mov_b32 m0, s61
	v_lshl_add_u64 v[206:207], s[10:11], 0, v[142:143]
	ds_read_b128 v[158:161], v162 offset:32768
	ds_read_b128 v[166:169], v162 offset:33792
	ds_read_b128 v[170:173], v162 offset:34816
	ds_read_b128 v[174:177], v162 offset:35840
	ds_read_b128 v[178:181], v162 offset:36864
	ds_read_b128 v[182:185], v162 offset:37888
	ds_read_b128 v[186:189], v162 offset:38912
	ds_read_b128 v[190:193], v162 offset:39936
	global_load_lds_dwordx4 v[206:207], off
	v_lshl_add_u64 v[206:207], s[10:11], 0, v[140:141]
	s_mov_b32 m0, s62
	s_nop 0
	global_load_lds_dwordx4 v[206:207], off
	s_waitcnt lgkmcnt(8)
	s_barrier
	s_waitcnt lgkmcnt(0)
	s_setprio 1
	v_mfma_f32_16x16x32_bf16 v[126:129], v[130:133], v[158:161], v[126:129]
	v_mfma_f32_16x16x32_bf16 v[122:125], v[150:153], v[158:161], v[122:125]
	v_mfma_f32_16x16x32_bf16 v[118:121], v[130:133], v[170:173], v[118:121]
	v_mfma_f32_16x16x32_bf16 v[114:117], v[150:153], v[170:173], v[114:117]
	v_mfma_f32_16x16x32_bf16 v[110:113], v[130:133], v[178:181], v[110:113]
	v_mfma_f32_16x16x32_bf16 v[106:109], v[150:153], v[178:181], v[106:109]
	v_mfma_f32_16x16x32_bf16 v[102:105], v[130:133], v[186:189], v[102:105]
	v_mfma_f32_16x16x32_bf16 v[98:101], v[150:153], v[186:189], v[98:101]
	v_mfma_f32_16x16x32_bf16 v[126:129], v[134:137], v[166:169], v[126:129]
	v_mfma_f32_16x16x32_bf16 v[122:125], v[154:157], v[166:169], v[122:125]
	v_mfma_f32_16x16x32_bf16 v[118:121], v[134:137], v[174:177], v[118:121]
	v_mfma_f32_16x16x32_bf16 v[114:117], v[154:157], v[174:177], v[114:117]
	v_mfma_f32_16x16x32_bf16 v[110:113], v[134:137], v[182:185], v[110:113]
	v_mfma_f32_16x16x32_bf16 v[106:109], v[154:157], v[182:185], v[106:109]
	v_mfma_f32_16x16x32_bf16 v[102:105], v[134:137], v[190:193], v[102:105]
	v_mfma_f32_16x16x32_bf16 v[98:101], v[154:157], v[190:193], v[98:101]
	s_setprio 0
	s_barrier
	v_or_b32_e32 v165, 0x1c000, v163
	s_mov_b32 m0, s70
	v_add_u32_e32 v197, 0x1c400, v163
	ds_read_b128 v[206:209], v165
	ds_read_b128 v[210:213], v197
	v_add_u32_e32 v165, 0x1c800, v163
	v_lshl_add_u64 v[222:223], v[222:223], 0, s[76:77]
	v_add_u32_e32 v197, 0x1cc00, v163
	ds_read_b128 v[214:217], v165
	ds_read_b128 v[218:221], v197
	global_load_lds_dwordx4 v[222:223], off
	v_lshl_add_u64 v[222:223], v[224:225], 0, s[76:77]
	s_mov_b32 m0, s71
	s_nop 0
	global_load_lds_dwordx4 v[222:223], off
	s_barrier
	s_waitcnt lgkmcnt(0)
	s_setprio 1
	v_mfma_f32_16x16x32_bf16 v[62:65], v[206:209], v[158:161], v[62:65]
	v_mfma_f32_16x16x32_bf16 v[58:61], v[214:217], v[158:161], v[58:61]
	v_mfma_f32_16x16x32_bf16 v[54:57], v[206:209], v[170:173], v[54:57]
	v_mfma_f32_16x16x32_bf16 v[46:49], v[214:217], v[170:173], v[46:49]
	v_mfma_f32_16x16x32_bf16 v[50:53], v[206:209], v[178:181], v[50:53]
	v_mfma_f32_16x16x32_bf16 v[42:45], v[214:217], v[178:181], v[42:45]
	v_mfma_f32_16x16x32_bf16 v[38:41], v[206:209], v[186:189], v[38:41]
	v_mfma_f32_16x16x32_bf16 v[34:37], v[214:217], v[186:189], v[34:37]
	v_mfma_f32_16x16x32_bf16 v[62:65], v[210:213], v[166:169], v[62:65]
	v_mfma_f32_16x16x32_bf16 v[58:61], v[218:221], v[166:169], v[58:61]
	v_mfma_f32_16x16x32_bf16 v[54:57], v[210:213], v[174:177], v[54:57]
	v_mfma_f32_16x16x32_bf16 v[46:49], v[218:221], v[174:177], v[46:49]
	v_mfma_f32_16x16x32_bf16 v[50:53], v[210:213], v[182:185], v[50:53]
	v_mfma_f32_16x16x32_bf16 v[42:45], v[218:221], v[182:185], v[42:45]
	v_mfma_f32_16x16x32_bf16 v[38:41], v[210:213], v[190:193], v[38:41]
	v_mfma_f32_16x16x32_bf16 v[34:37], v[218:221], v[190:193], v[34:37]
	s_setprio 0
	s_mov_b32 m0, s78
	v_lshl_add_u64 v[222:223], v[226:227], 0, s[76:77]
	s_barrier
	ds_read_b128 v[158:161], v162 offset:49152
	ds_read_b128 v[166:169], v162 offset:50176
	ds_read_b128 v[170:173], v162 offset:51200
	ds_read_b128 v[174:177], v162 offset:52224
	ds_read_b128 v[178:181], v162 offset:53248
	ds_read_b128 v[182:185], v162 offset:54272
	ds_read_b128 v[186:189], v162 offset:55296
	ds_read_b128 v[190:193], v162 offset:56320
	global_load_lds_dwordx4 v[222:223], off
	v_lshl_add_u64 v[222:223], v[228:229], 0, s[76:77]
	s_mov_b32 m0, s79
	s_nop 0
	global_load_lds_dwordx4 v[222:223], off
	s_barrier
	s_waitcnt lgkmcnt(0)
	s_setprio 1
	v_mfma_f32_16x16x32_bf16 v[94:97], v[130:133], v[158:161], v[94:97]
	v_mfma_f32_16x16x32_bf16 v[90:93], v[150:153], v[158:161], v[90:93]
	v_mfma_f32_16x16x32_bf16 v[86:89], v[130:133], v[170:173], v[86:89]
	v_mfma_f32_16x16x32_bf16 v[82:85], v[150:153], v[170:173], v[82:85]
	v_mfma_f32_16x16x32_bf16 v[78:81], v[130:133], v[178:181], v[78:81]
	v_mfma_f32_16x16x32_bf16 v[74:77], v[150:153], v[178:181], v[74:77]
	v_mfma_f32_16x16x32_bf16 v[70:73], v[130:133], v[186:189], v[70:73]
	v_mfma_f32_16x16x32_bf16 v[66:69], v[150:153], v[186:189], v[66:69]
	v_mfma_f32_16x16x32_bf16 v[94:97], v[134:137], v[166:169], v[94:97]
	v_mfma_f32_16x16x32_bf16 v[90:93], v[154:157], v[166:169], v[90:93]
	v_mfma_f32_16x16x32_bf16 v[86:89], v[134:137], v[174:177], v[86:89]
	v_mfma_f32_16x16x32_bf16 v[82:85], v[154:157], v[174:177], v[82:85]
	v_mfma_f32_16x16x32_bf16 v[78:81], v[134:137], v[182:185], v[78:81]
	v_mfma_f32_16x16x32_bf16 v[74:77], v[154:157], v[182:185], v[74:77]
	v_mfma_f32_16x16x32_bf16 v[70:73], v[134:137], v[190:193], v[70:73]
	v_mfma_f32_16x16x32_bf16 v[66:69], v[154:157], v[190:193], v[66:69]
	s_setprio 0
	s_barrier
	s_add_u32 s10, s54, 0x80080
	s_addc_u32 s11, s55, 0
	s_mov_b32 m0, s80
	v_lshl_add_u64 v[130:131], s[10:11], 0, v[194:195]
	global_load_lds_dwordx4 v[130:131], off
	v_lshl_add_u64 v[130:131], s[10:11], 0, v[138:139]
	s_mov_b32 m0, s81
	s_nop 0
	global_load_lds_dwordx4 v[130:131], off
	s_waitcnt vmcnt(6)
	s_barrier
	s_setprio 1
	v_mfma_f32_16x16x32_bf16 v[30:33], v[206:209], v[158:161], v[30:33]
	v_mfma_f32_16x16x32_bf16 v[18:21], v[214:217], v[158:161], v[18:21]
	v_mfma_f32_16x16x32_bf16 v[26:29], v[206:209], v[170:173], v[26:29]
	v_mfma_f32_16x16x32_bf16 v[14:17], v[214:217], v[170:173], v[14:17]
	v_mfma_f32_16x16x32_bf16 v[22:25], v[206:209], v[178:181], v[22:25]
	v_mfma_f32_16x16x32_bf16 v[6:9], v[214:217], v[178:181], v[6:9]
	v_mfma_f32_16x16x32_bf16 v[10:13], v[206:209], v[186:189], v[10:13]
	v_mfma_f32_16x16x32_bf16 v[2:5], v[214:217], v[186:189], v[2:5]
	v_mfma_f32_16x16x32_bf16 v[30:33], v[210:213], v[166:169], v[30:33]
	v_mfma_f32_16x16x32_bf16 v[18:21], v[218:221], v[166:169], v[18:21]
	v_mfma_f32_16x16x32_bf16 v[26:29], v[210:213], v[174:177], v[26:29]
	v_mfma_f32_16x16x32_bf16 v[14:17], v[218:221], v[174:177], v[14:17]
	v_mfma_f32_16x16x32_bf16 v[22:25], v[210:213], v[182:185], v[22:25]
	v_mfma_f32_16x16x32_bf16 v[6:9], v[218:221], v[182:185], v[6:9]
	v_mfma_f32_16x16x32_bf16 v[10:13], v[210:213], v[190:193], v[10:13]
	v_mfma_f32_16x16x32_bf16 v[2:5], v[218:221], v[190:193], v[2:5]
	s_setprio 0
	s_add_i32 s29, s29, 2
	s_add_u32 s52, s52, 0x100
	s_addc_u32 s53, s53, 0
	s_add_u32 s5, s5, 0x100
	s_addc_u32 s7, s7, 0
	s_cmp_gt_u32 s29, 29
	s_barrier
	s_cbranch_scc0 .LBB0_504
	v_readlane_b32 s10, v250, 21
	s_cmp_gt_i32 s40, 63
	v_readlane_b32 s11, v250, 22
	s_mov_b64 s[20:21], s[48:49]
	s_cselect_b32 s11, s21, s11
	s_cselect_b32 s10, s20, s10
	v_readlane_b32 s20, v252, 0
	v_readlane_b32 s26, v252, 6
	v_readlane_b32 s27, v252, 7
	s_cselect_b32 s53, s3, s27
	s_cselect_b32 s52, s2, s26
	s_sub_i32 s5, s40, 64
	s_cmp_gt_i32 s40, 63
	s_cselect_b32 s54, s5, s40
	s_lshr_b32 s5, s40, 3
	s_cmp_gt_i32 s40, 63
	s_mulk_i32 s5, 0x1800
	v_lshl_or_b32 v130, s28, 8, v164
	s_cselect_b32 s28, 0xc000, s5
	s_ashr_i32 s29, s28, 31
	s_lshl_b64 s[28:29], s[28:29], 2
	s_add_u32 s28, s63, s28
	v_ashrrev_i32_e32 v131, 31, v130
	s_addc_u32 s29, s67, s29
	v_lshlrev_b64 v[130:131], 2, v[130:131]
	v_lshl_add_u64 v[132:133], s[28:29], 0, v[130:131]
	s_mov_b64 s[28:29], 0x6484000
	s_ashr_i32 s55, s54, 31
	v_lshl_add_u64 v[154:155], v[132:133], 0, s[28:29]
	s_lshl_b64 s[28:29], s[54:55], 19
	v_lshl_add_u64 v[134:135], s[28:29], 0, v[144:145]
	v_lshlrev_b64 v[134:135], 2, v[134:135]
	v_lshl_add_u64 v[136:137], s[10:11], 0, v[134:135]
	v_lshl_add_u64 v[134:135], s[52:53], 0, v[134:135]
	s_mov_b32 s5, 0x6484000
	v_lshl_add_u64 v[150:151], v[136:137], 0, v[130:131]
	v_lshl_add_u64 v[152:153], v[134:135], 0, v[130:131]
	v_add_co_u32_e32 v130, vcc, s5, v132
	s_mov_b64 s[10:11], 0x20000
	s_nop 0
	v_addc_co_u32_e32 v131, vcc, 0, v133, vcc
	v_add_co_u32_e32 v156, vcc, s13, v150
	global_load_dwordx4 v[134:137], v[130:131], off
	s_nop 0
	global_load_dwordx4 v[130:133], v[154:155], off offset:16
	global_load_dwordx4 v[166:169], v[150:151], off offset:16
	global_load_dwordx4 v[170:173], v[150:151], off
	v_lshl_add_u64 v[158:159], v[150:151], 0, s[10:11]
	v_addc_co_u32_e32 v157, vcc, 0, v151, vcc
	s_mov_b32 s5, 0x40000
	global_load_dwordx4 v[174:177], v[156:157], off
	global_load_dwordx4 v[178:181], v[158:159], off offset:16
	s_mov_b64 s[10:11], 0x40000
	v_add_co_u32_e32 v158, vcc, s5, v150
	v_lshl_add_u64 v[160:161], v[150:151], 0, s[10:11]
	s_nop 0
	v_addc_co_u32_e32 v159, vcc, 0, v151, vcc
	s_mov_b32 s7, 0x60000
	global_load_dwordx4 v[182:185], v[158:159], off
	global_load_dwordx4 v[186:189], v[160:161], off offset:16
	s_mov_b64 s[10:11], 0x60000
	v_add_co_u32_e32 v160, vcc, s7, v150
	v_lshl_add_u64 v[206:207], v[150:151], 0, s[10:11]
	s_nop 0
	v_addc_co_u32_e32 v161, vcc, 0, v151, vcc
	global_load_dwordx4 v[190:193], v[160:161], off
	s_nop 0
	global_load_dwordx4 v[206:209], v[206:207], off offset:16
	v_readlane_b32 s21, v252, 1
	v_readlane_b32 s22, v252, 2
	v_readlane_b32 s23, v252, 3
	v_readlane_b32 s24, v252, 4
	v_readlane_b32 s25, v252, 5
	s_waitcnt vmcnt(0)
	v_pk_fma_f32 v[124:125], v[124:125], v[132:133], v[168:169]
	v_pk_fma_f32 v[122:123], v[122:123], v[130:131], v[166:167]
	global_store_dwordx4 v[152:153], v[122:125], off offset:16
	v_pk_fma_f32 v[128:129], v[128:129], v[136:137], v[172:173]
	v_pk_fma_f32 v[126:127], v[126:127], v[134:135], v[170:171]
	v_pk_fma_f32 v[122:123], v[120:121], v[136:137], v[176:177]
	v_pk_fma_f32 v[120:121], v[118:119], v[134:135], v[174:175]
	v_add_co_u32_e32 v118, vcc, s13, v152
	v_pk_fma_f32 v[116:117], v[116:117], v[132:133], v[180:181]
	s_nop 0
	v_addc_co_u32_e32 v119, vcc, 0, v153, vcc
	v_pk_fma_f32 v[114:115], v[114:115], v[130:131], v[178:179]
	global_store_dwordx4 v[118:119], v[114:117], off offset:16
	v_pk_fma_f32 v[108:109], v[108:109], v[132:133], v[188:189]
	v_pk_fma_f32 v[106:107], v[106:107], v[130:131], v[186:187]
	v_pk_fma_f32 v[114:115], v[112:113], v[136:137], v[184:185]
	v_pk_fma_f32 v[112:113], v[110:111], v[134:135], v[182:183]
	v_add_co_u32_e32 v110, vcc, s5, v152
	global_store_dwordx4 v[152:153], v[126:129], off
	s_nop 0
	v_addc_co_u32_e32 v111, vcc, 0, v153, vcc
	global_store_dwordx4 v[110:111], v[106:109], off offset:16
	v_pk_fma_f32 v[100:101], v[100:101], v[132:133], v[208:209]
	v_pk_fma_f32 v[98:99], v[98:99], v[130:131], v[206:207]
	v_pk_fma_f32 v[106:107], v[104:105], v[136:137], v[192:193]
	v_pk_fma_f32 v[104:105], v[102:103], v[134:135], v[190:191]
	v_add_co_u32_e32 v102, vcc, s7, v152
	global_store_dwordx4 v[118:119], v[120:123], off
	s_nop 0
	v_addc_co_u32_e32 v103, vcc, 0, v153, vcc
	global_store_dwordx4 v[110:111], v[112:115], off
	global_store_dwordx4 v[102:103], v[104:107], off
	global_store_dwordx4 v[102:103], v[98:101], off offset:16
	s_mov_b32 s5, 0x100000
	s_mov_b64 s[10:11], 0x100000
	v_add_co_u32_e32 v98, vcc, s5, v150
	v_lshl_add_u64 v[100:101], v[150:151], 0, s[10:11]
	s_nop 0
	v_addc_co_u32_e32 v99, vcc, 0, v151, vcc
	global_load_dwordx4 v[112:115], v[98:99], off
	global_load_dwordx4 v[120:123], v[100:101], off offset:16
	s_mov_b64 s[10:11], 0x120000
	v_add_co_u32_e32 v100, vcc, s45, v150
	v_lshl_add_u64 v[104:105], v[150:151], 0, s[10:11]
	s_nop 0
	v_addc_co_u32_e32 v101, vcc, 0, v151, vcc
	s_mov_b64 s[10:11], 0x140000
	s_mov_b32 s7, 0x140000
	global_load_dwordx4 v[124:127], v[100:101], off
	global_load_dwordx4 v[166:169], v[104:105], off offset:16
	v_lshl_add_u64 v[106:107], v[150:151], 0, s[10:11]
	v_add_co_u32_e32 v104, vcc, s7, v150
	s_mov_b64 s[10:11], 0x160000
	s_nop 0
	v_addc_co_u32_e32 v105, vcc, 0, v151, vcc
	v_lshl_add_u64 v[108:109], v[150:151], 0, s[10:11]
	s_mov_b32 s10, 0x160000
	global_load_dwordx4 v[170:173], v[104:105], off
	global_load_dwordx4 v[174:177], v[106:107], off offset:16
	v_add_co_u32_e32 v106, vcc, s10, v150
	s_waitcnt vmcnt(0)
	v_pk_fma_f32 v[112:113], v[94:95], v[134:135], v[112:113]
	v_addc_co_u32_e32 v107, vcc, 0, v151, vcc
	global_load_dwordx4 v[178:181], v[106:107], off
	global_load_dwordx4 v[182:185], v[108:109], off offset:16
	v_add_co_u32_e32 v94, vcc, s5, v152
	v_pk_fma_f32 v[92:93], v[92:93], v[132:133], v[122:123]
	s_nop 0
	v_addc_co_u32_e32 v95, vcc, 0, v153, vcc
	v_pk_fma_f32 v[90:91], v[90:91], v[130:131], v[120:121]
	global_store_dwordx4 v[94:95], v[90:93], off offset:16
	v_pk_fma_f32 v[84:85], v[84:85], v[132:133], v[168:169]
	v_pk_fma_f32 v[82:83], v[82:83], v[130:131], v[166:167]
	v_pk_fma_f32 v[90:91], v[88:89], v[136:137], v[126:127]
	v_pk_fma_f32 v[88:89], v[86:87], v[134:135], v[124:125]
	v_add_co_u32_e32 v86, vcc, s45, v152
	v_pk_fma_f32 v[114:115], v[96:97], v[136:137], v[114:115]
	s_nop 0
	v_addc_co_u32_e32 v87, vcc, 0, v153, vcc
	global_store_dwordx4 v[86:87], v[82:85], off offset:16
	v_pk_fma_f32 v[76:77], v[76:77], v[132:133], v[176:177]
	v_pk_fma_f32 v[74:75], v[74:75], v[130:131], v[174:175]
	v_pk_fma_f32 v[82:83], v[80:81], v[136:137], v[172:173]
	v_pk_fma_f32 v[80:81], v[78:79], v[134:135], v[170:171]
	v_add_co_u32_e32 v78, vcc, s7, v152
	global_store_dwordx4 v[94:95], v[112:115], off
	s_nop 0
	v_addc_co_u32_e32 v79, vcc, 0, v153, vcc
	global_store_dwordx4 v[78:79], v[74:77], off offset:16
	global_store_dwordx4 v[86:87], v[88:91], off
	global_store_dwordx4 v[78:79], v[80:83], off
	v_add_co_u32_e32 v74, vcc, s10, v152
	s_waitcnt vmcnt(0)
	v_pk_fma_f32 v[72:73], v[72:73], v[136:137], v[180:181]
	v_pk_fma_f32 v[70:71], v[70:71], v[134:135], v[178:179]
	v_addc_co_u32_e32 v75, vcc, 0, v153, vcc
	v_pk_fma_f32 v[68:69], v[68:69], v[132:133], v[184:185]
	v_pk_fma_f32 v[66:67], v[66:67], v[130:131], v[182:183]
	global_store_dwordx4 v[74:75], v[70:73], off
	global_store_dwordx4 v[74:75], v[66:69], off offset:16
	s_mov_b64 s[10:11], 0x20200
	v_lshl_add_u64 v[76:77], v[150:151], 0, s[10:11]
	s_mov_b64 s[10:11], 0x40200
	global_load_dwordx4 v[80:83], v[150:151], off offset:512
	global_load_dwordx4 v[70:73], v[154:155], off offset:512
	global_load_dwordx4 v[66:69], v[154:155], off offset:528
	global_load_dwordx4 v[88:91], v[150:151], off offset:528
	global_load_dwordx4 v[112:115], v[156:157], off offset:512
	global_load_dwordx4 v[120:123], v[158:159], off offset:512
	global_load_dwordx4 v[124:127], v[76:77], off offset:16
	v_lshl_add_u64 v[76:77], v[150:151], 0, s[10:11]
	s_mov_b64 s[10:11], 0x60200
	global_load_dwordx4 v[128:131], v[76:77], off offset:16
	global_load_dwordx4 v[132:135], v[160:161], off offset:512
	v_lshl_add_u64 v[76:77], v[150:151], 0, s[10:11]
	global_load_dwordx4 v[154:157], v[76:77], off offset:16
	s_waitcnt vmcnt(0)
	v_pk_fma_f32 v[64:65], v[64:65], v[72:73], v[82:83]
	v_pk_fma_f32 v[62:63], v[62:63], v[70:71], v[80:81]
	v_pk_fma_f32 v[60:61], v[60:61], v[68:69], v[90:91]
	v_pk_fma_f32 v[58:59], v[58:59], v[66:67], v[88:89]
	v_pk_fma_f32 v[52:53], v[52:53], v[72:73], v[122:123]
	v_pk_fma_f32 v[50:51], v[50:51], v[70:71], v[120:121]
	v_pk_fma_f32 v[48:49], v[48:49], v[68:69], v[126:127]
	v_pk_fma_f32 v[46:47], v[46:47], v[66:67], v[124:125]
	v_pk_fma_f32 v[56:57], v[56:57], v[72:73], v[114:115]
	v_pk_fma_f32 v[54:55], v[54:55], v[70:71], v[112:113]
	global_store_dwordx4 v[152:153], v[62:65], off offset:512
	global_store_dwordx4 v[152:153], v[58:61], off offset:528
	global_store_dwordx4 v[118:119], v[54:57], off offset:512
	global_store_dwordx4 v[110:111], v[50:53], off offset:512
	v_pk_fma_f32 v[44:45], v[44:45], v[68:69], v[130:131]
	v_pk_fma_f32 v[42:43], v[42:43], v[66:67], v[128:129]
	v_pk_fma_f32 v[40:41], v[40:41], v[72:73], v[134:135]
	v_pk_fma_f32 v[38:39], v[38:39], v[70:71], v[132:133]
	v_pk_fma_f32 v[36:37], v[36:37], v[68:69], v[156:157]
	v_pk_fma_f32 v[34:35], v[34:35], v[66:67], v[154:155]
	global_store_dwordx4 v[118:119], v[46:49], off offset:528
	global_store_dwordx4 v[110:111], v[42:45], off offset:528
	global_store_dwordx4 v[102:103], v[38:41], off offset:512
	global_store_dwordx4 v[102:103], v[34:37], off offset:528
	s_mov_b64 s[10:11], 0x100200
	v_lshl_add_u64 v[50:51], v[150:151], 0, s[10:11]
	s_mov_b64 s[10:11], 0x120200
	v_lshl_add_u64 v[54:55], v[150:151], 0, s[10:11]
	s_mov_b64 s[10:11], 0x140200
	v_lshl_add_u64 v[58:59], v[150:151], 0, s[10:11]
	s_mov_b64 s[10:11], 0x160200
	global_load_dwordx4 v[34:37], v[98:99], off offset:512
	global_load_dwordx4 v[38:41], v[100:101], off offset:512
	global_load_dwordx4 v[42:45], v[104:105], off offset:512
	global_load_dwordx4 v[46:49], v[106:107], off offset:512
	v_lshl_add_u64 v[62:63], v[150:151], 0, s[10:11]
	global_load_dwordx4 v[50:53], v[50:51], off offset:16
	s_waitcnt vmcnt(0)
	v_pk_fma_f32 v[32:33], v[32:33], v[72:73], v[36:37]
	global_load_dwordx4 v[54:57], v[54:55], off offset:16
	v_pk_fma_f32 v[30:31], v[30:31], v[70:71], v[34:35]
	global_load_dwordx4 v[58:61], v[58:59], off offset:16
	v_pk_fma_f32 v[28:29], v[28:29], v[72:73], v[40:41]
	global_load_dwordx4 v[62:65], v[62:63], off offset:16
	v_pk_fma_f32 v[26:27], v[26:27], v[70:71], v[38:39]
	v_pk_fma_f32 v[24:25], v[24:25], v[72:73], v[44:45]
	v_pk_fma_f32 v[22:23], v[22:23], v[70:71], v[42:43]
	v_pk_fma_f32 v[12:13], v[12:13], v[72:73], v[48:49]
	v_pk_fma_f32 v[10:11], v[10:11], v[70:71], v[46:47]
	v_pk_fma_f32 v[20:21], v[20:21], v[68:69], v[52:53]
	v_pk_fma_f32 v[18:19], v[18:19], v[66:67], v[50:51]
	global_store_dwordx4 v[94:95], v[30:33], off offset:512
	global_store_dwordx4 v[86:87], v[26:29], off offset:512
	global_store_dwordx4 v[78:79], v[22:25], off offset:512
	global_store_dwordx4 v[74:75], v[10:13], off offset:512
	s_waitcnt vmcnt(0)
	v_pk_fma_f32 v[16:17], v[16:17], v[68:69], v[56:57]
	v_pk_fma_f32 v[14:15], v[14:15], v[66:67], v[54:55]
	v_pk_fma_f32 v[8:9], v[8:9], v[68:69], v[60:61]
	v_pk_fma_f32 v[6:7], v[6:7], v[66:67], v[58:59]
	v_pk_fma_f32 v[4:5], v[4:5], v[68:69], v[64:65]
	v_pk_fma_f32 v[2:3], v[2:3], v[66:67], v[62:63]
	global_store_dwordx4 v[94:95], v[18:21], off offset:528
	global_store_dwordx4 v[86:87], v[14:17], off offset:528
	global_store_dwordx4 v[78:79], v[6:9], off offset:528
	global_store_dwordx4 v[74:75], v[2:5], off offset:528
	s_and_b64 vcc, exec, s[0:1]
	s_mov_b32 s40, s6
	s_mov_b32 s28, s4
	s_mov_b64 s[54:55], s[34:35]
	s_mov_b64 s[52:53], s[8:9]
	s_cbranch_vccz .LBB0_501
	s_waitcnt vmcnt(0)
	v_readlane_b32 s28, v250, 12
	v_readlane_b32 s26, v250, 15
	s_cmpk_gt_u32 s12, 0xff
	v_readlane_b32 s29, v250, 13
	v_readlane_b32 s27, v250, 16
	s_mov_b32 s70, 0x800000
	v_readlane_b32 s79, v250, 18
	s_cbranch_scc1 .LBB0_508
	s_barrier
